# GEMM K-loops: per-phase s_setprio flips deleted, one static s_setprio 1 for waves 4-7 during each K loop (asm guide 7.4)
# speedup vs baseline: 1.0986x; 1.0059x over previous
; #define G8_STAGE(bufoff, gbase, voff) do { _Pragma("unroll") for (int _i = 0; _i < 2; ++_i) \
;     __builtin_amdgcn_global_load_lds((const unsigned*)((const char*)(gbase) + (voff)[_i]), (LAS unsigned*)(lds + (bufoff) + ldsw + _i * 8192), 16, 0, 0); } while (0)
; #define G8_LDA(dst, b, h) do { _Pragma("unroll") for (int m = 0; m < 4; ++m) _Pragma("unroll") for (int k = 0; k < 2; ++k) dst[m][k] = *(const LAS bf16x8*)(lds + G8_SA(b, h) + aoff + m * 2048 + k * 1024); } while (0)
; #define G8_LDB(dst, b, h) do { _Pragma("unroll") for (int n = 0; n < 2; ++n) _Pragma("unroll") for (int k = 0; k < 2; ++k) dst[n][k] = *(const LAS bf16x8*)(lds + G8_SB(b, h) + boff + n * 2048 + k * 1024); } while (0)
; #define G8_MMA(ai, bj, At, Bt) do { __builtin_amdgcn_s_setprio(1); _Pragma("unroll") for (int m = 0; m < 4; ++m) _Pragma("unroll") for (int n = 0; n < 2; ++n) _Pragma("unroll") for (int k = 0; k < 2; ++k) \
;     acc[ai][bj][m][n] = __builtin_amdgcn_mfma_f32_16x16x32_bf16(Bt[n][k], At[m][k], acc[ai][bj][m][n], 0, 0, 0); __builtin_amdgcn_s_setprio(0); } while (0)
; #define G8_WAIT_L(n) asm volatile("s_waitcnt lgkmcnt(" #n ")" ::: "memory")
; #define G8_BAR __builtin_amdgcn_s_barrier()
; #define G8_SCHED __builtin_amdgcn_sched_barrier(0)
; template <class Epi, class Sched>
; __device__ __forceinline__ void gemm_phase(const int wv_, LAS unsigned char* lds, const int lda, const int ldb, const int K, const Sched& S, const Epi& E) {
;     ...
;     for (int t = 0; t < nt; t += 2) {
;       const bool last = (t == nt - 2);
;       const char* a1 = cA + (size_t)(t + 1) * kstep;
;       const char* a2 = last ? nA : cA + (size_t)(t + 2) * kstep; const char* b2 = last ? nB : cB + (size_t)(t + 2) * kstep;
;       const char* a3 = a2 + kstep; const char* b3 = b2 + kstep;
;       G8_LDB(B0, 0, 0); G8_SCHED; G8_LDA(At, 0, 0); G8_STAGE(G8_SA(1, 1), a1 + hstepA, voffA);
;       G8_WAIT_L(8); G8_BAR; G8_WAIT_L(0); G8_MMA(0, 0, At, B0); G8_BAR; G8_SCHED;
;     ...
; #pragma unroll
;       for (int a = 0; a < 2; ++a)
; #pragma unroll
;         for (int b = 0; b < 2; ++b)
; #pragma unroll
;           for (int m = 0; m < 4; ++m)
; #pragma unroll
;             for (int n = 0; n < 2; ++n) acc[a][b][m][n] = (f32x4){0.f, 0.f, 0.f, 0.f};
.LBB0_206:
	s_add_i32 s13, s47, -2
	s_add_u32 s4, s4, 0x80080
	s_addc_u32 s5, s5, 0
	s_add_u32 s50, s18, 0x100
	v_mov_b32_e32 v4, 0
	s_addc_u32 s51, s19, 0
	s_mov_b32 s18, 0
	v_mov_b32_e32 v5, v4
	v_mov_b32_e32 v6, v4
	v_mov_b32_e32 v7, v4
	v_mov_b32_e32 v8, v4
	v_mov_b32_e32 v9, v4
	v_mov_b32_e32 v10, v4
	v_mov_b32_e32 v11, v4
	v_mov_b32_e32 v20, v4
	v_mov_b32_e32 v21, v4
	v_mov_b32_e32 v22, v4
	v_mov_b32_e32 v23, v4
	v_mov_b32_e32 v24, v4
	v_mov_b32_e32 v25, v4
	v_mov_b32_e32 v26, v4
	v_mov_b32_e32 v27, v4
	v_mov_b32_e32 v36, v4
	v_mov_b32_e32 v37, v4
	v_mov_b32_e32 v38, v4
	v_mov_b32_e32 v39, v4
	v_mov_b32_e32 v40, v4
	v_mov_b32_e32 v41, v4
	v_mov_b32_e32 v42, v4
	v_mov_b32_e32 v43, v4
	v_mov_b32_e32 v52, v4
	v_mov_b32_e32 v53, v4
	v_mov_b32_e32 v54, v4
	v_mov_b32_e32 v55, v4
	v_mov_b32_e32 v56, v4
	v_mov_b32_e32 v57, v4
	v_mov_b32_e32 v58, v4
	v_mov_b32_e32 v59, v4
	v_mov_b32_e32 v12, v4
	v_mov_b32_e32 v13, v4
	v_mov_b32_e32 v14, v4
	v_mov_b32_e32 v15, v4
	v_mov_b32_e32 v16, v4
	v_mov_b32_e32 v17, v4
	v_mov_b32_e32 v18, v4
	v_mov_b32_e32 v19, v4
	v_mov_b32_e32 v28, v4
	v_mov_b32_e32 v29, v4
	v_mov_b32_e32 v30, v4
	v_mov_b32_e32 v31, v4
	v_mov_b32_e32 v32, v4
	v_mov_b32_e32 v33, v4
	v_mov_b32_e32 v34, v4
	v_mov_b32_e32 v35, v4
	v_mov_b32_e32 v44, v4
	v_mov_b32_e32 v45, v4
	v_mov_b32_e32 v46, v4
	v_mov_b32_e32 v47, v4
	v_mov_b32_e32 v48, v4
	v_mov_b32_e32 v49, v4
	v_mov_b32_e32 v50, v4
	v_mov_b32_e32 v51, v4
	v_mov_b32_e32 v60, v4
	v_mov_b32_e32 v61, v4
	v_mov_b32_e32 v62, v4
	v_mov_b32_e32 v63, v4
	v_mov_b32_e32 v64, v4
	v_mov_b32_e32 v65, v4
	v_mov_b32_e32 v66, v4
	v_mov_b32_e32 v67, v4
	v_mov_b32_e32 v68, v4
	v_mov_b32_e32 v69, v4
	v_mov_b32_e32 v70, v4
	v_mov_b32_e32 v71, v4
	v_mov_b32_e32 v72, v4
	v_mov_b32_e32 v73, v4
	v_mov_b32_e32 v74, v4
	v_mov_b32_e32 v75, v4
	v_mov_b32_e32 v84, v4
	v_mov_b32_e32 v85, v4
	v_mov_b32_e32 v86, v4
	v_mov_b32_e32 v87, v4
	v_mov_b32_e32 v88, v4
	v_mov_b32_e32 v89, v4
	v_mov_b32_e32 v90, v4
	v_mov_b32_e32 v91, v4
	v_mov_b32_e32 v100, v4
	v_mov_b32_e32 v101, v4
	v_mov_b32_e32 v102, v4
	v_mov_b32_e32 v103, v4
	v_mov_b32_e32 v104, v4
	v_mov_b32_e32 v105, v4
	v_mov_b32_e32 v106, v4
	v_mov_b32_e32 v107, v4
	v_mov_b32_e32 v116, v4
	v_mov_b32_e32 v117, v4
	v_mov_b32_e32 v118, v4
	v_mov_b32_e32 v119, v4
	v_mov_b32_e32 v120, v4
	v_mov_b32_e32 v121, v4
	v_mov_b32_e32 v122, v4
	v_mov_b32_e32 v123, v4
	v_mov_b32_e32 v76, v4
	v_mov_b32_e32 v77, v4
	v_mov_b32_e32 v78, v4
	v_mov_b32_e32 v79, v4
	v_mov_b32_e32 v80, v4
	v_mov_b32_e32 v81, v4
	v_mov_b32_e32 v82, v4
	v_mov_b32_e32 v83, v4
	v_mov_b32_e32 v92, v4
	v_mov_b32_e32 v93, v4
	v_mov_b32_e32 v94, v4
	v_mov_b32_e32 v95, v4
	v_mov_b32_e32 v96, v4
	v_mov_b32_e32 v97, v4
	v_mov_b32_e32 v98, v4
	v_mov_b32_e32 v99, v4
	v_mov_b32_e32 v108, v4
	v_mov_b32_e32 v109, v4
	v_mov_b32_e32 v110, v4
	v_mov_b32_e32 v111, v4
	v_mov_b32_e32 v112, v4
	v_mov_b32_e32 v113, v4
	v_mov_b32_e32 v114, v4
	v_mov_b32_e32 v115, v4
	v_mov_b32_e32 v124, v4
	v_mov_b32_e32 v125, v4
	v_mov_b32_e32 v126, v4
	v_mov_b32_e32 v127, v4
	v_mov_b32_e32 v128, v4
	v_mov_b32_e32 v129, v4
	v_mov_b32_e32 v130, v4
	v_mov_b32_e32 v131, v4
	s_cmp_ge_u32 s72, 0x100
	s_cbranch_scc0 .Lg1_noprio
	s_setprio 1
.Lg1_noprio:
.LBB0_207:
	s_add_i32 s53, s18, 2
	s_add_u32 s19, s4, 0xfff80080
	s_addc_u32 s20, s5, -1
	s_add_i32 s56, 0, 0x10000
	v_add_u32_e32 v147, s56, v148
	ds_read_b128 v[132:135], v147
	ds_read_b128 v[156:159], v147 offset:1024
	ds_read_b128 v[160:163], v147 offset:2048
	ds_read_b128 v[164:167], v147 offset:3072
	s_cmp_eq_u32 s13, s18
	s_cselect_b32 s18, s16, s50
	s_cselect_b32 s21, s15, s20
	s_cselect_b32 s20, s14, s19
	s_cselect_b32 s19, s17, s51
	v_lshl_add_u64 v[150:151], s[4:5], 0, v[142:143]
	s_add_i32 m0, s29, 0xc000
	ds_read_b128 v[190:193], v149
	ds_read_b128 v[194:197], v149 offset:1024
	ds_read_b128 v[198:201], v149 offset:2048
	ds_read_b128 v[202:205], v149 offset:3072
	ds_read_b128 v[206:209], v149 offset:4096
	ds_read_b128 v[210:213], v149 offset:5120
	ds_read_b128 v[214:217], v149 offset:6144
	ds_read_b128 v[218:221], v149 offset:7168
	global_load_lds_dwordx4 v[150:151], off
	v_lshl_add_u64 v[150:151], s[4:5], 0, v[144:145]
	s_add_i32 m0, s29, 0xe000
	s_nop 0
	global_load_lds_dwordx4 v[150:151], off
	s_waitcnt lgkmcnt(8)
	s_barrier
	s_waitcnt lgkmcnt(0)
	s_waitcnt lgkmcnt(0)
	v_mfma_f32_16x16x32_bf16 v[128:131], v[132:135], v[190:193], v[128:131]
	v_mfma_f32_16x16x32_bf16 v[124:127], v[160:163], v[190:193], v[124:127]
	v_mfma_f32_16x16x32_bf16 v[112:115], v[132:135], v[198:201], v[112:115]
	v_mfma_f32_16x16x32_bf16 v[108:111], v[160:163], v[198:201], v[108:111]
	v_mfma_f32_16x16x32_bf16 v[96:99], v[132:135], v[206:209], v[96:99]
	v_mfma_f32_16x16x32_bf16 v[92:95], v[160:163], v[206:209], v[92:95]
	v_mfma_f32_16x16x32_bf16 v[80:83], v[132:135], v[214:217], v[80:83]
	v_mfma_f32_16x16x32_bf16 v[76:79], v[160:163], v[214:217], v[76:79]
	v_mfma_f32_16x16x32_bf16 v[128:131], v[156:159], v[194:197], v[128:131]
	v_mfma_f32_16x16x32_bf16 v[124:127], v[164:167], v[194:197], v[124:127]
	v_mfma_f32_16x16x32_bf16 v[112:115], v[156:159], v[202:205], v[112:115]
	v_mfma_f32_16x16x32_bf16 v[108:111], v[164:167], v[202:205], v[108:111]
	v_mfma_f32_16x16x32_bf16 v[96:99], v[156:159], v[210:213], v[96:99]
	v_mfma_f32_16x16x32_bf16 v[92:95], v[164:167], v[210:213], v[92:95]
	v_mfma_f32_16x16x32_bf16 v[80:83], v[156:159], v[218:221], v[80:83]
	v_mfma_f32_16x16x32_bf16 v[76:79], v[164:167], v[218:221], v[76:79]
	s_barrier
; #define G8_STAGE(bufoff, gbase, voff) do { _Pragma("unroll") for (int _i = 0; _i < 2; ++_i) \
;     __builtin_amdgcn_global_load_lds((const unsigned*)((const char*)(gbase) + (voff)[_i]), (LAS unsigned*)(lds + (bufoff) + ldsw + _i * 8192), 16, 0, 0); } while (0)
; #define G8_LDA(dst, b, h) do { _Pragma("unroll") for (int m = 0; m < 4; ++m) _Pragma("unroll") for (int k = 0; k < 2; ++k) dst[m][k] = *(const LAS bf16x8*)(lds + G8_SA(b, h) + aoff + m * 2048 + k * 1024); } while (0)
; #define G8_LDB(dst, b, h) do { _Pragma("unroll") for (int n = 0; n < 2; ++n) _Pragma("unroll") for (int k = 0; k < 2; ++k) dst[n][k] = *(const LAS bf16x8*)(lds + G8_SB(b, h) + boff + n * 2048 + k * 1024); } while (0)
; #define G8_MMA(ai, bj, At, Bt) do { __builtin_amdgcn_s_setprio(1); _Pragma("unroll") for (int m = 0; m < 4; ++m) _Pragma("unroll") for (int n = 0; n < 2; ++n) _Pragma("unroll") for (int k = 0; k < 2; ++k) \
;     acc[ai][bj][m][n] = __builtin_amdgcn_mfma_f32_16x16x32_bf16(Bt[n][k], At[m][k], acc[ai][bj][m][n], 0, 0, 0); __builtin_amdgcn_s_setprio(0); } while (0)
; #define G8_WAIT_V(n) asm volatile("s_waitcnt vmcnt(" #n ")" ::: "memory")
; #define G8_WAIT_L(n) asm volatile("s_waitcnt lgkmcnt(" #n ")" ::: "memory")
; #define G8_BAR __builtin_amdgcn_s_barrier()
; #define G8_SCHED __builtin_amdgcn_sched_barrier(0)
; template <class Epi, class Sched>
; __device__ __forceinline__ void gemm_phase(const int wv_, LAS unsigned char* lds, const int lda, const int ldb, const int K, const Sched& S, const Epi& E) {
;     ...
;       G8_LDB(B1, 0, 1); G8_STAGE(G8_SB(0, 0), b2, voffB);
;       G8_BAR; G8_WAIT_L(0); G8_MMA(0, 1, At, B1); G8_BAR;
;       G8_LDA(At, 0, 1); G8_STAGE(G8_SA(0, 0), a2, voffA);
;       G8_BAR; G8_WAIT_L(0); G8_MMA(1, 0, At, B0); G8_BAR; G8_SCHED;
;       G8_STAGE(G8_SB(0, 1), b2 + hstepB, voffB);
;       G8_WAIT_V(6); G8_BAR; G8_MMA(1, 1, At, B1); G8_BAR;
;       G8_LDB(B0, 1, 0); G8_SCHED; G8_LDA(At, 1, 0); G8_STAGE(G8_SA(0, 1), a2 + hstepA, voffA);
;       G8_WAIT_L(8); G8_BAR; G8_WAIT_L(0); G8_MMA(0, 0, At, B0); G8_BAR; G8_SCHED;
;       G8_LDB(B1, 1, 1); G8_STAGE(G8_SB(1, 0), b3, voffB);
	s_add_i32 s58, 0, 0x14000
	s_add_i32 s56, s56, s28
	v_add_u32_e32 v147, s58, v148
	v_lshl_add_u64 v[150:151], s[18:19], 0, v[136:137]
	s_mov_b32 m0, s56
	ds_read_b128 v[222:225], v147
	ds_read_b128 v[226:229], v147 offset:1024
	ds_read_b128 v[230:233], v147 offset:2048
	ds_read_b128 v[234:237], v147 offset:3072
	global_load_lds_dwordx4 v[150:151], off
	v_lshl_add_u64 v[168:169], s[18:19], 0, v[140:141]
	s_add_i32 m0, s56, 0x2000
	s_nop 0
	global_load_lds_dwordx4 v[168:169], off
	s_barrier
	s_waitcnt lgkmcnt(0)
	s_waitcnt lgkmcnt(0)
	v_mfma_f32_16x16x32_bf16 v[120:123], v[222:225], v[190:193], v[120:123]
	v_mfma_f32_16x16x32_bf16 v[116:119], v[230:233], v[190:193], v[116:119]
	v_mfma_f32_16x16x32_bf16 v[104:107], v[222:225], v[198:201], v[104:107]
	v_mfma_f32_16x16x32_bf16 v[100:103], v[230:233], v[198:201], v[100:103]
	v_mfma_f32_16x16x32_bf16 v[88:91], v[222:225], v[206:209], v[88:91]
	v_mfma_f32_16x16x32_bf16 v[84:87], v[230:233], v[206:209], v[84:87]
	v_mfma_f32_16x16x32_bf16 v[72:75], v[222:225], v[214:217], v[72:75]
	v_mfma_f32_16x16x32_bf16 v[68:71], v[230:233], v[214:217], v[68:71]
	v_mfma_f32_16x16x32_bf16 v[120:123], v[226:229], v[194:197], v[120:123]
	v_mfma_f32_16x16x32_bf16 v[116:119], v[234:237], v[194:197], v[116:119]
	v_mfma_f32_16x16x32_bf16 v[104:107], v[226:229], v[202:205], v[104:107]
	v_mfma_f32_16x16x32_bf16 v[100:103], v[234:237], v[202:205], v[100:103]
	v_mfma_f32_16x16x32_bf16 v[88:91], v[226:229], v[210:213], v[88:91]
	v_mfma_f32_16x16x32_bf16 v[84:87], v[234:237], v[210:213], v[84:87]
	v_mfma_f32_16x16x32_bf16 v[72:75], v[226:229], v[218:221], v[72:75]
	v_mfma_f32_16x16x32_bf16 v[68:71], v[234:237], v[218:221], v[68:71]
	s_mov_b32 m0, s29
	v_lshl_add_u64 v[238:239], s[20:21], 0, v[0:1]
	s_barrier
	ds_read_b128 v[190:193], v149 offset:16384
	ds_read_b128 v[194:197], v149 offset:17408
	ds_read_b128 v[198:201], v149 offset:18432
	ds_read_b128 v[202:205], v149 offset:19456
	ds_read_b128 v[206:209], v149 offset:20480
	ds_read_b128 v[210:213], v149 offset:21504
	ds_read_b128 v[214:217], v149 offset:22528
	ds_read_b128 v[218:221], v149 offset:23552
	global_load_lds_dwordx4 v[238:239], off
	v_lshl_add_u64 v[240:241], s[20:21], 0, v[138:139]
	s_mov_b32 m0, s30
	s_nop 0
	global_load_lds_dwordx4 v[240:241], off
	s_barrier
	s_waitcnt lgkmcnt(0)
	s_waitcnt lgkmcnt(0)
	v_mfma_f32_16x16x32_bf16 v[64:67], v[132:135], v[190:193], v[64:67]
	v_mfma_f32_16x16x32_bf16 v[60:63], v[160:163], v[190:193], v[60:63]
	v_mfma_f32_16x16x32_bf16 v[48:51], v[132:135], v[198:201], v[48:51]
	v_mfma_f32_16x16x32_bf16 v[44:47], v[160:163], v[198:201], v[44:47]
	v_mfma_f32_16x16x32_bf16 v[32:35], v[132:135], v[206:209], v[32:35]
	v_mfma_f32_16x16x32_bf16 v[28:31], v[160:163], v[206:209], v[28:31]
	v_mfma_f32_16x16x32_bf16 v[16:19], v[132:135], v[214:217], v[16:19]
	v_mfma_f32_16x16x32_bf16 v[12:15], v[160:163], v[214:217], v[12:15]
	v_mfma_f32_16x16x32_bf16 v[64:67], v[156:159], v[194:197], v[64:67]
	v_mfma_f32_16x16x32_bf16 v[60:63], v[164:167], v[194:197], v[60:63]
	v_mfma_f32_16x16x32_bf16 v[48:51], v[156:159], v[202:205], v[48:51]
	v_mfma_f32_16x16x32_bf16 v[44:47], v[164:167], v[202:205], v[44:47]
	v_mfma_f32_16x16x32_bf16 v[32:35], v[156:159], v[210:213], v[32:35]
	v_mfma_f32_16x16x32_bf16 v[28:31], v[164:167], v[210:213], v[28:31]
	v_mfma_f32_16x16x32_bf16 v[16:19], v[156:159], v[218:221], v[16:19]
	v_mfma_f32_16x16x32_bf16 v[12:15], v[164:167], v[218:221], v[12:15]
	s_barrier
	s_add_u32 s56, s18, 0x80000
	s_addc_u32 s57, s19, 0
	s_add_i32 s58, s58, s28
	v_lshl_add_u64 v[132:133], s[56:57], 0, v[136:137]
	s_mov_b32 m0, s58
	s_nop 0
	global_load_lds_dwordx4 v[132:133], off
	v_lshl_add_u64 v[132:133], s[56:57], 0, v[140:141]
	s_add_i32 m0, s58, 0x2000
	s_nop 0
	global_load_lds_dwordx4 v[132:133], off
	s_waitcnt vmcnt(6)
	s_barrier
	v_mfma_f32_16x16x32_bf16 v[56:59], v[222:225], v[190:193], v[56:59]
	v_mfma_f32_16x16x32_bf16 v[52:55], v[230:233], v[190:193], v[52:55]
	v_mfma_f32_16x16x32_bf16 v[40:43], v[222:225], v[198:201], v[40:43]
	v_mfma_f32_16x16x32_bf16 v[36:39], v[230:233], v[198:201], v[36:39]
	v_mfma_f32_16x16x32_bf16 v[24:27], v[222:225], v[206:209], v[24:27]
	v_mfma_f32_16x16x32_bf16 v[20:23], v[230:233], v[206:209], v[20:23]
	v_mfma_f32_16x16x32_bf16 v[8:11], v[222:225], v[214:217], v[8:11]
	v_mfma_f32_16x16x32_bf16 v[4:7], v[230:233], v[214:217], v[4:7]
	v_mfma_f32_16x16x32_bf16 v[56:59], v[226:229], v[194:197], v[56:59]
	v_mfma_f32_16x16x32_bf16 v[52:55], v[234:237], v[194:197], v[52:55]
	v_mfma_f32_16x16x32_bf16 v[40:43], v[226:229], v[202:205], v[40:43]
	v_mfma_f32_16x16x32_bf16 v[36:39], v[234:237], v[202:205], v[36:39]
	v_mfma_f32_16x16x32_bf16 v[24:27], v[226:229], v[210:213], v[24:27]
	v_mfma_f32_16x16x32_bf16 v[20:23], v[234:237], v[210:213], v[20:23]
	v_mfma_f32_16x16x32_bf16 v[8:11], v[226:229], v[218:221], v[8:11]
	v_mfma_f32_16x16x32_bf16 v[4:7], v[234:237], v[218:221], v[4:7]
	s_add_i32 s56, 0, 0x18000
	v_add_u32_e32 v147, s56, v148
	s_barrier
	ds_read_b128 v[132:135], v147
	ds_read_b128 v[156:159], v147 offset:1024
	ds_read_b128 v[160:163], v147 offset:2048
	ds_read_b128 v[164:167], v147 offset:3072
	s_add_u32 s20, s20, 0x80000
	s_addc_u32 s21, s21, 0
	s_mov_b32 m0, s31
	v_lshl_add_u64 v[222:223], s[20:21], 0, v[0:1]
	ds_read_b128 v[190:193], v149 offset:32768
	ds_read_b128 v[194:197], v149 offset:33792
	ds_read_b128 v[198:201], v149 offset:34816
	ds_read_b128 v[202:205], v149 offset:35840
	ds_read_b128 v[206:209], v149 offset:36864
	ds_read_b128 v[210:213], v149 offset:37888
	ds_read_b128 v[214:217], v149 offset:38912
	ds_read_b128 v[218:221], v149 offset:39936
	global_load_lds_dwordx4 v[222:223], off
	v_lshl_add_u64 v[222:223], s[20:21], 0, v[138:139]
	s_mov_b32 m0, s34
	s_nop 0
	global_load_lds_dwordx4 v[222:223], off
	s_waitcnt lgkmcnt(8)
	s_barrier
; #define G8_STAGE(bufoff, gbase, voff) do { _Pragma("unroll") for (int _i = 0; _i < 2; ++_i) \
;     __builtin_amdgcn_global_load_lds((const unsigned*)((const char*)(gbase) + (voff)[_i]), (LAS unsigned*)(lds + (bufoff) + ldsw + _i * 8192), 16, 0, 0); } while (0)
; #define G8_LDA(dst, b, h) do { _Pragma("unroll") for (int m = 0; m < 4; ++m) _Pragma("unroll") for (int k = 0; k < 2; ++k) dst[m][k] = *(const LAS bf16x8*)(lds + G8_SA(b, h) + aoff + m * 2048 + k * 1024); } while (0)
; #define G8_MMA(ai, bj, At, Bt) do { __builtin_amdgcn_s_setprio(1); _Pragma("unroll") for (int m = 0; m < 4; ++m) _Pragma("unroll") for (int n = 0; n < 2; ++n) _Pragma("unroll") for (int k = 0; k < 2; ++k) \
;     acc[ai][bj][m][n] = __builtin_amdgcn_mfma_f32_16x16x32_bf16(Bt[n][k], At[m][k], acc[ai][bj][m][n], 0, 0, 0); __builtin_amdgcn_s_setprio(0); } while (0)
; #define G8_WAIT_V(n) asm volatile("s_waitcnt vmcnt(" #n ")" ::: "memory")
; #define G8_WAIT_L(n) asm volatile("s_waitcnt lgkmcnt(" #n ")" ::: "memory")
; #define G8_BAR __builtin_amdgcn_s_barrier()
; #define G8_SCHED __builtin_amdgcn_sched_barrier(0)
; template <class Epi, class Sched>
; __device__ __forceinline__ void gemm_phase(const int wv_, LAS unsigned char* lds, const int lda, const int ldb, const int K, const Sched& S, const Epi& E) {
;     ...
;       G8_BAR; G8_WAIT_L(0); G8_MMA(0, 1, At, B1); G8_BAR;
;       G8_LDA(At, 1, 1); G8_STAGE(G8_SA(1, 0), a3, voffA);
;       G8_BAR; G8_WAIT_L(0); G8_MMA(1, 0, At, B0); G8_BAR; G8_SCHED;
;       G8_STAGE(G8_SB(1, 1), b3 + hstepB, voffB);
;       G8_WAIT_V(6); G8_BAR; G8_MMA(1, 1, At, B1); G8_BAR;
;     }
;     const bool zero = E(acc, cur, wr, wc, fr, fq);
;     if (!has_next) break;
;   __device__ __forceinline__ bool operator()(f32x4 (&acc)[2][2][4][2], const Unit& u, int wr, int wc, int fr, int fq) const {
;     if (u.split == 2) return true;
;     const int row0 = u.pm * BM + wr * 64 + fr;
;     const bool gate = u.pn >= 28;
;     bf16_t* base = gate ? pg + (size_t)(u.pn - 28) * BM : png + (size_t)u.pn * BM;
;     const size_t ldc = gate ? 8192 : NNGP;
	s_waitcnt lgkmcnt(0)
	s_waitcnt lgkmcnt(0)
	v_mfma_f32_16x16x32_bf16 v[128:131], v[132:135], v[190:193], v[128:131]
	v_mfma_f32_16x16x32_bf16 v[124:127], v[160:163], v[190:193], v[124:127]
	v_mfma_f32_16x16x32_bf16 v[112:115], v[132:135], v[198:201], v[112:115]
	v_mfma_f32_16x16x32_bf16 v[108:111], v[160:163], v[198:201], v[108:111]
	v_mfma_f32_16x16x32_bf16 v[96:99], v[132:135], v[206:209], v[96:99]
	v_mfma_f32_16x16x32_bf16 v[92:95], v[160:163], v[206:209], v[92:95]
	v_mfma_f32_16x16x32_bf16 v[80:83], v[132:135], v[214:217], v[80:83]
	v_mfma_f32_16x16x32_bf16 v[76:79], v[160:163], v[214:217], v[76:79]
	v_mfma_f32_16x16x32_bf16 v[128:131], v[156:159], v[194:197], v[128:131]
	v_mfma_f32_16x16x32_bf16 v[124:127], v[164:167], v[194:197], v[124:127]
	v_mfma_f32_16x16x32_bf16 v[112:115], v[156:159], v[202:205], v[112:115]
	v_mfma_f32_16x16x32_bf16 v[108:111], v[164:167], v[202:205], v[108:111]
	v_mfma_f32_16x16x32_bf16 v[96:99], v[156:159], v[210:213], v[96:99]
	v_mfma_f32_16x16x32_bf16 v[92:95], v[164:167], v[210:213], v[92:95]
	v_mfma_f32_16x16x32_bf16 v[80:83], v[156:159], v[218:221], v[80:83]
	v_mfma_f32_16x16x32_bf16 v[76:79], v[164:167], v[218:221], v[76:79]
	s_barrier
	s_add_i32 s20, 0, 0x1c000
	s_add_i32 s21, s56, s28
	v_add_u32_e32 v147, s20, v148
	v_lshl_add_u64 v[150:151], v[150:151], 0, s[90:91]
	s_mov_b32 m0, s21
	ds_read_b128 v[222:225], v147
	ds_read_b128 v[226:229], v147 offset:1024
	ds_read_b128 v[230:233], v147 offset:2048
	ds_read_b128 v[234:237], v147 offset:3072
	global_load_lds_dwordx4 v[150:151], off
	v_lshl_add_u64 v[150:151], v[168:169], 0, s[90:91]
	s_add_i32 m0, s21, 0x2000
	s_nop 0
	global_load_lds_dwordx4 v[150:151], off
	s_barrier
	s_waitcnt lgkmcnt(0)
	s_waitcnt lgkmcnt(0)
	v_mfma_f32_16x16x32_bf16 v[120:123], v[222:225], v[190:193], v[120:123]
	v_mfma_f32_16x16x32_bf16 v[116:119], v[230:233], v[190:193], v[116:119]
	v_mfma_f32_16x16x32_bf16 v[104:107], v[222:225], v[198:201], v[104:107]
	v_mfma_f32_16x16x32_bf16 v[100:103], v[230:233], v[198:201], v[100:103]
	v_mfma_f32_16x16x32_bf16 v[88:91], v[222:225], v[206:209], v[88:91]
	v_mfma_f32_16x16x32_bf16 v[84:87], v[230:233], v[206:209], v[84:87]
	v_mfma_f32_16x16x32_bf16 v[72:75], v[222:225], v[214:217], v[72:75]
	v_mfma_f32_16x16x32_bf16 v[68:71], v[230:233], v[214:217], v[68:71]
	v_mfma_f32_16x16x32_bf16 v[120:123], v[226:229], v[194:197], v[120:123]
	v_mfma_f32_16x16x32_bf16 v[116:119], v[234:237], v[194:197], v[116:119]
	v_mfma_f32_16x16x32_bf16 v[104:107], v[226:229], v[202:205], v[104:107]
	v_mfma_f32_16x16x32_bf16 v[100:103], v[234:237], v[202:205], v[100:103]
	v_mfma_f32_16x16x32_bf16 v[88:91], v[226:229], v[210:213], v[88:91]
	v_mfma_f32_16x16x32_bf16 v[84:87], v[234:237], v[210:213], v[84:87]
	v_mfma_f32_16x16x32_bf16 v[72:75], v[226:229], v[218:221], v[72:75]
	v_mfma_f32_16x16x32_bf16 v[68:71], v[234:237], v[218:221], v[68:71]
	s_mov_b32 m0, s39
	v_lshl_add_u64 v[150:151], v[238:239], 0, s[90:91]
	s_barrier
	ds_read_b128 v[190:193], v149 offset:49152
	ds_read_b128 v[194:197], v149 offset:50176
	ds_read_b128 v[198:201], v149 offset:51200
	ds_read_b128 v[202:205], v149 offset:52224
	ds_read_b128 v[206:209], v149 offset:53248
	ds_read_b128 v[210:213], v149 offset:54272
	ds_read_b128 v[214:217], v149 offset:55296
	ds_read_b128 v[218:221], v149 offset:56320
	global_load_lds_dwordx4 v[150:151], off
	v_lshl_add_u64 v[150:151], v[240:241], 0, s[90:91]
	s_mov_b32 m0, s40
	s_nop 0
	global_load_lds_dwordx4 v[150:151], off
	s_barrier
	s_waitcnt lgkmcnt(0)
	s_waitcnt lgkmcnt(0)
	v_mfma_f32_16x16x32_bf16 v[64:67], v[132:135], v[190:193], v[64:67]
	v_mfma_f32_16x16x32_bf16 v[60:63], v[160:163], v[190:193], v[60:63]
	v_mfma_f32_16x16x32_bf16 v[48:51], v[132:135], v[198:201], v[48:51]
	v_mfma_f32_16x16x32_bf16 v[44:47], v[160:163], v[198:201], v[44:47]
	v_mfma_f32_16x16x32_bf16 v[32:35], v[132:135], v[206:209], v[32:35]
	v_mfma_f32_16x16x32_bf16 v[28:31], v[160:163], v[206:209], v[28:31]
	v_mfma_f32_16x16x32_bf16 v[16:19], v[132:135], v[214:217], v[16:19]
	v_mfma_f32_16x16x32_bf16 v[12:15], v[160:163], v[214:217], v[12:15]
	v_mfma_f32_16x16x32_bf16 v[64:67], v[156:159], v[194:197], v[64:67]
	v_mfma_f32_16x16x32_bf16 v[60:63], v[164:167], v[194:197], v[60:63]
	v_mfma_f32_16x16x32_bf16 v[48:51], v[156:159], v[202:205], v[48:51]
	v_mfma_f32_16x16x32_bf16 v[44:47], v[164:167], v[202:205], v[44:47]
	v_mfma_f32_16x16x32_bf16 v[32:35], v[156:159], v[210:213], v[32:35]
	v_mfma_f32_16x16x32_bf16 v[28:31], v[164:167], v[210:213], v[28:31]
	v_mfma_f32_16x16x32_bf16 v[16:19], v[156:159], v[218:221], v[16:19]
	v_mfma_f32_16x16x32_bf16 v[12:15], v[164:167], v[218:221], v[12:15]
	s_barrier
	s_add_u32 s18, s18, 0x80080
	s_addc_u32 s19, s19, 0
	s_add_i32 s20, s20, s28
	v_lshl_add_u64 v[132:133], s[18:19], 0, v[136:137]
	s_mov_b32 m0, s20
	s_nop 0
	global_load_lds_dwordx4 v[132:133], off
	v_lshl_add_u64 v[132:133], s[18:19], 0, v[140:141]
	s_add_i32 m0, s20, 0x2000
	s_nop 0
	global_load_lds_dwordx4 v[132:133], off
	s_waitcnt vmcnt(6)
	s_barrier
	v_mfma_f32_16x16x32_bf16 v[56:59], v[222:225], v[190:193], v[56:59]
	v_mfma_f32_16x16x32_bf16 v[52:55], v[230:233], v[190:193], v[52:55]
	v_mfma_f32_16x16x32_bf16 v[40:43], v[222:225], v[198:201], v[40:43]
	v_mfma_f32_16x16x32_bf16 v[36:39], v[230:233], v[198:201], v[36:39]
	v_mfma_f32_16x16x32_bf16 v[24:27], v[222:225], v[206:209], v[24:27]
	v_mfma_f32_16x16x32_bf16 v[20:23], v[230:233], v[206:209], v[20:23]
	v_mfma_f32_16x16x32_bf16 v[8:11], v[222:225], v[214:217], v[8:11]
	v_mfma_f32_16x16x32_bf16 v[4:7], v[230:233], v[214:217], v[4:7]
	v_mfma_f32_16x16x32_bf16 v[56:59], v[226:229], v[194:197], v[56:59]
	v_mfma_f32_16x16x32_bf16 v[52:55], v[234:237], v[194:197], v[52:55]
	v_mfma_f32_16x16x32_bf16 v[40:43], v[226:229], v[202:205], v[40:43]
	v_mfma_f32_16x16x32_bf16 v[36:39], v[234:237], v[202:205], v[36:39]
	v_mfma_f32_16x16x32_bf16 v[24:27], v[226:229], v[210:213], v[24:27]
	v_mfma_f32_16x16x32_bf16 v[20:23], v[234:237], v[210:213], v[20:23]
	v_mfma_f32_16x16x32_bf16 v[8:11], v[226:229], v[218:221], v[8:11]
	v_mfma_f32_16x16x32_bf16 v[4:7], v[234:237], v[218:221], v[4:7]
	s_add_u32 s4, s4, 0x100
	s_addc_u32 s5, s5, 0
	s_add_u32 s50, s50, 0x100
	s_addc_u32 s51, s51, 0
	s_cmp_ge_i32 s53, s47
	s_mov_b32 s18, s53
	s_barrier
	s_cbranch_scc0 .LBB0_207
	s_setprio 0
	s_cmp_eq_u32 s46, 2
	s_cbranch_scc1 .LBB0_202
	s_cmp_gt_i32 s27, 27
	s_cselect_b64 s[18:19], -1, 0
	s_cmp_lt_i32 s27, 28
	s_cselect_b64 s[20:21], -1, 0
	s_mov_b64 s[4:5], -1
	s_and_b64 vcc, exec, s[18:19]
	s_cbranch_vccnz .LBB0_211
	s_mov_b64 s[4:5], 0

; #define G8_STAGE(bufoff, gbase, voff) do { _Pragma("unroll") for (int _i = 0; _i < 2; ++_i) \
;     __builtin_amdgcn_global_load_lds((const unsigned*)((const char*)(gbase) + (voff)[_i]), (LAS unsigned*)(lds + (bufoff) + ldsw + _i * 8192), 16, 0, 0); } while (0)
; #define G8_LDA(dst, b, h) do { _Pragma("unroll") for (int m = 0; m < 4; ++m) _Pragma("unroll") for (int k = 0; k < 2; ++k) dst[m][k] = *(const LAS bf16x8*)(lds + G8_SA(b, h) + aoff + m * 2048 + k * 1024); } while (0)
; #define G8_LDB(dst, b, h) do { _Pragma("unroll") for (int n = 0; n < 2; ++n) _Pragma("unroll") for (int k = 0; k < 2; ++k) dst[n][k] = *(const LAS bf16x8*)(lds + G8_SB(b, h) + boff + n * 2048 + k * 1024); } while (0)
; #define G8_MMA(ai, bj, At, Bt) do { __builtin_amdgcn_s_setprio(1); _Pragma("unroll") for (int m = 0; m < 4; ++m) _Pragma("unroll") for (int n = 0; n < 2; ++n) _Pragma("unroll") for (int k = 0; k < 2; ++k) \
;     acc[ai][bj][m][n] = __builtin_amdgcn_mfma_f32_16x16x32_bf16(Bt[n][k], At[m][k], acc[ai][bj][m][n], 0, 0, 0); __builtin_amdgcn_s_setprio(0); } while (0)
; #define G8_WAIT_L(n) asm volatile("s_waitcnt lgkmcnt(" #n ")" ::: "memory")
; #define G8_BAR __builtin_amdgcn_s_barrier()
; #define G8_SCHED __builtin_amdgcn_sched_barrier(0)
; template <class Epi, class Sched>
; __device__ __forceinline__ void gemm_phase(const int wv_, LAS unsigned char* lds, const int lda, const int ldb, const int K, const Sched& S, const Epi& E) {
;     ...
;     for (int t = 0; t < nt; t += 2) {
;       const bool last = (t == nt - 2);
;       const char* a1 = cA + (size_t)(t + 1) * kstep;
;       const char* a2 = last ? nA : cA + (size_t)(t + 2) * kstep; const char* b2 = last ? nB : cB + (size_t)(t + 2) * kstep;
;       const char* a3 = a2 + kstep; const char* b3 = b2 + kstep;
;       G8_LDB(B0, 0, 0); G8_SCHED; G8_LDA(At, 0, 0); G8_STAGE(G8_SA(1, 1), a1 + hstepA, voffA);
;       G8_WAIT_L(8); G8_BAR; G8_WAIT_L(0); G8_MMA(0, 0, At, B0); G8_BAR; G8_SCHED;
;       G8_LDB(B1, 0, 1); G8_STAGE(G8_SB(0, 0), b2, voffB);
;       G8_BAR; G8_WAIT_L(0); G8_MMA(0, 1, At, B1); G8_BAR;
;       G8_LDA(At, 0, 1); G8_STAGE(G8_SA(0, 0), a2, voffA);
;       G8_BAR; G8_WAIT_L(0); G8_MMA(1, 0, At, B0); G8_BAR; G8_SCHED;
.LBB0_811:
	s_add_u32 s28, s28, 0x20080
	s_addc_u32 s29, s29, 0
	v_mov_b64_e32 v[142:143], s[14:15]
	s_add_u32 s11, s30, 0x100
	v_cmp_lt_i64_e64 s[8:9], s[8:9], v[142:143]
	s_addc_u32 s13, s31, 0
	s_mov_b32 s21, -2
	s_cmp_ge_u32 s72, 0x100
	s_cbranch_scc0 .Lg2_noprio
	s_setprio 1
.Lg2_noprio:
.LBB0_812:
	s_add_u32 s23, s28, 0xfffe0080
	s_addc_u32 s30, s29, -1
	s_add_i32 s69, 0, 0x10000
	v_add_u32_e32 v150, s69, v162
	ds_read_b128 v[142:145], v150
	ds_read_b128 v[146:149], v150 offset:1024
	ds_read_b128 v[156:159], v150 offset:2048
	ds_read_b128 v[166:169], v150 offset:3072
	s_cmp_eq_u32 s21, 4
	s_cselect_b32 s35, s25, s30
	s_cselect_b32 s34, s24, s23
	s_cselect_b32 s31, s27, s13
	s_cselect_b32 s30, s26, s11
	v_lshl_add_u64 v[150:151], s[28:29], 0, v[138:139]
	s_add_i32 m0, s46, 0xc000
	ds_read_b128 v[190:193], v164
	ds_read_b128 v[194:197], v164 offset:1024
	ds_read_b128 v[198:201], v164 offset:2048
	ds_read_b128 v[202:205], v164 offset:3072
	ds_read_b128 v[206:209], v164 offset:4096
	ds_read_b128 v[210:213], v164 offset:5120
	ds_read_b128 v[214:217], v164 offset:6144
	ds_read_b128 v[218:221], v164 offset:7168
	global_load_lds_dwordx4 v[150:151], off
	v_lshl_add_u64 v[150:151], s[28:29], 0, v[140:141]
	s_add_i32 m0, s46, 0xe000
	s_nop 0
	global_load_lds_dwordx4 v[150:151], off
	s_waitcnt lgkmcnt(8)
	s_barrier
	s_waitcnt lgkmcnt(0)
	s_waitcnt lgkmcnt(0)
	v_mfma_f32_16x16x32_bf16 v[128:131], v[142:145], v[190:193], v[128:131]
	v_mfma_f32_16x16x32_bf16 v[124:127], v[156:159], v[190:193], v[124:127]
	v_mfma_f32_16x16x32_bf16 v[120:123], v[142:145], v[198:201], v[120:123]
	v_mfma_f32_16x16x32_bf16 v[116:119], v[156:159], v[198:201], v[116:119]
	v_mfma_f32_16x16x32_bf16 v[112:115], v[142:145], v[206:209], v[112:115]
	v_mfma_f32_16x16x32_bf16 v[108:111], v[156:159], v[206:209], v[108:111]
	v_mfma_f32_16x16x32_bf16 v[104:107], v[142:145], v[214:217], v[104:107]
	v_mfma_f32_16x16x32_bf16 v[100:103], v[156:159], v[214:217], v[100:103]
	v_mfma_f32_16x16x32_bf16 v[128:131], v[146:149], v[194:197], v[128:131]
	v_mfma_f32_16x16x32_bf16 v[124:127], v[166:169], v[194:197], v[124:127]
	v_mfma_f32_16x16x32_bf16 v[120:123], v[146:149], v[202:205], v[120:123]
	v_mfma_f32_16x16x32_bf16 v[116:119], v[166:169], v[202:205], v[116:119]
	v_mfma_f32_16x16x32_bf16 v[112:115], v[146:149], v[210:213], v[112:115]
	v_mfma_f32_16x16x32_bf16 v[108:111], v[166:169], v[210:213], v[108:111]
	v_mfma_f32_16x16x32_bf16 v[104:107], v[146:149], v[218:221], v[104:107]
	v_mfma_f32_16x16x32_bf16 v[100:103], v[166:169], v[218:221], v[100:103]
	s_barrier
	s_add_i32 s23, 0, 0x14000
	v_add_u32_e32 v150, s23, v162
	s_add_i32 s69, s69, s43
	ds_read_b128 v[222:225], v150
	ds_read_b128 v[226:229], v150 offset:1024
	ds_read_b128 v[230:233], v150 offset:2048
	ds_read_b128 v[234:237], v150 offset:3072
	v_lshl_add_u64 v[150:151], s[30:31], 0, v[132:133]
	s_mov_b32 m0, s69
	v_lshl_add_u64 v[160:161], s[30:31], 0, v[136:137]
	global_load_lds_dwordx4 v[150:151], off
	s_add_i32 m0, s69, 0x2000
	s_nop 0
	global_load_lds_dwordx4 v[160:161], off
	s_barrier
	s_waitcnt lgkmcnt(0)
	s_waitcnt lgkmcnt(0)
	v_mfma_f32_16x16x32_bf16 v[96:99], v[222:225], v[190:193], v[96:99]
	v_mfma_f32_16x16x32_bf16 v[92:95], v[230:233], v[190:193], v[92:95]
	v_mfma_f32_16x16x32_bf16 v[88:91], v[222:225], v[198:201], v[88:91]
	v_mfma_f32_16x16x32_bf16 v[84:87], v[230:233], v[198:201], v[84:87]
	v_mfma_f32_16x16x32_bf16 v[80:83], v[222:225], v[206:209], v[80:83]
	v_mfma_f32_16x16x32_bf16 v[76:79], v[230:233], v[206:209], v[76:79]
	v_mfma_f32_16x16x32_bf16 v[72:75], v[222:225], v[214:217], v[72:75]
	v_mfma_f32_16x16x32_bf16 v[68:71], v[230:233], v[214:217], v[68:71]
	v_mfma_f32_16x16x32_bf16 v[96:99], v[226:229], v[194:197], v[96:99]
	v_mfma_f32_16x16x32_bf16 v[92:95], v[234:237], v[194:197], v[92:95]
	v_mfma_f32_16x16x32_bf16 v[88:91], v[226:229], v[202:205], v[88:91]
	v_mfma_f32_16x16x32_bf16 v[84:87], v[234:237], v[202:205], v[84:87]
	v_mfma_f32_16x16x32_bf16 v[80:83], v[226:229], v[210:213], v[80:83]
	v_mfma_f32_16x16x32_bf16 v[76:79], v[234:237], v[210:213], v[76:79]
	v_mfma_f32_16x16x32_bf16 v[72:75], v[226:229], v[218:221], v[72:75]
	v_mfma_f32_16x16x32_bf16 v[68:71], v[234:237], v[218:221], v[68:71]
	s_mov_b32 m0, s46
	v_lshl_add_u64 v[238:239], s[34:35], 0, v[0:1]
	s_barrier
	ds_read_b128 v[190:193], v164 offset:16384
	ds_read_b128 v[194:197], v164 offset:17408
	ds_read_b128 v[198:201], v164 offset:18432
	ds_read_b128 v[202:205], v164 offset:19456
	ds_read_b128 v[206:209], v164 offset:20480
	ds_read_b128 v[210:213], v164 offset:21504
	ds_read_b128 v[214:217], v164 offset:22528
	ds_read_b128 v[218:221], v164 offset:23552
	global_load_lds_dwordx4 v[238:239], off
	v_lshl_add_u64 v[240:241], s[34:35], 0, v[134:135]
	s_mov_b32 m0, s47
	s_nop 0
	global_load_lds_dwordx4 v[240:241], off
	s_barrier
	s_waitcnt lgkmcnt(0)
	s_waitcnt lgkmcnt(0)
	v_mfma_f32_16x16x32_bf16 v[64:67], v[142:145], v[190:193], v[64:67]
	v_mfma_f32_16x16x32_bf16 v[60:63], v[156:159], v[190:193], v[60:63]
	v_mfma_f32_16x16x32_bf16 v[56:59], v[142:145], v[198:201], v[56:59]
	v_mfma_f32_16x16x32_bf16 v[52:55], v[156:159], v[198:201], v[52:55]
	v_mfma_f32_16x16x32_bf16 v[48:51], v[142:145], v[206:209], v[48:51]
	v_mfma_f32_16x16x32_bf16 v[44:47], v[156:159], v[206:209], v[44:47]
	v_mfma_f32_16x16x32_bf16 v[40:43], v[142:145], v[214:217], v[40:43]
	v_mfma_f32_16x16x32_bf16 v[36:39], v[156:159], v[214:217], v[36:39]
	v_mfma_f32_16x16x32_bf16 v[64:67], v[146:149], v[194:197], v[64:67]
	v_mfma_f32_16x16x32_bf16 v[60:63], v[166:169], v[194:197], v[60:63]
	v_mfma_f32_16x16x32_bf16 v[56:59], v[146:149], v[202:205], v[56:59]
	v_mfma_f32_16x16x32_bf16 v[52:55], v[166:169], v[202:205], v[52:55]
	v_mfma_f32_16x16x32_bf16 v[48:51], v[146:149], v[210:213], v[48:51]
	v_mfma_f32_16x16x32_bf16 v[44:47], v[166:169], v[210:213], v[44:47]
	v_mfma_f32_16x16x32_bf16 v[40:43], v[146:149], v[218:221], v[40:43]
	v_mfma_f32_16x16x32_bf16 v[36:39], v[166:169], v[218:221], v[36:39]
	s_barrier
; #define G8_STAGE(bufoff, gbase, voff) do { _Pragma("unroll") for (int _i = 0; _i < 2; ++_i) \
;     __builtin_amdgcn_global_load_lds((const unsigned*)((const char*)(gbase) + (voff)[_i]), (LAS unsigned*)(lds + (bufoff) + ldsw + _i * 8192), 16, 0, 0); } while (0)
; #define G8_LDA(dst, b, h) do { _Pragma("unroll") for (int m = 0; m < 4; ++m) _Pragma("unroll") for (int k = 0; k < 2; ++k) dst[m][k] = *(const LAS bf16x8*)(lds + G8_SA(b, h) + aoff + m * 2048 + k * 1024); } while (0)
; #define G8_LDB(dst, b, h) do { _Pragma("unroll") for (int n = 0; n < 2; ++n) _Pragma("unroll") for (int k = 0; k < 2; ++k) dst[n][k] = *(const LAS bf16x8*)(lds + G8_SB(b, h) + boff + n * 2048 + k * 1024); } while (0)
; #define G8_MMA(ai, bj, At, Bt) do { __builtin_amdgcn_s_setprio(1); _Pragma("unroll") for (int m = 0; m < 4; ++m) _Pragma("unroll") for (int n = 0; n < 2; ++n) _Pragma("unroll") for (int k = 0; k < 2; ++k) \
;     acc[ai][bj][m][n] = __builtin_amdgcn_mfma_f32_16x16x32_bf16(Bt[n][k], At[m][k], acc[ai][bj][m][n], 0, 0, 0); __builtin_amdgcn_s_setprio(0); } while (0)
; #define G8_WAIT_V(n) asm volatile("s_waitcnt vmcnt(" #n ")" ::: "memory")
; #define G8_WAIT_L(n) asm volatile("s_waitcnt lgkmcnt(" #n ")" ::: "memory")
; #define G8_BAR __builtin_amdgcn_s_barrier()
; #define G8_SCHED __builtin_amdgcn_sched_barrier(0)
; template <class Epi, class Sched>
; __device__ __forceinline__ void gemm_phase(const int wv_, LAS unsigned char* lds, const int lda, const int ldb, const int K, const Sched& S, const Epi& E) {
;     ...
;       G8_STAGE(G8_SB(0, 1), b2 + hstepB, voffB);
;       G8_WAIT_V(6); G8_BAR; G8_MMA(1, 1, At, B1); G8_BAR;
;       G8_LDB(B0, 1, 0); G8_SCHED; G8_LDA(At, 1, 0); G8_STAGE(G8_SA(0, 1), a2 + hstepA, voffA);
;       G8_WAIT_L(8); G8_BAR; G8_WAIT_L(0); G8_MMA(0, 0, At, B0); G8_BAR; G8_SCHED;
;       G8_LDB(B1, 1, 1); G8_STAGE(G8_SB(1, 0), b3, voffB);
;       G8_BAR; G8_WAIT_L(0); G8_MMA(0, 1, At, B1); G8_BAR;
;       G8_LDA(At, 1, 1); G8_STAGE(G8_SA(1, 0), a3, voffA);
;       G8_BAR; G8_WAIT_L(0); G8_MMA(1, 0, At, B0); G8_BAR; G8_SCHED;
;       G8_STAGE(G8_SB(1, 1), b3 + hstepB, voffB);
	s_add_u32 s70, s30, 0x20000
	s_addc_u32 s71, s31, 0
	s_add_i32 s23, s23, s43
	v_lshl_add_u64 v[142:143], s[70:71], 0, v[132:133]
	s_mov_b32 m0, s23
	s_nop 0
	global_load_lds_dwordx4 v[142:143], off
	v_lshl_add_u64 v[142:143], s[70:71], 0, v[136:137]
	s_add_i32 m0, s23, 0x2000
	s_nop 0
	global_load_lds_dwordx4 v[142:143], off
	s_waitcnt vmcnt(6)
	s_barrier
	v_mfma_f32_16x16x32_bf16 v[32:35], v[222:225], v[190:193], v[32:35]
	v_mfma_f32_16x16x32_bf16 v[28:31], v[230:233], v[190:193], v[28:31]
	v_mfma_f32_16x16x32_bf16 v[24:27], v[222:225], v[198:201], v[24:27]
	v_mfma_f32_16x16x32_bf16 v[20:23], v[230:233], v[198:201], v[20:23]
	v_mfma_f32_16x16x32_bf16 v[16:19], v[222:225], v[206:209], v[16:19]
	v_mfma_f32_16x16x32_bf16 v[12:15], v[230:233], v[206:209], v[12:15]
	v_mfma_f32_16x16x32_bf16 v[8:11], v[222:225], v[214:217], v[8:11]
	v_mfma_f32_16x16x32_bf16 v[4:7], v[230:233], v[214:217], v[4:7]
	v_mfma_f32_16x16x32_bf16 v[32:35], v[226:229], v[194:197], v[32:35]
	v_mfma_f32_16x16x32_bf16 v[28:31], v[234:237], v[194:197], v[28:31]
	v_mfma_f32_16x16x32_bf16 v[24:27], v[226:229], v[202:205], v[24:27]
	v_mfma_f32_16x16x32_bf16 v[20:23], v[234:237], v[202:205], v[20:23]
	v_mfma_f32_16x16x32_bf16 v[16:19], v[226:229], v[210:213], v[16:19]
	v_mfma_f32_16x16x32_bf16 v[12:15], v[234:237], v[210:213], v[12:15]
	v_mfma_f32_16x16x32_bf16 v[8:11], v[226:229], v[218:221], v[8:11]
	v_mfma_f32_16x16x32_bf16 v[4:7], v[234:237], v[218:221], v[4:7]
	s_add_i32 s23, 0, 0x18000
	v_add_u32_e32 v165, s23, v162
	s_barrier
	ds_read_b128 v[142:145], v165
	ds_read_b128 v[146:149], v165 offset:1024
	ds_read_b128 v[156:159], v165 offset:2048
	ds_read_b128 v[166:169], v165 offset:3072
	s_add_u32 s34, s34, 0x20000
	s_addc_u32 s35, s35, 0
	s_mov_b32 m0, s50
	v_lshl_add_u64 v[222:223], s[34:35], 0, v[0:1]
	ds_read_b128 v[190:193], v164 offset:32768
	ds_read_b128 v[194:197], v164 offset:33792
	ds_read_b128 v[198:201], v164 offset:34816
	ds_read_b128 v[202:205], v164 offset:35840
	ds_read_b128 v[206:209], v164 offset:36864
	ds_read_b128 v[210:213], v164 offset:37888
	ds_read_b128 v[214:217], v164 offset:38912
	ds_read_b128 v[218:221], v164 offset:39936
	global_load_lds_dwordx4 v[222:223], off
	v_lshl_add_u64 v[222:223], s[34:35], 0, v[134:135]
	s_mov_b32 m0, s51
	s_nop 0
	global_load_lds_dwordx4 v[222:223], off
	s_waitcnt lgkmcnt(8)
	s_barrier
	s_waitcnt lgkmcnt(0)
	s_waitcnt lgkmcnt(0)
	v_mfma_f32_16x16x32_bf16 v[128:131], v[142:145], v[190:193], v[128:131]
	v_mfma_f32_16x16x32_bf16 v[124:127], v[156:159], v[190:193], v[124:127]
	v_mfma_f32_16x16x32_bf16 v[120:123], v[142:145], v[198:201], v[120:123]
	v_mfma_f32_16x16x32_bf16 v[116:119], v[156:159], v[198:201], v[116:119]
	v_mfma_f32_16x16x32_bf16 v[112:115], v[142:145], v[206:209], v[112:115]
	v_mfma_f32_16x16x32_bf16 v[108:111], v[156:159], v[206:209], v[108:111]
	v_mfma_f32_16x16x32_bf16 v[104:107], v[142:145], v[214:217], v[104:107]
	v_mfma_f32_16x16x32_bf16 v[100:103], v[156:159], v[214:217], v[100:103]
	v_mfma_f32_16x16x32_bf16 v[128:131], v[146:149], v[194:197], v[128:131]
	v_mfma_f32_16x16x32_bf16 v[124:127], v[166:169], v[194:197], v[124:127]
	v_mfma_f32_16x16x32_bf16 v[120:123], v[146:149], v[202:205], v[120:123]
	v_mfma_f32_16x16x32_bf16 v[116:119], v[166:169], v[202:205], v[116:119]
	v_mfma_f32_16x16x32_bf16 v[112:115], v[146:149], v[210:213], v[112:115]
	v_mfma_f32_16x16x32_bf16 v[108:111], v[166:169], v[210:213], v[108:111]
	v_mfma_f32_16x16x32_bf16 v[104:107], v[146:149], v[218:221], v[104:107]
	v_mfma_f32_16x16x32_bf16 v[100:103], v[166:169], v[218:221], v[100:103]
	s_barrier
	s_add_i32 s34, 0, 0x1c000
	s_add_i32 s23, s23, s43
	v_add_u32_e32 v165, s34, v162
	v_lshl_add_u64 v[150:151], v[150:151], 0, s[90:91]
	s_mov_b32 m0, s23
	ds_read_b128 v[222:225], v165
	ds_read_b128 v[226:229], v165 offset:1024
	ds_read_b128 v[230:233], v165 offset:2048
	ds_read_b128 v[234:237], v165 offset:3072
	global_load_lds_dwordx4 v[150:151], off
	v_lshl_add_u64 v[150:151], v[160:161], 0, s[90:91]
	s_add_i32 m0, s23, 0x2000
	s_nop 0
	global_load_lds_dwordx4 v[150:151], off
	s_barrier
	s_waitcnt lgkmcnt(0)
	s_waitcnt lgkmcnt(0)
	v_mfma_f32_16x16x32_bf16 v[96:99], v[222:225], v[190:193], v[96:99]
	v_mfma_f32_16x16x32_bf16 v[92:95], v[230:233], v[190:193], v[92:95]
	v_mfma_f32_16x16x32_bf16 v[88:91], v[222:225], v[198:201], v[88:91]
	v_mfma_f32_16x16x32_bf16 v[84:87], v[230:233], v[198:201], v[84:87]
	v_mfma_f32_16x16x32_bf16 v[80:83], v[222:225], v[206:209], v[80:83]
	v_mfma_f32_16x16x32_bf16 v[76:79], v[230:233], v[206:209], v[76:79]
	v_mfma_f32_16x16x32_bf16 v[72:75], v[222:225], v[214:217], v[72:75]
	v_mfma_f32_16x16x32_bf16 v[68:71], v[230:233], v[214:217], v[68:71]
	v_mfma_f32_16x16x32_bf16 v[96:99], v[226:229], v[194:197], v[96:99]
	v_mfma_f32_16x16x32_bf16 v[92:95], v[234:237], v[194:197], v[92:95]
	v_mfma_f32_16x16x32_bf16 v[88:91], v[226:229], v[202:205], v[88:91]
	v_mfma_f32_16x16x32_bf16 v[84:87], v[234:237], v[202:205], v[84:87]
	v_mfma_f32_16x16x32_bf16 v[80:83], v[226:229], v[210:213], v[80:83]
	v_mfma_f32_16x16x32_bf16 v[76:79], v[234:237], v[210:213], v[76:79]
	v_mfma_f32_16x16x32_bf16 v[72:75], v[226:229], v[218:221], v[72:75]
	v_mfma_f32_16x16x32_bf16 v[68:71], v[234:237], v[218:221], v[68:71]
	s_mov_b32 m0, s56
	v_lshl_add_u64 v[150:151], v[238:239], 0, s[90:91]
	s_barrier
	ds_read_b128 v[190:193], v164 offset:49152
	ds_read_b128 v[194:197], v164 offset:50176
	ds_read_b128 v[198:201], v164 offset:51200
	ds_read_b128 v[202:205], v164 offset:52224
	ds_read_b128 v[206:209], v164 offset:53248
	ds_read_b128 v[210:213], v164 offset:54272
	ds_read_b128 v[214:217], v164 offset:55296
	ds_read_b128 v[218:221], v164 offset:56320
	global_load_lds_dwordx4 v[150:151], off
	v_lshl_add_u64 v[150:151], v[240:241], 0, s[90:91]
	s_mov_b32 m0, s57
	s_nop 0
	global_load_lds_dwordx4 v[150:151], off
	s_barrier
; __device__ __forceinline__ float lo16(unsigned u) { return __uint_as_float(u << 16); }
; __device__ __forceinline__ float hi16(unsigned u) { return __uint_as_float(u & 0xffff0000u); }
; #define G8_STAGE(bufoff, gbase, voff) do { _Pragma("unroll") for (int _i = 0; _i < 2; ++_i) \
;     __builtin_amdgcn_global_load_lds((const unsigned*)((const char*)(gbase) + (voff)[_i]), (LAS unsigned*)(lds + (bufoff) + ldsw + _i * 8192), 16, 0, 0); } while (0)
; #define G8_MMA(ai, bj, At, Bt) do { __builtin_amdgcn_s_setprio(1); _Pragma("unroll") for (int m = 0; m < 4; ++m) _Pragma("unroll") for (int n = 0; n < 2; ++n) _Pragma("unroll") for (int k = 0; k < 2; ++k) \
;     acc[ai][bj][m][n] = __builtin_amdgcn_mfma_f32_16x16x32_bf16(Bt[n][k], At[m][k], acc[ai][bj][m][n], 0, 0, 0); __builtin_amdgcn_s_setprio(0); } while (0)
; template <class Epi, class Sched>
; __device__ __forceinline__ void gemm_phase(const int wv_, LAS unsigned char* lds, const int lda, const int ldb, const int K, const Sched& S, const Epi& E) {
;     ...
;       G8_STAGE(G8_SB(1, 1), b3 + hstepB, voffB);
;       G8_WAIT_V(6); G8_BAR; G8_MMA(1, 1, At, B1); G8_BAR;
;     }
;   __device__ __forceinline__ bool operator()(f32x4 (&acc)[2][2][4][2], const Unit& u, int wr, int wc, int fr, int fq) const {
;     const int row0 = u.pm * BM + wr * 64 + fr, col0 = u.pn * BM + wc * 32 + 8 * fq, j = u.j;
; #pragma unroll
;     for (int ai = 0; ai < 2; ++ai)
; #pragma unroll
;       for (int m = 0; m < 4; ++m) { const size_t row = (size_t)(row0 + ai * HALF + m * 16);
; #pragma unroll
;         for (int bj = 0; bj < 2; ++bj) {
;           const bf16_t* sp = pg + row * 8192 + (size_t)j * 2048 + col0 + bj * HALF;
;           const u32x4 sc = *(const u32x4*)sp;
;           float f[8] = {lo16(sc.x), hi16(sc.x), lo16(sc.y), hi16(sc.y), lo16(sc.z), hi16(sc.z), lo16(sc.w), hi16(sc.w)};
;           if (j < 3) { const u32x4 sn = *(const u32x4*)(sp + 2048);
;             float g[8] = {lo16(sn.x), hi16(sn.x), lo16(sn.y), hi16(sn.y), lo16(sn.z), hi16(sn.z), lo16(sn.w), hi16(sn.w)};
; #pragma unroll
;             for (int e = 0; e < 8; ++e) f[e] = f[e] * __builtin_amdgcn_rcpf(fmaxf(g[e], 1e-30f)); }
;           f32x4 v0 = acc[ai][bj][m][0], v1 = acc[ai][bj][m][1];
; #pragma unroll
;           for (int e = 0; e < 4; ++e) { v0[e] *= f[e]; v1[e] *= f[4 + e]; }
;           acc[ai][bj][m][0] = v0; acc[ai][bj][m][1] = v1;
	s_waitcnt lgkmcnt(0)
	s_waitcnt lgkmcnt(0)
	v_mfma_f32_16x16x32_bf16 v[64:67], v[142:145], v[190:193], v[64:67]
	v_mfma_f32_16x16x32_bf16 v[60:63], v[156:159], v[190:193], v[60:63]
	v_mfma_f32_16x16x32_bf16 v[56:59], v[142:145], v[198:201], v[56:59]
	v_mfma_f32_16x16x32_bf16 v[52:55], v[156:159], v[198:201], v[52:55]
	v_mfma_f32_16x16x32_bf16 v[48:51], v[142:145], v[206:209], v[48:51]
	v_mfma_f32_16x16x32_bf16 v[44:47], v[156:159], v[206:209], v[44:47]
	v_mfma_f32_16x16x32_bf16 v[40:43], v[142:145], v[214:217], v[40:43]
	v_mfma_f32_16x16x32_bf16 v[36:39], v[156:159], v[214:217], v[36:39]
	v_mfma_f32_16x16x32_bf16 v[64:67], v[146:149], v[194:197], v[64:67]
	v_mfma_f32_16x16x32_bf16 v[60:63], v[166:169], v[194:197], v[60:63]
	v_mfma_f32_16x16x32_bf16 v[56:59], v[146:149], v[202:205], v[56:59]
	v_mfma_f32_16x16x32_bf16 v[52:55], v[166:169], v[202:205], v[52:55]
	v_mfma_f32_16x16x32_bf16 v[48:51], v[146:149], v[210:213], v[48:51]
	v_mfma_f32_16x16x32_bf16 v[44:47], v[166:169], v[210:213], v[44:47]
	v_mfma_f32_16x16x32_bf16 v[40:43], v[146:149], v[218:221], v[40:43]
	v_mfma_f32_16x16x32_bf16 v[36:39], v[166:169], v[218:221], v[36:39]
	s_barrier
	s_add_u32 s30, s30, 0x20080
	s_addc_u32 s31, s31, 0
	s_add_i32 s23, s34, s43
	v_lshl_add_u64 v[142:143], s[30:31], 0, v[132:133]
	s_mov_b32 m0, s23
	s_nop 0
	global_load_lds_dwordx4 v[142:143], off
	v_lshl_add_u64 v[142:143], s[30:31], 0, v[136:137]
	s_add_i32 m0, s23, 0x2000
	s_nop 0
	global_load_lds_dwordx4 v[142:143], off
	s_waitcnt vmcnt(6)
	s_barrier
	v_mfma_f32_16x16x32_bf16 v[32:35], v[222:225], v[190:193], v[32:35]
	v_mfma_f32_16x16x32_bf16 v[28:31], v[230:233], v[190:193], v[28:31]
	v_mfma_f32_16x16x32_bf16 v[24:27], v[222:225], v[198:201], v[24:27]
	v_mfma_f32_16x16x32_bf16 v[20:23], v[230:233], v[198:201], v[20:23]
	v_mfma_f32_16x16x32_bf16 v[16:19], v[222:225], v[206:209], v[16:19]
	v_mfma_f32_16x16x32_bf16 v[12:15], v[230:233], v[206:209], v[12:15]
	v_mfma_f32_16x16x32_bf16 v[8:11], v[222:225], v[214:217], v[8:11]
	v_mfma_f32_16x16x32_bf16 v[4:7], v[230:233], v[214:217], v[4:7]
	v_mfma_f32_16x16x32_bf16 v[32:35], v[226:229], v[194:197], v[32:35]
	v_mfma_f32_16x16x32_bf16 v[28:31], v[234:237], v[194:197], v[28:31]
	v_mfma_f32_16x16x32_bf16 v[24:27], v[226:229], v[202:205], v[24:27]
	v_mfma_f32_16x16x32_bf16 v[20:23], v[234:237], v[202:205], v[20:23]
	v_mfma_f32_16x16x32_bf16 v[16:19], v[226:229], v[210:213], v[16:19]
	v_mfma_f32_16x16x32_bf16 v[12:15], v[234:237], v[210:213], v[12:15]
	v_mfma_f32_16x16x32_bf16 v[8:11], v[226:229], v[218:221], v[8:11]
	v_mfma_f32_16x16x32_bf16 v[4:7], v[234:237], v[218:221], v[4:7]
	s_add_i32 s21, s21, 2
	s_add_u32 s28, s28, 0x100
	s_addc_u32 s29, s29, 0
	s_add_u32 s11, s11, 0x100
	s_addc_u32 s13, s13, 0
	s_cmp_gt_u32 s21, 5
	s_barrier
	s_cbranch_scc0 .LBB0_812
	s_setprio 0
	s_lshl_b32 s11, s12, 22
	s_lshl_b32 s13, s10, 12
	s_add_u32 s30, s16, s11
	s_addc_u32 s31, s17, 0
	s_add_u32 s30, s30, s13
	s_addc_u32 s31, s31, 0
	s_lshl_b32 s13, s68, 9
	s_add_u32 s30, s30, s13
	s_addc_u32 s31, s31, 0
	v_lshlrev_b32_e32 v165, 1, v163
	v_lshl_add_u32 v160, v3, 14, v165
	v_mov_b32_e32 v161, 0
	v_lshl_add_u64 v[160:161], v[160:161], 0, s[30:31]
	s_mov_b32 s28, 0x40000
	s_mov_b32 s29, 0
	s_cmp_eq_u32 s10, 3
	s_cbranch_scc1 .Lg2e_eq3
	s_mov_b64 s[34:35], 0x1000
	v_lshl_add_u64 v[150:151], v[160:161], 0, s[34:35]
	global_load_dwordx4 v[190:193], v[160:161], off
	global_load_dwordx4 v[194:197], v[150:151], off
	global_load_dwordx4 v[198:201], v[160:161], off offset:256
	global_load_dwordx4 v[202:205], v[150:151], off offset:256
	v_lshl_add_u64 v[160:161], v[160:161], 0, s[28:29]
	v_lshl_add_u64 v[150:151], v[150:151], 0, s[28:29]
	global_load_dwordx4 v[206:209], v[160:161], off
	global_load_dwordx4 v[210:213], v[150:151], off
	global_load_dwordx4 v[214:217], v[160:161], off offset:256
	global_load_dwordx4 v[218:221], v[150:151], off offset:256
	v_lshl_add_u64 v[160:161], v[160:161], 0, s[28:29]
	v_lshl_add_u64 v[150:151], v[150:151], 0, s[28:29]
	global_load_dwordx4 v[222:225], v[160:161], off
	global_load_dwordx4 v[226:229], v[150:151], off
	global_load_dwordx4 v[230:233], v[160:161], off offset:256
	global_load_dwordx4 v[234:237], v[150:151], off offset:256
	v_lshl_add_u64 v[160:161], v[160:161], 0, s[28:29]
	v_lshl_add_u64 v[150:151], v[150:151], 0, s[28:29]
	global_load_dwordx4 v[238:241], v[160:161], off
	global_load_dwordx4 v[142:145], v[150:151], off
	global_load_dwordx4 v[146:149], v[160:161], off offset:256
	global_load_dwordx4 v[156:159], v[150:151], off offset:256
	s_mov_b32 s28, 0x140000
	v_lshl_add_u64 v[160:161], v[160:161], 0, s[28:29]
	s_mov_b32 s28, 0x40000
	s_mov_b32 s28, 0x140000
	v_lshl_add_u64 v[150:151], v[150:151], 0, s[28:29]
	s_mov_b32 s28, 0x40000
	s_waitcnt vmcnt(14)
	v_lshlrev_b32_e32 v168, 16, v194
	v_and_b32_e32 v169, 0xffff0000, v194
	v_max_f32_e32 v168, 0xda24260, v168
	v_max_f32_e32 v169, 0xda24260, v169
	v_rcp_f32_e32 v168, v168
	v_rcp_f32_e32 v169, v169
	v_lshlrev_b32_e32 v166, 16, v190
	v_and_b32_e32 v167, 0xffff0000, v190
	v_pk_mul_f32 v[166:167], v[168:169], v[166:167]
	v_pk_mul_f32 v[128:129], v[128:129], v[166:167]
	v_lshlrev_b32_e32 v168, 16, v195
	v_and_b32_e32 v169, 0xffff0000, v195
	v_max_f32_e32 v168, 0xda24260, v168
	v_max_f32_e32 v169, 0xda24260, v169
	v_rcp_f32_e32 v168, v168
	v_rcp_f32_e32 v169, v169
	v_lshlrev_b32_e32 v166, 16, v191
	v_and_b32_e32 v167, 0xffff0000, v191
	v_pk_mul_f32 v[166:167], v[168:169], v[166:167]
	v_pk_mul_f32 v[130:131], v[130:131], v[166:167]
	v_lshlrev_b32_e32 v168, 16, v196
	v_and_b32_e32 v169, 0xffff0000, v196
	v_max_f32_e32 v168, 0xda24260, v168
	v_max_f32_e32 v169, 0xda24260, v169
	v_rcp_f32_e32 v168, v168
	v_rcp_f32_e32 v169, v169
	v_lshlrev_b32_e32 v166, 16, v192
	v_and_b32_e32 v167, 0xffff0000, v192
	v_pk_mul_f32 v[166:167], v[168:169], v[166:167]
	v_pk_mul_f32 v[124:125], v[124:125], v[166:167]
	v_lshlrev_b32_e32 v168, 16, v197
	v_and_b32_e32 v169, 0xffff0000, v197
	v_max_f32_e32 v168, 0xda24260, v168
	v_max_f32_e32 v169, 0xda24260, v169
	v_rcp_f32_e32 v168, v168
	v_rcp_f32_e32 v169, v169
	v_lshlrev_b32_e32 v166, 16, v193
	v_and_b32_e32 v167, 0xffff0000, v193
	v_pk_mul_f32 v[166:167], v[168:169], v[166:167]
	v_pk_mul_f32 v[126:127], v[126:127], v[166:167]
	global_load_dwordx4 v[190:193], v[160:161], off
	global_load_dwordx4 v[194:197], v[150:151], off
	s_waitcnt vmcnt(14)
; __device__ __forceinline__ float lo16(unsigned u) { return __uint_as_float(u << 16); }
; __device__ __forceinline__ float hi16(unsigned u) { return __uint_as_float(u & 0xffff0000u); }
;   __device__ __forceinline__ bool operator()(f32x4 (&acc)[2][2][4][2], const Unit& u, int wr, int wc, int fr, int fq) const {
;     ...
;       for (int m = 0; m < 4; ++m) { const size_t row = (size_t)(row0 + ai * HALF + m * 16);
; #pragma unroll
;         for (int bj = 0; bj < 2; ++bj) {
;           const bf16_t* sp = pg + row * 8192 + (size_t)j * 2048 + col0 + bj * HALF;
;           const u32x4 sc = *(const u32x4*)sp;
;           float f[8] = {lo16(sc.x), hi16(sc.x), lo16(sc.y), hi16(sc.y), lo16(sc.z), hi16(sc.z), lo16(sc.w), hi16(sc.w)};
;           if (j < 3) { const u32x4 sn = *(const u32x4*)(sp + 2048);
;             float g[8] = {lo16(sn.x), hi16(sn.x), lo16(sn.y), hi16(sn.y), lo16(sn.z), hi16(sn.z), lo16(sn.w), hi16(sn.w)};
; #pragma unroll
;             for (int e = 0; e < 8; ++e) f[e] = f[e] * __builtin_amdgcn_rcpf(fmaxf(g[e], 1e-30f)); }
;           f32x4 v0 = acc[ai][bj][m][0], v1 = acc[ai][bj][m][1];
; #pragma unroll
;           for (int e = 0; e < 4; ++e) { v0[e] *= f[e]; v1[e] *= f[4 + e]; }
;           acc[ai][bj][m][0] = v0; acc[ai][bj][m][1] = v1;
	v_lshlrev_b32_e32 v168, 16, v202
	v_and_b32_e32 v169, 0xffff0000, v202
	v_max_f32_e32 v168, 0xda24260, v168
	v_max_f32_e32 v169, 0xda24260, v169
	v_rcp_f32_e32 v168, v168
	v_rcp_f32_e32 v169, v169
	v_lshlrev_b32_e32 v166, 16, v198
	v_and_b32_e32 v167, 0xffff0000, v198
	v_pk_mul_f32 v[166:167], v[168:169], v[166:167]
	v_pk_mul_f32 v[96:97], v[96:97], v[166:167]
	v_lshlrev_b32_e32 v168, 16, v203
	v_and_b32_e32 v169, 0xffff0000, v203
	v_max_f32_e32 v168, 0xda24260, v168
	v_max_f32_e32 v169, 0xda24260, v169
	v_rcp_f32_e32 v168, v168
	v_rcp_f32_e32 v169, v169
	v_lshlrev_b32_e32 v166, 16, v199
	v_and_b32_e32 v167, 0xffff0000, v199
	v_pk_mul_f32 v[166:167], v[168:169], v[166:167]
	v_pk_mul_f32 v[98:99], v[98:99], v[166:167]
	v_lshlrev_b32_e32 v168, 16, v204
	v_and_b32_e32 v169, 0xffff0000, v204
	v_max_f32_e32 v168, 0xda24260, v168
	v_max_f32_e32 v169, 0xda24260, v169
	v_rcp_f32_e32 v168, v168
	v_rcp_f32_e32 v169, v169
	v_lshlrev_b32_e32 v166, 16, v200
	v_and_b32_e32 v167, 0xffff0000, v200
	v_pk_mul_f32 v[166:167], v[168:169], v[166:167]
	v_pk_mul_f32 v[92:93], v[92:93], v[166:167]
	v_lshlrev_b32_e32 v168, 16, v205
	v_and_b32_e32 v169, 0xffff0000, v205
	v_max_f32_e32 v168, 0xda24260, v168
	v_max_f32_e32 v169, 0xda24260, v169
	v_rcp_f32_e32 v168, v168
	v_rcp_f32_e32 v169, v169
	v_lshlrev_b32_e32 v166, 16, v201
	v_and_b32_e32 v167, 0xffff0000, v201
	v_pk_mul_f32 v[166:167], v[168:169], v[166:167]
	v_pk_mul_f32 v[94:95], v[94:95], v[166:167]
	global_load_dwordx4 v[198:201], v[160:161], off offset:256
	global_load_dwordx4 v[202:205], v[150:151], off offset:256
	v_lshl_add_u64 v[160:161], v[160:161], 0, s[28:29]
	v_lshl_add_u64 v[150:151], v[150:151], 0, s[28:29]
	s_waitcnt vmcnt(14)
	v_lshlrev_b32_e32 v168, 16, v210
	v_and_b32_e32 v169, 0xffff0000, v210
	v_max_f32_e32 v168, 0xda24260, v168
	v_max_f32_e32 v169, 0xda24260, v169
	v_rcp_f32_e32 v168, v168
	v_rcp_f32_e32 v169, v169
	v_lshlrev_b32_e32 v166, 16, v206
	v_and_b32_e32 v167, 0xffff0000, v206
	v_pk_mul_f32 v[166:167], v[168:169], v[166:167]
	v_pk_mul_f32 v[120:121], v[120:121], v[166:167]
	v_lshlrev_b32_e32 v168, 16, v211
	v_and_b32_e32 v169, 0xffff0000, v211
	v_max_f32_e32 v168, 0xda24260, v168
	v_max_f32_e32 v169, 0xda24260, v169
	v_rcp_f32_e32 v168, v168
	v_rcp_f32_e32 v169, v169
	v_lshlrev_b32_e32 v166, 16, v207
	v_and_b32_e32 v167, 0xffff0000, v207
	v_pk_mul_f32 v[166:167], v[168:169], v[166:167]
	v_pk_mul_f32 v[122:123], v[122:123], v[166:167]
	v_lshlrev_b32_e32 v168, 16, v212
	v_and_b32_e32 v169, 0xffff0000, v212
	v_max_f32_e32 v168, 0xda24260, v168
	v_max_f32_e32 v169, 0xda24260, v169
	v_rcp_f32_e32 v168, v168
	v_rcp_f32_e32 v169, v169
	v_lshlrev_b32_e32 v166, 16, v208
	v_and_b32_e32 v167, 0xffff0000, v208
	v_pk_mul_f32 v[166:167], v[168:169], v[166:167]
	v_pk_mul_f32 v[116:117], v[116:117], v[166:167]
	v_lshlrev_b32_e32 v168, 16, v213
	v_and_b32_e32 v169, 0xffff0000, v213
	v_max_f32_e32 v168, 0xda24260, v168
	v_max_f32_e32 v169, 0xda24260, v169
	v_rcp_f32_e32 v168, v168
	v_rcp_f32_e32 v169, v169
	v_lshlrev_b32_e32 v166, 16, v209
	v_and_b32_e32 v167, 0xffff0000, v209
	v_pk_mul_f32 v[166:167], v[168:169], v[166:167]
	v_pk_mul_f32 v[118:119], v[118:119], v[166:167]
	global_load_dwordx4 v[206:209], v[160:161], off
	global_load_dwordx4 v[210:213], v[150:151], off
	s_waitcnt vmcnt(14)
	v_lshlrev_b32_e32 v168, 16, v218
	v_and_b32_e32 v169, 0xffff0000, v218
	v_max_f32_e32 v168, 0xda24260, v168
	v_max_f32_e32 v169, 0xda24260, v169
	v_rcp_f32_e32 v168, v168
	v_rcp_f32_e32 v169, v169
	v_lshlrev_b32_e32 v166, 16, v214
	v_and_b32_e32 v167, 0xffff0000, v214
	v_pk_mul_f32 v[166:167], v[168:169], v[166:167]
	v_pk_mul_f32 v[88:89], v[88:89], v[166:167]
	v_lshlrev_b32_e32 v168, 16, v219
	v_and_b32_e32 v169, 0xffff0000, v219
	v_max_f32_e32 v168, 0xda24260, v168
	v_max_f32_e32 v169, 0xda24260, v169
	v_rcp_f32_e32 v168, v168
	v_rcp_f32_e32 v169, v169
	v_lshlrev_b32_e32 v166, 16, v215
	v_and_b32_e32 v167, 0xffff0000, v215
	v_pk_mul_f32 v[166:167], v[168:169], v[166:167]
	v_pk_mul_f32 v[90:91], v[90:91], v[166:167]
	v_lshlrev_b32_e32 v168, 16, v220
	v_and_b32_e32 v169, 0xffff0000, v220
	v_max_f32_e32 v168, 0xda24260, v168
	v_max_f32_e32 v169, 0xda24260, v169
	v_rcp_f32_e32 v168, v168
	v_rcp_f32_e32 v169, v169
	v_lshlrev_b32_e32 v166, 16, v216
	v_and_b32_e32 v167, 0xffff0000, v216
	v_pk_mul_f32 v[166:167], v[168:169], v[166:167]
	v_pk_mul_f32 v[84:85], v[84:85], v[166:167]
	v_lshlrev_b32_e32 v168, 16, v221
	v_and_b32_e32 v169, 0xffff0000, v221
	v_max_f32_e32 v168, 0xda24260, v168
	v_max_f32_e32 v169, 0xda24260, v169
	v_rcp_f32_e32 v168, v168
	v_rcp_f32_e32 v169, v169
	v_lshlrev_b32_e32 v166, 16, v217
	v_and_b32_e32 v167, 0xffff0000, v217
	v_pk_mul_f32 v[166:167], v[168:169], v[166:167]
	v_pk_mul_f32 v[86:87], v[86:87], v[166:167]
	global_load_dwordx4 v[214:217], v[160:161], off offset:256
	global_load_dwordx4 v[218:221], v[150:151], off offset:256
	v_lshl_add_u64 v[160:161], v[160:161], 0, s[28:29]
	v_lshl_add_u64 v[150:151], v[150:151], 0, s[28:29]
	s_waitcnt vmcnt(14)
; __device__ __forceinline__ float lo16(unsigned u) { return __uint_as_float(u << 16); }
; __device__ __forceinline__ float hi16(unsigned u) { return __uint_as_float(u & 0xffff0000u); }
;   __device__ __forceinline__ bool operator()(f32x4 (&acc)[2][2][4][2], const Unit& u, int wr, int wc, int fr, int fq) const {
;     ...
;       for (int m = 0; m < 4; ++m) { const size_t row = (size_t)(row0 + ai * HALF + m * 16);
; #pragma unroll
;         for (int bj = 0; bj < 2; ++bj) {
;           const bf16_t* sp = pg + row * 8192 + (size_t)j * 2048 + col0 + bj * HALF;
;           const u32x4 sc = *(const u32x4*)sp;
;           float f[8] = {lo16(sc.x), hi16(sc.x), lo16(sc.y), hi16(sc.y), lo16(sc.z), hi16(sc.z), lo16(sc.w), hi16(sc.w)};
;           if (j < 3) { const u32x4 sn = *(const u32x4*)(sp + 2048);
;             float g[8] = {lo16(sn.x), hi16(sn.x), lo16(sn.y), hi16(sn.y), lo16(sn.z), hi16(sn.z), lo16(sn.w), hi16(sn.w)};
; #pragma unroll
;             for (int e = 0; e < 8; ++e) f[e] = f[e] * __builtin_amdgcn_rcpf(fmaxf(g[e], 1e-30f)); }
;           f32x4 v0 = acc[ai][bj][m][0], v1 = acc[ai][bj][m][1];
; #pragma unroll
;           for (int e = 0; e < 4; ++e) { v0[e] *= f[e]; v1[e] *= f[4 + e]; }
;           acc[ai][bj][m][0] = v0; acc[ai][bj][m][1] = v1;
	v_lshlrev_b32_e32 v168, 16, v226
	v_and_b32_e32 v169, 0xffff0000, v226
	v_max_f32_e32 v168, 0xda24260, v168
	v_max_f32_e32 v169, 0xda24260, v169
	v_rcp_f32_e32 v168, v168
	v_rcp_f32_e32 v169, v169
	v_lshlrev_b32_e32 v166, 16, v222
	v_and_b32_e32 v167, 0xffff0000, v222
	v_pk_mul_f32 v[166:167], v[168:169], v[166:167]
	v_pk_mul_f32 v[112:113], v[112:113], v[166:167]
	v_lshlrev_b32_e32 v168, 16, v227
	v_and_b32_e32 v169, 0xffff0000, v227
	v_max_f32_e32 v168, 0xda24260, v168
	v_max_f32_e32 v169, 0xda24260, v169
	v_rcp_f32_e32 v168, v168
	v_rcp_f32_e32 v169, v169
	v_lshlrev_b32_e32 v166, 16, v223
	v_and_b32_e32 v167, 0xffff0000, v223
	v_pk_mul_f32 v[166:167], v[168:169], v[166:167]
	v_pk_mul_f32 v[114:115], v[114:115], v[166:167]
	v_lshlrev_b32_e32 v168, 16, v228
	v_and_b32_e32 v169, 0xffff0000, v228
	v_max_f32_e32 v168, 0xda24260, v168
	v_max_f32_e32 v169, 0xda24260, v169
	v_rcp_f32_e32 v168, v168
	v_rcp_f32_e32 v169, v169
	v_lshlrev_b32_e32 v166, 16, v224
	v_and_b32_e32 v167, 0xffff0000, v224
	v_pk_mul_f32 v[166:167], v[168:169], v[166:167]
	v_pk_mul_f32 v[108:109], v[108:109], v[166:167]
	v_lshlrev_b32_e32 v168, 16, v229
	v_and_b32_e32 v169, 0xffff0000, v229
	v_max_f32_e32 v168, 0xda24260, v168
	v_max_f32_e32 v169, 0xda24260, v169
	v_rcp_f32_e32 v168, v168
	v_rcp_f32_e32 v169, v169
	v_lshlrev_b32_e32 v166, 16, v225
	v_and_b32_e32 v167, 0xffff0000, v225
	v_pk_mul_f32 v[166:167], v[168:169], v[166:167]
	v_pk_mul_f32 v[110:111], v[110:111], v[166:167]
	global_load_dwordx4 v[222:225], v[160:161], off
	global_load_dwordx4 v[226:229], v[150:151], off
	s_waitcnt vmcnt(14)
	v_lshlrev_b32_e32 v168, 16, v234
	v_and_b32_e32 v169, 0xffff0000, v234
	v_max_f32_e32 v168, 0xda24260, v168
	v_max_f32_e32 v169, 0xda24260, v169
	v_rcp_f32_e32 v168, v168
	v_rcp_f32_e32 v169, v169
	v_lshlrev_b32_e32 v166, 16, v230
	v_and_b32_e32 v167, 0xffff0000, v230
	v_pk_mul_f32 v[166:167], v[168:169], v[166:167]
	v_pk_mul_f32 v[80:81], v[80:81], v[166:167]
	v_lshlrev_b32_e32 v168, 16, v235
	v_and_b32_e32 v169, 0xffff0000, v235
	v_max_f32_e32 v168, 0xda24260, v168
	v_max_f32_e32 v169, 0xda24260, v169
	v_rcp_f32_e32 v168, v168
	v_rcp_f32_e32 v169, v169
	v_lshlrev_b32_e32 v166, 16, v231
	v_and_b32_e32 v167, 0xffff0000, v231
	v_pk_mul_f32 v[166:167], v[168:169], v[166:167]
	v_pk_mul_f32 v[82:83], v[82:83], v[166:167]
	v_lshlrev_b32_e32 v168, 16, v236
	v_and_b32_e32 v169, 0xffff0000, v236
	v_max_f32_e32 v168, 0xda24260, v168
	v_max_f32_e32 v169, 0xda24260, v169
	v_rcp_f32_e32 v168, v168
	v_rcp_f32_e32 v169, v169
	v_lshlrev_b32_e32 v166, 16, v232
	v_and_b32_e32 v167, 0xffff0000, v232
	v_pk_mul_f32 v[166:167], v[168:169], v[166:167]
	v_pk_mul_f32 v[76:77], v[76:77], v[166:167]
	v_lshlrev_b32_e32 v168, 16, v237
	v_and_b32_e32 v169, 0xffff0000, v237
	v_max_f32_e32 v168, 0xda24260, v168
	v_max_f32_e32 v169, 0xda24260, v169
	v_rcp_f32_e32 v168, v168
	v_rcp_f32_e32 v169, v169
	v_lshlrev_b32_e32 v166, 16, v233
	v_and_b32_e32 v167, 0xffff0000, v233
	v_pk_mul_f32 v[166:167], v[168:169], v[166:167]
	v_pk_mul_f32 v[78:79], v[78:79], v[166:167]
	global_load_dwordx4 v[230:233], v[160:161], off offset:256
	global_load_dwordx4 v[234:237], v[150:151], off offset:256
	v_lshl_add_u64 v[160:161], v[160:161], 0, s[28:29]
	v_lshl_add_u64 v[150:151], v[150:151], 0, s[28:29]
	s_waitcnt vmcnt(14)
	v_lshlrev_b32_e32 v168, 16, v142
	v_and_b32_e32 v169, 0xffff0000, v142
	v_max_f32_e32 v168, 0xda24260, v168
	v_max_f32_e32 v169, 0xda24260, v169
	v_rcp_f32_e32 v168, v168
	v_rcp_f32_e32 v169, v169
	v_lshlrev_b32_e32 v166, 16, v238
	v_and_b32_e32 v167, 0xffff0000, v238
	v_pk_mul_f32 v[166:167], v[168:169], v[166:167]
	v_pk_mul_f32 v[104:105], v[104:105], v[166:167]
	v_lshlrev_b32_e32 v168, 16, v143
	v_and_b32_e32 v169, 0xffff0000, v143
	v_max_f32_e32 v168, 0xda24260, v168
	v_max_f32_e32 v169, 0xda24260, v169
	v_rcp_f32_e32 v168, v168
	v_rcp_f32_e32 v169, v169
	v_lshlrev_b32_e32 v166, 16, v239
	v_and_b32_e32 v167, 0xffff0000, v239
	v_pk_mul_f32 v[166:167], v[168:169], v[166:167]
	v_pk_mul_f32 v[106:107], v[106:107], v[166:167]
	v_lshlrev_b32_e32 v168, 16, v144
	v_and_b32_e32 v169, 0xffff0000, v144
	v_max_f32_e32 v168, 0xda24260, v168
	v_max_f32_e32 v169, 0xda24260, v169
	v_rcp_f32_e32 v168, v168
	v_rcp_f32_e32 v169, v169
	v_lshlrev_b32_e32 v166, 16, v240
	v_and_b32_e32 v167, 0xffff0000, v240
	v_pk_mul_f32 v[166:167], v[168:169], v[166:167]
	v_pk_mul_f32 v[100:101], v[100:101], v[166:167]
	v_lshlrev_b32_e32 v168, 16, v145
	v_and_b32_e32 v169, 0xffff0000, v145
	v_max_f32_e32 v168, 0xda24260, v168
	v_max_f32_e32 v169, 0xda24260, v169
	v_rcp_f32_e32 v168, v168
	v_rcp_f32_e32 v169, v169
	v_lshlrev_b32_e32 v166, 16, v241
	v_and_b32_e32 v167, 0xffff0000, v241
	v_pk_mul_f32 v[166:167], v[168:169], v[166:167]
	v_pk_mul_f32 v[102:103], v[102:103], v[166:167]
	global_load_dwordx4 v[238:241], v[160:161], off
	global_load_dwordx4 v[142:145], v[150:151], off
	s_waitcnt vmcnt(14)
; __device__ __forceinline__ float lo16(unsigned u) { return __uint_as_float(u << 16); }
; __device__ __forceinline__ float hi16(unsigned u) { return __uint_as_float(u & 0xffff0000u); }
;   __device__ __forceinline__ bool operator()(f32x4 (&acc)[2][2][4][2], const Unit& u, int wr, int wc, int fr, int fq) const {
;     ...
;       for (int m = 0; m < 4; ++m) { const size_t row = (size_t)(row0 + ai * HALF + m * 16);
; #pragma unroll
;         for (int bj = 0; bj < 2; ++bj) {
;           const bf16_t* sp = pg + row * 8192 + (size_t)j * 2048 + col0 + bj * HALF;
;           const u32x4 sc = *(const u32x4*)sp;
;           float f[8] = {lo16(sc.x), hi16(sc.x), lo16(sc.y), hi16(sc.y), lo16(sc.z), hi16(sc.z), lo16(sc.w), hi16(sc.w)};
;           if (j < 3) { const u32x4 sn = *(const u32x4*)(sp + 2048);
;             float g[8] = {lo16(sn.x), hi16(sn.x), lo16(sn.y), hi16(sn.y), lo16(sn.z), hi16(sn.z), lo16(sn.w), hi16(sn.w)};
; #pragma unroll
;             for (int e = 0; e < 8; ++e) f[e] = f[e] * __builtin_amdgcn_rcpf(fmaxf(g[e], 1e-30f)); }
;           f32x4 v0 = acc[ai][bj][m][0], v1 = acc[ai][bj][m][1];
; #pragma unroll
;           for (int e = 0; e < 4; ++e) { v0[e] *= f[e]; v1[e] *= f[4 + e]; }
;           acc[ai][bj][m][0] = v0; acc[ai][bj][m][1] = v1;
	v_lshlrev_b32_e32 v168, 16, v156
	v_and_b32_e32 v169, 0xffff0000, v156
	v_max_f32_e32 v168, 0xda24260, v168
	v_max_f32_e32 v169, 0xda24260, v169
	v_rcp_f32_e32 v168, v168
	v_rcp_f32_e32 v169, v169
	v_lshlrev_b32_e32 v166, 16, v146
	v_and_b32_e32 v167, 0xffff0000, v146
	v_pk_mul_f32 v[166:167], v[168:169], v[166:167]
	v_pk_mul_f32 v[72:73], v[72:73], v[166:167]
	v_lshlrev_b32_e32 v168, 16, v157
	v_and_b32_e32 v169, 0xffff0000, v157
	v_max_f32_e32 v168, 0xda24260, v168
	v_max_f32_e32 v169, 0xda24260, v169
	v_rcp_f32_e32 v168, v168
	v_rcp_f32_e32 v169, v169
	v_lshlrev_b32_e32 v166, 16, v147
	v_and_b32_e32 v167, 0xffff0000, v147
	v_pk_mul_f32 v[166:167], v[168:169], v[166:167]
	v_pk_mul_f32 v[74:75], v[74:75], v[166:167]
	v_lshlrev_b32_e32 v168, 16, v158
	v_and_b32_e32 v169, 0xffff0000, v158
	v_max_f32_e32 v168, 0xda24260, v168
	v_max_f32_e32 v169, 0xda24260, v169
	v_rcp_f32_e32 v168, v168
	v_rcp_f32_e32 v169, v169
	v_lshlrev_b32_e32 v166, 16, v148
	v_and_b32_e32 v167, 0xffff0000, v148
	v_pk_mul_f32 v[166:167], v[168:169], v[166:167]
	v_pk_mul_f32 v[68:69], v[68:69], v[166:167]
	v_lshlrev_b32_e32 v168, 16, v159
	v_and_b32_e32 v169, 0xffff0000, v159
	v_max_f32_e32 v168, 0xda24260, v168
	v_max_f32_e32 v169, 0xda24260, v169
	v_rcp_f32_e32 v168, v168
	v_rcp_f32_e32 v169, v169
	v_lshlrev_b32_e32 v166, 16, v149
	v_and_b32_e32 v167, 0xffff0000, v149
	v_pk_mul_f32 v[166:167], v[168:169], v[166:167]
	v_pk_mul_f32 v[70:71], v[70:71], v[166:167]
	global_load_dwordx4 v[146:149], v[160:161], off offset:256
	global_load_dwordx4 v[156:159], v[150:151], off offset:256
	s_waitcnt vmcnt(14)
	v_lshlrev_b32_e32 v168, 16, v194
	v_and_b32_e32 v169, 0xffff0000, v194
	v_max_f32_e32 v168, 0xda24260, v168
	v_max_f32_e32 v169, 0xda24260, v169
	v_rcp_f32_e32 v168, v168
	v_rcp_f32_e32 v169, v169
	v_lshlrev_b32_e32 v166, 16, v190
	v_and_b32_e32 v167, 0xffff0000, v190
	v_pk_mul_f32 v[166:167], v[168:169], v[166:167]
	v_pk_mul_f32 v[64:65], v[64:65], v[166:167]
	v_lshlrev_b32_e32 v168, 16, v195
	v_and_b32_e32 v169, 0xffff0000, v195
	v_max_f32_e32 v168, 0xda24260, v168
	v_max_f32_e32 v169, 0xda24260, v169
	v_rcp_f32_e32 v168, v168
	v_rcp_f32_e32 v169, v169
	v_lshlrev_b32_e32 v166, 16, v191
	v_and_b32_e32 v167, 0xffff0000, v191
	v_pk_mul_f32 v[166:167], v[168:169], v[166:167]
	v_pk_mul_f32 v[66:67], v[66:67], v[166:167]
	v_lshlrev_b32_e32 v168, 16, v196
	v_and_b32_e32 v169, 0xffff0000, v196
	v_max_f32_e32 v168, 0xda24260, v168
	v_max_f32_e32 v169, 0xda24260, v169
	v_rcp_f32_e32 v168, v168
	v_rcp_f32_e32 v169, v169
	v_lshlrev_b32_e32 v166, 16, v192
	v_and_b32_e32 v167, 0xffff0000, v192
	v_pk_mul_f32 v[166:167], v[168:169], v[166:167]
	v_pk_mul_f32 v[60:61], v[60:61], v[166:167]
	v_lshlrev_b32_e32 v168, 16, v197
	v_and_b32_e32 v169, 0xffff0000, v197
	v_max_f32_e32 v168, 0xda24260, v168
	v_max_f32_e32 v169, 0xda24260, v169
	v_rcp_f32_e32 v168, v168
	v_rcp_f32_e32 v169, v169
	v_lshlrev_b32_e32 v166, 16, v193
	v_and_b32_e32 v167, 0xffff0000, v193
	v_pk_mul_f32 v[166:167], v[168:169], v[166:167]
	v_pk_mul_f32 v[62:63], v[62:63], v[166:167]
	s_waitcnt vmcnt(12)
	v_lshlrev_b32_e32 v168, 16, v202
	v_and_b32_e32 v169, 0xffff0000, v202
	v_max_f32_e32 v168, 0xda24260, v168
	v_max_f32_e32 v169, 0xda24260, v169
	v_rcp_f32_e32 v168, v168
	v_rcp_f32_e32 v169, v169
	v_lshlrev_b32_e32 v166, 16, v198
	v_and_b32_e32 v167, 0xffff0000, v198
	v_pk_mul_f32 v[166:167], v[168:169], v[166:167]
	v_pk_mul_f32 v[32:33], v[32:33], v[166:167]
	v_lshlrev_b32_e32 v168, 16, v203
	v_and_b32_e32 v169, 0xffff0000, v203
	v_max_f32_e32 v168, 0xda24260, v168
	v_max_f32_e32 v169, 0xda24260, v169
	v_rcp_f32_e32 v168, v168
	v_rcp_f32_e32 v169, v169
	v_lshlrev_b32_e32 v166, 16, v199
	v_and_b32_e32 v167, 0xffff0000, v199
	v_pk_mul_f32 v[166:167], v[168:169], v[166:167]
	v_pk_mul_f32 v[34:35], v[34:35], v[166:167]
	v_lshlrev_b32_e32 v168, 16, v204
	v_and_b32_e32 v169, 0xffff0000, v204
	v_max_f32_e32 v168, 0xda24260, v168
	v_max_f32_e32 v169, 0xda24260, v169
	v_rcp_f32_e32 v168, v168
	v_rcp_f32_e32 v169, v169
	v_lshlrev_b32_e32 v166, 16, v200
	v_and_b32_e32 v167, 0xffff0000, v200
	v_pk_mul_f32 v[166:167], v[168:169], v[166:167]
	v_pk_mul_f32 v[28:29], v[28:29], v[166:167]
	v_lshlrev_b32_e32 v168, 16, v205
	v_and_b32_e32 v169, 0xffff0000, v205
	v_max_f32_e32 v168, 0xda24260, v168
	v_max_f32_e32 v169, 0xda24260, v169
	v_rcp_f32_e32 v168, v168
	v_rcp_f32_e32 v169, v169
	v_lshlrev_b32_e32 v166, 16, v201
	v_and_b32_e32 v167, 0xffff0000, v201
	v_pk_mul_f32 v[166:167], v[168:169], v[166:167]
	v_pk_mul_f32 v[30:31], v[30:31], v[166:167]
	s_waitcnt vmcnt(10)
	v_lshlrev_b32_e32 v168, 16, v210
	v_and_b32_e32 v169, 0xffff0000, v210
	v_max_f32_e32 v168, 0xda24260, v168
	v_max_f32_e32 v169, 0xda24260, v169
	v_rcp_f32_e32 v168, v168
	v_rcp_f32_e32 v169, v169
	v_lshlrev_b32_e32 v166, 16, v206
	v_and_b32_e32 v167, 0xffff0000, v206
	v_pk_mul_f32 v[166:167], v[168:169], v[166:167]
	v_pk_mul_f32 v[56:57], v[56:57], v[166:167]
	v_lshlrev_b32_e32 v168, 16, v211
	v_and_b32_e32 v169, 0xffff0000, v211
	v_max_f32_e32 v168, 0xda24260, v168
	v_max_f32_e32 v169, 0xda24260, v169
	v_rcp_f32_e32 v168, v168
	v_rcp_f32_e32 v169, v169
	v_lshlrev_b32_e32 v166, 16, v207
	v_and_b32_e32 v167, 0xffff0000, v207
	v_pk_mul_f32 v[166:167], v[168:169], v[166:167]
	v_pk_mul_f32 v[58:59], v[58:59], v[166:167]
	v_lshlrev_b32_e32 v168, 16, v212
	v_and_b32_e32 v169, 0xffff0000, v212
	v_max_f32_e32 v168, 0xda24260, v168
	v_max_f32_e32 v169, 0xda24260, v169
	v_rcp_f32_e32 v168, v168
	v_rcp_f32_e32 v169, v169
	v_lshlrev_b32_e32 v166, 16, v208
	v_and_b32_e32 v167, 0xffff0000, v208
	v_pk_mul_f32 v[166:167], v[168:169], v[166:167]
	v_pk_mul_f32 v[52:53], v[52:53], v[166:167]
	v_lshlrev_b32_e32 v168, 16, v213
	v_and_b32_e32 v169, 0xffff0000, v213
	v_max_f32_e32 v168, 0xda24260, v168
	v_max_f32_e32 v169, 0xda24260, v169
	v_rcp_f32_e32 v168, v168
	v_rcp_f32_e32 v169, v169
	v_lshlrev_b32_e32 v166, 16, v209
	v_and_b32_e32 v167, 0xffff0000, v209
	v_pk_mul_f32 v[166:167], v[168:169], v[166:167]
	v_pk_mul_f32 v[54:55], v[54:55], v[166:167]
	s_waitcnt vmcnt(8)
; __device__ __forceinline__ float lo16(unsigned u) { return __uint_as_float(u << 16); }
; __device__ __forceinline__ float hi16(unsigned u) { return __uint_as_float(u & 0xffff0000u); }
;   __device__ __forceinline__ bool operator()(f32x4 (&acc)[2][2][4][2], const Unit& u, int wr, int wc, int fr, int fq) const {
;     ...
;       for (int m = 0; m < 4; ++m) { const size_t row = (size_t)(row0 + ai * HALF + m * 16);
; #pragma unroll
;         for (int bj = 0; bj < 2; ++bj) {
;           const bf16_t* sp = pg + row * 8192 + (size_t)j * 2048 + col0 + bj * HALF;
;           const u32x4 sc = *(const u32x4*)sp;
;           float f[8] = {lo16(sc.x), hi16(sc.x), lo16(sc.y), hi16(sc.y), lo16(sc.z), hi16(sc.z), lo16(sc.w), hi16(sc.w)};
;           if (j < 3) { const u32x4 sn = *(const u32x4*)(sp + 2048);
;             float g[8] = {lo16(sn.x), hi16(sn.x), lo16(sn.y), hi16(sn.y), lo16(sn.z), hi16(sn.z), lo16(sn.w), hi16(sn.w)};
; #pragma unroll
;             for (int e = 0; e < 8; ++e) f[e] = f[e] * __builtin_amdgcn_rcpf(fmaxf(g[e], 1e-30f)); }
;           f32x4 v0 = acc[ai][bj][m][0], v1 = acc[ai][bj][m][1];
; #pragma unroll
;           for (int e = 0; e < 4; ++e) { v0[e] *= f[e]; v1[e] *= f[4 + e]; }
;           acc[ai][bj][m][0] = v0; acc[ai][bj][m][1] = v1;
	v_lshlrev_b32_e32 v168, 16, v218
	v_and_b32_e32 v169, 0xffff0000, v218
	v_max_f32_e32 v168, 0xda24260, v168
	v_max_f32_e32 v169, 0xda24260, v169
	v_rcp_f32_e32 v168, v168
	v_rcp_f32_e32 v169, v169
	v_lshlrev_b32_e32 v166, 16, v214
	v_and_b32_e32 v167, 0xffff0000, v214
	v_pk_mul_f32 v[166:167], v[168:169], v[166:167]
	v_pk_mul_f32 v[24:25], v[24:25], v[166:167]
	v_lshlrev_b32_e32 v168, 16, v219
	v_and_b32_e32 v169, 0xffff0000, v219
	v_max_f32_e32 v168, 0xda24260, v168
	v_max_f32_e32 v169, 0xda24260, v169
	v_rcp_f32_e32 v168, v168
	v_rcp_f32_e32 v169, v169
	v_lshlrev_b32_e32 v166, 16, v215
	v_and_b32_e32 v167, 0xffff0000, v215
	v_pk_mul_f32 v[166:167], v[168:169], v[166:167]
	v_pk_mul_f32 v[26:27], v[26:27], v[166:167]
	v_lshlrev_b32_e32 v168, 16, v220
	v_and_b32_e32 v169, 0xffff0000, v220
	v_max_f32_e32 v168, 0xda24260, v168
	v_max_f32_e32 v169, 0xda24260, v169
	v_rcp_f32_e32 v168, v168
	v_rcp_f32_e32 v169, v169
	v_lshlrev_b32_e32 v166, 16, v216
	v_and_b32_e32 v167, 0xffff0000, v216
	v_pk_mul_f32 v[166:167], v[168:169], v[166:167]
	v_pk_mul_f32 v[20:21], v[20:21], v[166:167]
	v_lshlrev_b32_e32 v168, 16, v221
	v_and_b32_e32 v169, 0xffff0000, v221
	v_max_f32_e32 v168, 0xda24260, v168
	v_max_f32_e32 v169, 0xda24260, v169
	v_rcp_f32_e32 v168, v168
	v_rcp_f32_e32 v169, v169
	v_lshlrev_b32_e32 v166, 16, v217
	v_and_b32_e32 v167, 0xffff0000, v217
	v_pk_mul_f32 v[166:167], v[168:169], v[166:167]
	v_pk_mul_f32 v[22:23], v[22:23], v[166:167]
	s_waitcnt vmcnt(6)
	v_lshlrev_b32_e32 v168, 16, v226
	v_and_b32_e32 v169, 0xffff0000, v226
	v_max_f32_e32 v168, 0xda24260, v168
	v_max_f32_e32 v169, 0xda24260, v169
	v_rcp_f32_e32 v168, v168
	v_rcp_f32_e32 v169, v169
	v_lshlrev_b32_e32 v166, 16, v222
	v_and_b32_e32 v167, 0xffff0000, v222
	v_pk_mul_f32 v[166:167], v[168:169], v[166:167]
	v_pk_mul_f32 v[48:49], v[48:49], v[166:167]
	v_lshlrev_b32_e32 v168, 16, v227
	v_and_b32_e32 v169, 0xffff0000, v227
	v_max_f32_e32 v168, 0xda24260, v168
	v_max_f32_e32 v169, 0xda24260, v169
	v_rcp_f32_e32 v168, v168
	v_rcp_f32_e32 v169, v169
	v_lshlrev_b32_e32 v166, 16, v223
	v_and_b32_e32 v167, 0xffff0000, v223
	v_pk_mul_f32 v[166:167], v[168:169], v[166:167]
	v_pk_mul_f32 v[50:51], v[50:51], v[166:167]
	v_lshlrev_b32_e32 v168, 16, v228
	v_and_b32_e32 v169, 0xffff0000, v228
	v_max_f32_e32 v168, 0xda24260, v168
	v_max_f32_e32 v169, 0xda24260, v169
	v_rcp_f32_e32 v168, v168
	v_rcp_f32_e32 v169, v169
	v_lshlrev_b32_e32 v166, 16, v224
	v_and_b32_e32 v167, 0xffff0000, v224
	v_pk_mul_f32 v[166:167], v[168:169], v[166:167]
	v_pk_mul_f32 v[44:45], v[44:45], v[166:167]
	v_lshlrev_b32_e32 v168, 16, v229
	v_and_b32_e32 v169, 0xffff0000, v229
	v_max_f32_e32 v168, 0xda24260, v168
	v_max_f32_e32 v169, 0xda24260, v169
	v_rcp_f32_e32 v168, v168
	v_rcp_f32_e32 v169, v169
	v_lshlrev_b32_e32 v166, 16, v225
	v_and_b32_e32 v167, 0xffff0000, v225
	v_pk_mul_f32 v[166:167], v[168:169], v[166:167]
	v_pk_mul_f32 v[46:47], v[46:47], v[166:167]
	s_waitcnt vmcnt(4)
; __device__ __forceinline__ float lo16(unsigned u) { return __uint_as_float(u << 16); }
; __device__ __forceinline__ float hi16(unsigned u) { return __uint_as_float(u & 0xffff0000u); }
;   __device__ __forceinline__ bool operator()(f32x4 (&acc)[2][2][4][2], const Unit& u, int wr, int wc, int fr, int fq) const {
;     ...
;       for (int m = 0; m < 4; ++m) { const size_t row = (size_t)(row0 + ai * HALF + m * 16);
; #pragma unroll
;         for (int bj = 0; bj < 2; ++bj) {
;           const bf16_t* sp = pg + row * 8192 + (size_t)j * 2048 + col0 + bj * HALF;
;           const u32x4 sc = *(const u32x4*)sp;
;           float f[8] = {lo16(sc.x), hi16(sc.x), lo16(sc.y), hi16(sc.y), lo16(sc.z), hi16(sc.z), lo16(sc.w), hi16(sc.w)};
;           if (j < 3) { const u32x4 sn = *(const u32x4*)(sp + 2048);
;             float g[8] = {lo16(sn.x), hi16(sn.x), lo16(sn.y), hi16(sn.y), lo16(sn.z), hi16(sn.z), lo16(sn.w), hi16(sn.w)};
; #pragma unroll
;             for (int e = 0; e < 8; ++e) f[e] = f[e] * __builtin_amdgcn_rcpf(fmaxf(g[e], 1e-30f)); }
;           f32x4 v0 = acc[ai][bj][m][0], v1 = acc[ai][bj][m][1];
; #pragma unroll
;           for (int e = 0; e < 4; ++e) { v0[e] *= f[e]; v1[e] *= f[4 + e]; }
;           acc[ai][bj][m][0] = v0; acc[ai][bj][m][1] = v1;
	v_lshlrev_b32_e32 v168, 16, v234
	v_and_b32_e32 v169, 0xffff0000, v234
	v_max_f32_e32 v168, 0xda24260, v168
	v_max_f32_e32 v169, 0xda24260, v169
	v_rcp_f32_e32 v168, v168
	v_rcp_f32_e32 v169, v169
	v_lshlrev_b32_e32 v166, 16, v230
	v_and_b32_e32 v167, 0xffff0000, v230
	v_pk_mul_f32 v[166:167], v[168:169], v[166:167]
	v_pk_mul_f32 v[16:17], v[16:17], v[166:167]
	v_lshlrev_b32_e32 v168, 16, v235
	v_and_b32_e32 v169, 0xffff0000, v235
	v_max_f32_e32 v168, 0xda24260, v168
	v_max_f32_e32 v169, 0xda24260, v169
	v_rcp_f32_e32 v168, v168
	v_rcp_f32_e32 v169, v169
	v_lshlrev_b32_e32 v166, 16, v231
	v_and_b32_e32 v167, 0xffff0000, v231
	v_pk_mul_f32 v[166:167], v[168:169], v[166:167]
	v_pk_mul_f32 v[18:19], v[18:19], v[166:167]
	v_lshlrev_b32_e32 v168, 16, v236
	v_and_b32_e32 v169, 0xffff0000, v236
	v_max_f32_e32 v168, 0xda24260, v168
	v_max_f32_e32 v169, 0xda24260, v169
	v_rcp_f32_e32 v168, v168
	v_rcp_f32_e32 v169, v169
	v_lshlrev_b32_e32 v166, 16, v232
	v_and_b32_e32 v167, 0xffff0000, v232
	v_pk_mul_f32 v[166:167], v[168:169], v[166:167]
	v_pk_mul_f32 v[12:13], v[12:13], v[166:167]
	v_lshlrev_b32_e32 v168, 16, v237
	v_and_b32_e32 v169, 0xffff0000, v237
	v_max_f32_e32 v168, 0xda24260, v168
	v_max_f32_e32 v169, 0xda24260, v169
	v_rcp_f32_e32 v168, v168
	v_rcp_f32_e32 v169, v169
	v_lshlrev_b32_e32 v166, 16, v233
	v_and_b32_e32 v167, 0xffff0000, v233
	v_pk_mul_f32 v[166:167], v[168:169], v[166:167]
	v_pk_mul_f32 v[14:15], v[14:15], v[166:167]
	s_waitcnt vmcnt(2)
	v_lshlrev_b32_e32 v168, 16, v142
	v_and_b32_e32 v169, 0xffff0000, v142
	v_max_f32_e32 v168, 0xda24260, v168
	v_max_f32_e32 v169, 0xda24260, v169
	v_rcp_f32_e32 v168, v168
	v_rcp_f32_e32 v169, v169
	v_lshlrev_b32_e32 v166, 16, v238
	v_and_b32_e32 v167, 0xffff0000, v238
	v_pk_mul_f32 v[166:167], v[168:169], v[166:167]
	v_pk_mul_f32 v[40:41], v[40:41], v[166:167]
	v_lshlrev_b32_e32 v168, 16, v143
	v_and_b32_e32 v169, 0xffff0000, v143
	v_max_f32_e32 v168, 0xda24260, v168
	v_max_f32_e32 v169, 0xda24260, v169
	v_rcp_f32_e32 v168, v168
	v_rcp_f32_e32 v169, v169
	v_lshlrev_b32_e32 v166, 16, v239
	v_and_b32_e32 v167, 0xffff0000, v239
	v_pk_mul_f32 v[166:167], v[168:169], v[166:167]
	v_pk_mul_f32 v[42:43], v[42:43], v[166:167]
	v_lshlrev_b32_e32 v168, 16, v144
	v_and_b32_e32 v169, 0xffff0000, v144
	v_max_f32_e32 v168, 0xda24260, v168
	v_max_f32_e32 v169, 0xda24260, v169
	v_rcp_f32_e32 v168, v168
	v_rcp_f32_e32 v169, v169
	v_lshlrev_b32_e32 v166, 16, v240
	v_and_b32_e32 v167, 0xffff0000, v240
	v_pk_mul_f32 v[166:167], v[168:169], v[166:167]
	v_pk_mul_f32 v[36:37], v[36:37], v[166:167]
	v_lshlrev_b32_e32 v168, 16, v145
	v_and_b32_e32 v169, 0xffff0000, v145
	v_max_f32_e32 v168, 0xda24260, v168
	v_max_f32_e32 v169, 0xda24260, v169
	v_rcp_f32_e32 v168, v168
	v_rcp_f32_e32 v169, v169
	v_lshlrev_b32_e32 v166, 16, v241
	v_and_b32_e32 v167, 0xffff0000, v241
	v_pk_mul_f32 v[166:167], v[168:169], v[166:167]
	v_pk_mul_f32 v[38:39], v[38:39], v[166:167]
	s_waitcnt vmcnt(0)
	v_lshlrev_b32_e32 v168, 16, v156
	v_and_b32_e32 v169, 0xffff0000, v156
	v_max_f32_e32 v168, 0xda24260, v168
	v_max_f32_e32 v169, 0xda24260, v169
	v_rcp_f32_e32 v168, v168
	v_rcp_f32_e32 v169, v169
	v_lshlrev_b32_e32 v166, 16, v146
	v_and_b32_e32 v167, 0xffff0000, v146
	v_pk_mul_f32 v[166:167], v[168:169], v[166:167]
	v_pk_mul_f32 v[8:9], v[8:9], v[166:167]
	v_lshlrev_b32_e32 v168, 16, v157
	v_and_b32_e32 v169, 0xffff0000, v157
	v_max_f32_e32 v168, 0xda24260, v168
	v_max_f32_e32 v169, 0xda24260, v169
	v_rcp_f32_e32 v168, v168
	v_rcp_f32_e32 v169, v169
	v_lshlrev_b32_e32 v166, 16, v147
	v_and_b32_e32 v167, 0xffff0000, v147
	v_pk_mul_f32 v[166:167], v[168:169], v[166:167]
	v_pk_mul_f32 v[10:11], v[10:11], v[166:167]
	v_lshlrev_b32_e32 v168, 16, v158
	v_and_b32_e32 v169, 0xffff0000, v158
	v_max_f32_e32 v168, 0xda24260, v168
	v_max_f32_e32 v169, 0xda24260, v169
	v_rcp_f32_e32 v168, v168
	v_rcp_f32_e32 v169, v169
	v_lshlrev_b32_e32 v166, 16, v148
	v_and_b32_e32 v167, 0xffff0000, v148
	v_pk_mul_f32 v[166:167], v[168:169], v[166:167]
	v_pk_mul_f32 v[4:5], v[4:5], v[166:167]
	v_lshlrev_b32_e32 v168, 16, v159
	v_and_b32_e32 v169, 0xffff0000, v159
	v_max_f32_e32 v168, 0xda24260, v168
	v_max_f32_e32 v169, 0xda24260, v169
	v_rcp_f32_e32 v168, v168
	v_rcp_f32_e32 v169, v169
	v_lshlrev_b32_e32 v166, 16, v149
	v_and_b32_e32 v167, 0xffff0000, v149
	v_pk_mul_f32 v[166:167], v[168:169], v[166:167]
	v_pk_mul_f32 v[6:7], v[6:7], v[166:167]
	s_branch .Lg2e_done

; #define G8_STAGE(bufoff, gbase, voff) do { _Pragma("unroll") for (int _i = 0; _i < 2; ++_i) \
;     __builtin_amdgcn_global_load_lds((const unsigned*)((const char*)(gbase) + (voff)[_i]), (LAS unsigned*)(lds + (bufoff) + ldsw + _i * 8192), 16, 0, 0); } while (0)
; #define G8_LDA(dst, b, h) do { _Pragma("unroll") for (int m = 0; m < 4; ++m) _Pragma("unroll") for (int k = 0; k < 2; ++k) dst[m][k] = *(const LAS bf16x8*)(lds + G8_SA(b, h) + aoff + m * 2048 + k * 1024); } while (0)
; #define G8_LDB(dst, b, h) do { _Pragma("unroll") for (int n = 0; n < 2; ++n) _Pragma("unroll") for (int k = 0; k < 2; ++k) dst[n][k] = *(const LAS bf16x8*)(lds + G8_SB(b, h) + boff + n * 2048 + k * 1024); } while (0)
; #define G8_MMA(ai, bj, At, Bt) do { __builtin_amdgcn_s_setprio(1); _Pragma("unroll") for (int m = 0; m < 4; ++m) _Pragma("unroll") for (int n = 0; n < 2; ++n) _Pragma("unroll") for (int k = 0; k < 2; ++k) \
;     acc[ai][bj][m][n] = __builtin_amdgcn_mfma_f32_16x16x32_bf16(Bt[n][k], At[m][k], acc[ai][bj][m][n], 0, 0, 0); __builtin_amdgcn_s_setprio(0); } while (0)
; #define G8_WAIT_L(n) asm volatile("s_waitcnt lgkmcnt(" #n ")" ::: "memory")
; #define G8_BAR __builtin_amdgcn_s_barrier()
; #define G8_SCHED __builtin_amdgcn_sched_barrier(0)
; template <class Epi, class Sched>
; __device__ __forceinline__ void gemm_phase(const int wv_, LAS unsigned char* lds, const int lda, const int ldb, const int K, const Sched& S, const Epi& E) {
;     ...
;     for (int t = 0; t < nt; t += 2) {
;       const bool last = (t == nt - 2);
;       const char* a1 = cA + (size_t)(t + 1) * kstep;
;       const char* a2 = last ? nA : cA + (size_t)(t + 2) * kstep; const char* b2 = last ? nB : cB + (size_t)(t + 2) * kstep;
;       const char* a3 = a2 + kstep; const char* b3 = b2 + kstep;
;       G8_LDB(B0, 0, 0); G8_SCHED; G8_LDA(At, 0, 0); G8_STAGE(G8_SA(1, 1), a1 + hstepA, voffA);
;       G8_WAIT_L(8); G8_BAR; G8_WAIT_L(0); G8_MMA(0, 0, At, B0); G8_BAR; G8_SCHED;
;     ...
; #pragma unroll
;       for (int a = 0; a < 2; ++a)
; #pragma unroll
;         for (int b = 0; b < 2; ++b)
; #pragma unroll
;           for (int m = 0; m < 4; ++m)
; #pragma unroll
;             for (int n = 0; n < 2; ++n) acc[a][b][m][n] = (f32x4){0.f, 0.f, 0.f, 0.f};
.LBB0_948:
	s_add_u32 s30, s30, 0x80080
	s_addc_u32 s31, s31, 0
	s_add_u32 s11, s34, 0x100
	v_mov_b32_e32 v4, 0
	s_addc_u32 s17, s35, 0
	s_mov_b32 s19, -2
	v_mov_b32_e32 v5, v4
	v_mov_b32_e32 v6, v4
	v_mov_b32_e32 v7, v4
	v_mov_b32_e32 v8, v4
	v_mov_b32_e32 v9, v4
	v_mov_b32_e32 v10, v4
	v_mov_b32_e32 v11, v4
	v_mov_b32_e32 v20, v4
	v_mov_b32_e32 v21, v4
	v_mov_b32_e32 v22, v4
	v_mov_b32_e32 v23, v4
	v_mov_b32_e32 v24, v4
	v_mov_b32_e32 v25, v4
	v_mov_b32_e32 v26, v4
	v_mov_b32_e32 v27, v4
	v_mov_b32_e32 v36, v4
	v_mov_b32_e32 v37, v4
	v_mov_b32_e32 v38, v4
	v_mov_b32_e32 v39, v4
	v_mov_b32_e32 v40, v4
	v_mov_b32_e32 v41, v4
	v_mov_b32_e32 v42, v4
	v_mov_b32_e32 v43, v4
	v_mov_b32_e32 v52, v4
	v_mov_b32_e32 v53, v4
	v_mov_b32_e32 v54, v4
	v_mov_b32_e32 v55, v4
	v_mov_b32_e32 v60, v4
	v_mov_b32_e32 v61, v4
	v_mov_b32_e32 v62, v4
	v_mov_b32_e32 v63, v4
	v_mov_b32_e32 v12, v4
	v_mov_b32_e32 v13, v4
	v_mov_b32_e32 v14, v4
	v_mov_b32_e32 v15, v4
	v_mov_b32_e32 v16, v4
	v_mov_b32_e32 v17, v4
	v_mov_b32_e32 v18, v4
	v_mov_b32_e32 v19, v4
	v_mov_b32_e32 v28, v4
	v_mov_b32_e32 v29, v4
	v_mov_b32_e32 v30, v4
	v_mov_b32_e32 v31, v4
	v_mov_b32_e32 v32, v4
	v_mov_b32_e32 v33, v4
	v_mov_b32_e32 v34, v4
	v_mov_b32_e32 v35, v4
	v_mov_b32_e32 v44, v4
	v_mov_b32_e32 v45, v4
	v_mov_b32_e32 v46, v4
	v_mov_b32_e32 v47, v4
	v_mov_b32_e32 v48, v4
	v_mov_b32_e32 v49, v4
	v_mov_b32_e32 v50, v4
	v_mov_b32_e32 v51, v4
	v_mov_b32_e32 v76, v4
	v_mov_b32_e32 v77, v4
	v_mov_b32_e32 v78, v4
	v_mov_b32_e32 v79, v4
	v_mov_b32_e32 v80, v4
	v_mov_b32_e32 v81, v4
	v_mov_b32_e32 v82, v4
	v_mov_b32_e32 v83, v4
	v_mov_b32_e32 v84, v4
	v_mov_b32_e32 v85, v4
	v_mov_b32_e32 v86, v4
	v_mov_b32_e32 v87, v4
	v_mov_b32_e32 v88, v4
	v_mov_b32_e32 v89, v4
	v_mov_b32_e32 v90, v4
	v_mov_b32_e32 v91, v4
	v_mov_b32_e32 v100, v4
	v_mov_b32_e32 v101, v4
	v_mov_b32_e32 v102, v4
	v_mov_b32_e32 v103, v4
	v_mov_b32_e32 v104, v4
	v_mov_b32_e32 v105, v4
	v_mov_b32_e32 v106, v4
	v_mov_b32_e32 v107, v4
	v_mov_b32_e32 v116, v4
	v_mov_b32_e32 v117, v4
	v_mov_b32_e32 v118, v4
	v_mov_b32_e32 v119, v4
	v_mov_b32_e32 v120, v4
	v_mov_b32_e32 v121, v4
	v_mov_b32_e32 v122, v4
	v_mov_b32_e32 v123, v4
	v_mov_b32_e32 v132, v4
	v_mov_b32_e32 v133, v4
	v_mov_b32_e32 v134, v4
	v_mov_b32_e32 v135, v4
	v_mov_b32_e32 v136, v4
	v_mov_b32_e32 v137, v4
	v_mov_b32_e32 v138, v4
	v_mov_b32_e32 v139, v4
	v_mov_b32_e32 v92, v4
	v_mov_b32_e32 v93, v4
	v_mov_b32_e32 v94, v4
	v_mov_b32_e32 v95, v4
	v_mov_b32_e32 v96, v4
	v_mov_b32_e32 v97, v4
	v_mov_b32_e32 v98, v4
	v_mov_b32_e32 v99, v4
	v_mov_b32_e32 v108, v4
	v_mov_b32_e32 v109, v4
	v_mov_b32_e32 v110, v4
	v_mov_b32_e32 v111, v4
	v_mov_b32_e32 v112, v4
	v_mov_b32_e32 v113, v4
	v_mov_b32_e32 v114, v4
	v_mov_b32_e32 v115, v4
	v_mov_b32_e32 v124, v4
	v_mov_b32_e32 v125, v4
	v_mov_b32_e32 v126, v4
	v_mov_b32_e32 v127, v4
	v_mov_b32_e32 v128, v4
	v_mov_b32_e32 v129, v4
	v_mov_b32_e32 v130, v4
	v_mov_b32_e32 v131, v4
	v_mov_b32_e32 v140, v4
	v_mov_b32_e32 v141, v4
	v_mov_b32_e32 v142, v4
	v_mov_b32_e32 v143, v4
	v_mov_b32_e32 v144, v4
	v_mov_b32_e32 v145, v4
	v_mov_b32_e32 v146, v4
	v_mov_b32_e32 v147, v4
	s_cmp_ge_u32 s72, 0x100
	s_cbranch_scc0 .Lg3_noprio
	s_setprio 1
.Lg3_noprio:
.LBB0_949:
	s_add_u32 s25, s30, 0xfff80080
	s_addc_u32 s34, s31, -1
	s_add_i32 s70, 0, 0x10000
	v_add_u32_e32 v72, s70, v168
	ds_read_b128 v[56:59], v72
	ds_read_b128 v[64:67], v72 offset:1024
	ds_read_b128 v[68:71], v72 offset:2048
	ds_read_b128 v[72:75], v72 offset:3072
	s_cmp_eq_u32 s19, 28
	s_cselect_b32 s37, s27, s34
	s_cselect_b32 s36, s26, s25
	s_cselect_b32 s35, s29, s17
	s_cselect_b32 s34, s28, s11
	v_lshl_add_u64 v[166:167], s[30:31], 0, v[150:151]
	s_add_i32 m0, s50, 0xc000
	ds_read_b128 v[158:161], v189
	ds_read_b128 v[162:165], v189 offset:1024
	ds_read_b128 v[190:193], v189 offset:2048
	ds_read_b128 v[194:197], v189 offset:3072
	ds_read_b128 v[198:201], v189 offset:4096
	ds_read_b128 v[202:205], v189 offset:5120
	ds_read_b128 v[206:209], v189 offset:6144
	ds_read_b128 v[210:213], v189 offset:7168
	global_load_lds_dwordx4 v[166:167], off
	v_lshl_add_u64 v[166:167], s[30:31], 0, v[156:157]
	s_add_i32 m0, s50, 0xe000
	s_nop 0
	global_load_lds_dwordx4 v[166:167], off
	s_waitcnt lgkmcnt(8)
	s_barrier
	s_waitcnt lgkmcnt(0)
	s_waitcnt lgkmcnt(0)
	v_mfma_f32_16x16x32_bf16 v[144:147], v[56:59], v[158:161], v[144:147]
	v_mfma_f32_16x16x32_bf16 v[140:143], v[68:71], v[158:161], v[140:143]
	v_mfma_f32_16x16x32_bf16 v[128:131], v[56:59], v[190:193], v[128:131]
	v_mfma_f32_16x16x32_bf16 v[124:127], v[68:71], v[190:193], v[124:127]
	v_mfma_f32_16x16x32_bf16 v[112:115], v[56:59], v[198:201], v[112:115]
	v_mfma_f32_16x16x32_bf16 v[108:111], v[68:71], v[198:201], v[108:111]
	v_mfma_f32_16x16x32_bf16 v[96:99], v[56:59], v[206:209], v[96:99]
	v_mfma_f32_16x16x32_bf16 v[92:95], v[68:71], v[206:209], v[92:95]
	v_mfma_f32_16x16x32_bf16 v[144:147], v[64:67], v[162:165], v[144:147]
	v_mfma_f32_16x16x32_bf16 v[140:143], v[72:75], v[162:165], v[140:143]
	v_mfma_f32_16x16x32_bf16 v[128:131], v[64:67], v[194:197], v[128:131]
	v_mfma_f32_16x16x32_bf16 v[124:127], v[72:75], v[194:197], v[124:127]
	v_mfma_f32_16x16x32_bf16 v[112:115], v[64:67], v[202:205], v[112:115]
	v_mfma_f32_16x16x32_bf16 v[108:111], v[72:75], v[202:205], v[108:111]
	v_mfma_f32_16x16x32_bf16 v[96:99], v[64:67], v[210:213], v[96:99]
	v_mfma_f32_16x16x32_bf16 v[92:95], v[72:75], v[210:213], v[92:95]
	s_barrier
; #define G8_STAGE(bufoff, gbase, voff) do { _Pragma("unroll") for (int _i = 0; _i < 2; ++_i) \
;     __builtin_amdgcn_global_load_lds((const unsigned*)((const char*)(gbase) + (voff)[_i]), (LAS unsigned*)(lds + (bufoff) + ldsw + _i * 8192), 16, 0, 0); } while (0)
; #define G8_LDA(dst, b, h) do { _Pragma("unroll") for (int m = 0; m < 4; ++m) _Pragma("unroll") for (int k = 0; k < 2; ++k) dst[m][k] = *(const LAS bf16x8*)(lds + G8_SA(b, h) + aoff + m * 2048 + k * 1024); } while (0)
; #define G8_LDB(dst, b, h) do { _Pragma("unroll") for (int n = 0; n < 2; ++n) _Pragma("unroll") for (int k = 0; k < 2; ++k) dst[n][k] = *(const LAS bf16x8*)(lds + G8_SB(b, h) + boff + n * 2048 + k * 1024); } while (0)
; #define G8_MMA(ai, bj, At, Bt) do { __builtin_amdgcn_s_setprio(1); _Pragma("unroll") for (int m = 0; m < 4; ++m) _Pragma("unroll") for (int n = 0; n < 2; ++n) _Pragma("unroll") for (int k = 0; k < 2; ++k) \
;     acc[ai][bj][m][n] = __builtin_amdgcn_mfma_f32_16x16x32_bf16(Bt[n][k], At[m][k], acc[ai][bj][m][n], 0, 0, 0); __builtin_amdgcn_s_setprio(0); } while (0)
; #define G8_WAIT_V(n) asm volatile("s_waitcnt vmcnt(" #n ")" ::: "memory")
; #define G8_WAIT_L(n) asm volatile("s_waitcnt lgkmcnt(" #n ")" ::: "memory")
; #define G8_BAR __builtin_amdgcn_s_barrier()
; #define G8_SCHED __builtin_amdgcn_sched_barrier(0)
; template <class Epi, class Sched>
; __device__ __forceinline__ void gemm_phase(const int wv_, LAS unsigned char* lds, const int lda, const int ldb, const int K, const Sched& S, const Epi& E) {
;     ...
;       G8_LDB(B1, 0, 1); G8_STAGE(G8_SB(0, 0), b2, voffB);
;       G8_BAR; G8_WAIT_L(0); G8_MMA(0, 1, At, B1); G8_BAR;
;       G8_LDA(At, 0, 1); G8_STAGE(G8_SA(0, 0), a2, voffA);
;       G8_BAR; G8_WAIT_L(0); G8_MMA(1, 0, At, B0); G8_BAR; G8_SCHED;
;       G8_STAGE(G8_SB(0, 1), b2 + hstepB, voffB);
;       G8_WAIT_V(6); G8_BAR; G8_MMA(1, 1, At, B1); G8_BAR;
;       G8_LDB(B0, 1, 0); G8_SCHED; G8_LDA(At, 1, 0); G8_STAGE(G8_SA(0, 1), a2 + hstepA, voffA);
;       G8_WAIT_L(8); G8_BAR; G8_WAIT_L(0); G8_MMA(0, 0, At, B0); G8_BAR; G8_SCHED;
;       G8_LDB(B1, 1, 1); G8_STAGE(G8_SB(1, 0), b3, voffB);
	s_add_i32 s25, 0, 0x14000
	v_add_u32_e32 v166, s25, v168
	s_add_i32 s70, s70, s47
	ds_read_b128 v[214:217], v166
	ds_read_b128 v[218:221], v166 offset:1024
	ds_read_b128 v[222:225], v166 offset:2048
	ds_read_b128 v[226:229], v166 offset:3072
	v_lshl_add_u64 v[166:167], s[34:35], 0, v[0:1]
	s_mov_b32 m0, s70
	v_lshl_add_u64 v[230:231], s[34:35], 0, v[148:149]
	global_load_lds_dwordx4 v[166:167], off
	s_add_i32 m0, s70, 0x2000
	s_nop 0
	global_load_lds_dwordx4 v[230:231], off
	s_barrier
	s_waitcnt lgkmcnt(0)
	s_waitcnt lgkmcnt(0)
	v_mfma_f32_16x16x32_bf16 v[136:139], v[214:217], v[158:161], v[136:139]
	v_mfma_f32_16x16x32_bf16 v[132:135], v[222:225], v[158:161], v[132:135]
	v_mfma_f32_16x16x32_bf16 v[120:123], v[214:217], v[190:193], v[120:123]
	v_mfma_f32_16x16x32_bf16 v[116:119], v[222:225], v[190:193], v[116:119]
	v_mfma_f32_16x16x32_bf16 v[104:107], v[214:217], v[198:201], v[104:107]
	v_mfma_f32_16x16x32_bf16 v[100:103], v[222:225], v[198:201], v[100:103]
	v_mfma_f32_16x16x32_bf16 v[88:91], v[214:217], v[206:209], v[88:91]
	v_mfma_f32_16x16x32_bf16 v[84:87], v[222:225], v[206:209], v[84:87]
	v_mfma_f32_16x16x32_bf16 v[136:139], v[218:221], v[162:165], v[136:139]
	v_mfma_f32_16x16x32_bf16 v[132:135], v[226:229], v[162:165], v[132:135]
	v_mfma_f32_16x16x32_bf16 v[120:123], v[218:221], v[194:197], v[120:123]
	v_mfma_f32_16x16x32_bf16 v[116:119], v[226:229], v[194:197], v[116:119]
	v_mfma_f32_16x16x32_bf16 v[104:107], v[218:221], v[202:205], v[104:107]
	v_mfma_f32_16x16x32_bf16 v[100:103], v[226:229], v[202:205], v[100:103]
	v_mfma_f32_16x16x32_bf16 v[88:91], v[218:221], v[210:213], v[88:91]
	v_mfma_f32_16x16x32_bf16 v[84:87], v[226:229], v[210:213], v[84:87]
	s_mov_b32 m0, s50
	v_lshl_add_u64 v[232:233], s[36:37], 0, v[0:1]
	s_barrier
	ds_read_b128 v[158:161], v189 offset:16384
	ds_read_b128 v[162:165], v189 offset:17408
	ds_read_b128 v[190:193], v189 offset:18432
	ds_read_b128 v[194:197], v189 offset:19456
	ds_read_b128 v[198:201], v189 offset:20480
	ds_read_b128 v[202:205], v189 offset:21504
	ds_read_b128 v[206:209], v189 offset:22528
	ds_read_b128 v[210:213], v189 offset:23552
	global_load_lds_dwordx4 v[232:233], off
	v_lshl_add_u64 v[234:235], s[36:37], 0, v[148:149]
	s_mov_b32 m0, s51
	s_nop 0
	global_load_lds_dwordx4 v[234:235], off
	s_barrier
	s_waitcnt lgkmcnt(0)
	s_waitcnt lgkmcnt(0)
	v_mfma_f32_16x16x32_bf16 v[80:83], v[56:59], v[158:161], v[80:83]
	v_mfma_f32_16x16x32_bf16 v[76:79], v[68:71], v[158:161], v[76:79]
	v_mfma_f32_16x16x32_bf16 v[48:51], v[56:59], v[190:193], v[48:51]
	v_mfma_f32_16x16x32_bf16 v[44:47], v[68:71], v[190:193], v[44:47]
	v_mfma_f32_16x16x32_bf16 v[32:35], v[56:59], v[198:201], v[32:35]
	v_mfma_f32_16x16x32_bf16 v[28:31], v[68:71], v[198:201], v[28:31]
	v_mfma_f32_16x16x32_bf16 v[16:19], v[56:59], v[206:209], v[16:19]
	v_mfma_f32_16x16x32_bf16 v[12:15], v[68:71], v[206:209], v[12:15]
	v_mfma_f32_16x16x32_bf16 v[80:83], v[64:67], v[162:165], v[80:83]
	v_mfma_f32_16x16x32_bf16 v[76:79], v[72:75], v[162:165], v[76:79]
	v_mfma_f32_16x16x32_bf16 v[48:51], v[64:67], v[194:197], v[48:51]
	v_mfma_f32_16x16x32_bf16 v[44:47], v[72:75], v[194:197], v[44:47]
	v_mfma_f32_16x16x32_bf16 v[32:35], v[64:67], v[202:205], v[32:35]
	v_mfma_f32_16x16x32_bf16 v[28:31], v[72:75], v[202:205], v[28:31]
	v_mfma_f32_16x16x32_bf16 v[16:19], v[64:67], v[210:213], v[16:19]
	v_mfma_f32_16x16x32_bf16 v[12:15], v[72:75], v[210:213], v[12:15]
	s_barrier
	s_add_u32 s70, s34, 0x80000
	s_addc_u32 s71, s35, 0
	s_add_i32 s25, s25, s47
	v_lshl_add_u64 v[56:57], s[70:71], 0, v[0:1]
	s_mov_b32 m0, s25
	s_nop 0
	global_load_lds_dwordx4 v[56:57], off
	v_lshl_add_u64 v[56:57], s[70:71], 0, v[148:149]
	s_add_i32 m0, s25, 0x2000
	s_nop 0
	global_load_lds_dwordx4 v[56:57], off
	s_waitcnt vmcnt(6)
	s_barrier
	v_mfma_f32_16x16x32_bf16 v[52:55], v[222:225], v[158:161], v[52:55]
	v_mfma_f32_16x16x32_bf16 v[40:43], v[214:217], v[190:193], v[40:43]
	v_mfma_f32_16x16x32_bf16 v[36:39], v[222:225], v[190:193], v[36:39]
	v_mfma_f32_16x16x32_bf16 v[24:27], v[214:217], v[198:201], v[24:27]
	v_mfma_f32_16x16x32_bf16 v[20:23], v[222:225], v[198:201], v[20:23]
	v_mfma_f32_16x16x32_bf16 v[8:11], v[214:217], v[206:209], v[8:11]
	v_mfma_f32_16x16x32_bf16 v[4:7], v[222:225], v[206:209], v[4:7]
	v_mfma_f32_16x16x32_bf16 v[56:59], v[214:217], v[158:161], v[60:63]
	v_mfma_f32_16x16x32_bf16 v[52:55], v[226:229], v[162:165], v[52:55]
	v_mfma_f32_16x16x32_bf16 v[40:43], v[218:221], v[194:197], v[40:43]
	v_mfma_f32_16x16x32_bf16 v[36:39], v[226:229], v[194:197], v[36:39]
	v_mfma_f32_16x16x32_bf16 v[24:27], v[218:221], v[202:205], v[24:27]
	v_mfma_f32_16x16x32_bf16 v[20:23], v[226:229], v[202:205], v[20:23]
	v_mfma_f32_16x16x32_bf16 v[8:11], v[218:221], v[210:213], v[8:11]
	v_mfma_f32_16x16x32_bf16 v[4:7], v[226:229], v[210:213], v[4:7]
	v_mfma_f32_16x16x32_bf16 v[56:59], v[218:221], v[162:165], v[56:59]
	s_add_i32 s25, 0, 0x18000
	v_add_u32_e32 v72, s25, v168
	s_barrier
	ds_read_b128 v[60:63], v72
	ds_read_b128 v[64:67], v72 offset:1024
	ds_read_b128 v[68:71], v72 offset:2048
	ds_read_b128 v[72:75], v72 offset:3072
	s_add_u32 s36, s36, 0x80000
	s_addc_u32 s37, s37, 0
	s_mov_b32 m0, s58
	v_lshl_add_u64 v[214:215], s[36:37], 0, v[0:1]
	ds_read_b128 v[158:161], v189 offset:32768
	ds_read_b128 v[162:165], v189 offset:33792
	ds_read_b128 v[190:193], v189 offset:34816
	ds_read_b128 v[194:197], v189 offset:35840
	ds_read_b128 v[198:201], v189 offset:36864
	ds_read_b128 v[202:205], v189 offset:37888
	ds_read_b128 v[206:209], v189 offset:38912
	ds_read_b128 v[210:213], v189 offset:39936
	global_load_lds_dwordx4 v[214:215], off
	v_lshl_add_u64 v[214:215], s[36:37], 0, v[148:149]
	s_mov_b32 m0, s59
	s_nop 0
	global_load_lds_dwordx4 v[214:215], off
	s_waitcnt lgkmcnt(8)
	s_barrier
; #define G8_STAGE(bufoff, gbase, voff) do { _Pragma("unroll") for (int _i = 0; _i < 2; ++_i) \
;     __builtin_amdgcn_global_load_lds((const unsigned*)((const char*)(gbase) + (voff)[_i]), (LAS unsigned*)(lds + (bufoff) + ldsw + _i * 8192), 16, 0, 0); } while (0)
; #define G8_LDA(dst, b, h) do { _Pragma("unroll") for (int m = 0; m < 4; ++m) _Pragma("unroll") for (int k = 0; k < 2; ++k) dst[m][k] = *(const LAS bf16x8*)(lds + G8_SA(b, h) + aoff + m * 2048 + k * 1024); } while (0)
; #define G8_MMA(ai, bj, At, Bt) do { __builtin_amdgcn_s_setprio(1); _Pragma("unroll") for (int m = 0; m < 4; ++m) _Pragma("unroll") for (int n = 0; n < 2; ++n) _Pragma("unroll") for (int k = 0; k < 2; ++k) \
;     acc[ai][bj][m][n] = __builtin_amdgcn_mfma_f32_16x16x32_bf16(Bt[n][k], At[m][k], acc[ai][bj][m][n], 0, 0, 0); __builtin_amdgcn_s_setprio(0); } while (0)
; #define G8_WAIT_V(n) asm volatile("s_waitcnt vmcnt(" #n ")" ::: "memory")
; #define G8_WAIT_L(n) asm volatile("s_waitcnt lgkmcnt(" #n ")" ::: "memory")
; #define G8_BAR __builtin_amdgcn_s_barrier()
; template <class Epi, class Sched>
; __device__ __forceinline__ void gemm_phase(const int wv_, LAS unsigned char* lds, const int lda, const int ldb, const int K, const Sched& S, const Epi& E) {
;     ...
;       G8_BAR; G8_WAIT_L(0); G8_MMA(0, 1, At, B1); G8_BAR;
;       G8_LDA(At, 1, 1); G8_STAGE(G8_SA(1, 0), a3, voffA);
;       G8_BAR; G8_WAIT_L(0); G8_MMA(1, 0, At, B0); G8_BAR; G8_SCHED;
;       G8_STAGE(G8_SB(1, 1), b3 + hstepB, voffB);
;       G8_WAIT_V(6); G8_BAR; G8_MMA(1, 1, At, B1); G8_BAR;
;     }
;   __device__ __forceinline__ bool operator()(f32x4 (&acc)[2][2][4][2], const Unit& u, int wr, int wc, int fr, int fq) const {
;     const int row0 = u.pm * BM + wr * 64 + fr, col0 = u.pn * BM + wc * 32 + 4 * fq;
;     const int who = row_who(u.pm * BM);
;     const float* gp = modl + (size_t)who * 12288 + part * 2048 + col0;
;     f32x4 gv[2][2];
; #pragma unroll
;     for (int bj = 0; bj < 2; ++bj)
; #pragma unroll
;       for (int n = 0; n < 2; ++n) gv[bj][n] = *(const f32x4*)(gp + bj * HALF + n * 16);
; #pragma unroll
;     for (int ai = 0; ai < 2; ++ai)
; #pragma unroll
;       for (int m = 0; m < 4; ++m) { const int row = row0 + ai * HALF + m * 16;
;         KPR p = (KParams*)__builtin_amdgcn_kernarg_segment_ptr();
;         const float* src = xrow_ptr(p, layer_src, row) + col0; float* dst = xrow_dst(p, row) + col0;
	s_waitcnt lgkmcnt(0)
	s_waitcnt lgkmcnt(0)
	v_mfma_f32_16x16x32_bf16 v[144:147], v[60:63], v[158:161], v[144:147]
	v_mfma_f32_16x16x32_bf16 v[140:143], v[68:71], v[158:161], v[140:143]
	v_mfma_f32_16x16x32_bf16 v[128:131], v[60:63], v[190:193], v[128:131]
	v_mfma_f32_16x16x32_bf16 v[124:127], v[68:71], v[190:193], v[124:127]
	v_mfma_f32_16x16x32_bf16 v[112:115], v[60:63], v[198:201], v[112:115]
	v_mfma_f32_16x16x32_bf16 v[108:111], v[68:71], v[198:201], v[108:111]
	v_mfma_f32_16x16x32_bf16 v[96:99], v[60:63], v[206:209], v[96:99]
	v_mfma_f32_16x16x32_bf16 v[92:95], v[68:71], v[206:209], v[92:95]
	v_mfma_f32_16x16x32_bf16 v[144:147], v[64:67], v[162:165], v[144:147]
	v_mfma_f32_16x16x32_bf16 v[140:143], v[72:75], v[162:165], v[140:143]
	v_mfma_f32_16x16x32_bf16 v[128:131], v[64:67], v[194:197], v[128:131]
	v_mfma_f32_16x16x32_bf16 v[124:127], v[72:75], v[194:197], v[124:127]
	v_mfma_f32_16x16x32_bf16 v[112:115], v[64:67], v[202:205], v[112:115]
	v_mfma_f32_16x16x32_bf16 v[108:111], v[72:75], v[202:205], v[108:111]
	v_mfma_f32_16x16x32_bf16 v[96:99], v[64:67], v[210:213], v[96:99]
	v_mfma_f32_16x16x32_bf16 v[92:95], v[72:75], v[210:213], v[92:95]
	s_barrier
	s_add_i32 s36, 0, 0x1c000
	s_add_i32 s25, s25, s47
	v_add_u32_e32 v226, s36, v168
	v_lshl_add_u64 v[166:167], v[166:167], 0, s[90:91]
	s_mov_b32 m0, s25
	ds_read_b128 v[214:217], v226
	ds_read_b128 v[218:221], v226 offset:1024
	ds_read_b128 v[222:225], v226 offset:2048
	ds_read_b128 v[226:229], v226 offset:3072
	global_load_lds_dwordx4 v[166:167], off
	v_lshl_add_u64 v[166:167], v[230:231], 0, s[90:91]
	s_add_i32 m0, s25, 0x2000
	s_nop 0
	global_load_lds_dwordx4 v[166:167], off
	s_barrier
	s_waitcnt lgkmcnt(0)
	s_waitcnt lgkmcnt(0)
	v_mfma_f32_16x16x32_bf16 v[136:139], v[214:217], v[158:161], v[136:139]
	v_mfma_f32_16x16x32_bf16 v[132:135], v[222:225], v[158:161], v[132:135]
	v_mfma_f32_16x16x32_bf16 v[120:123], v[214:217], v[190:193], v[120:123]
	v_mfma_f32_16x16x32_bf16 v[116:119], v[222:225], v[190:193], v[116:119]
	v_mfma_f32_16x16x32_bf16 v[104:107], v[214:217], v[198:201], v[104:107]
	v_mfma_f32_16x16x32_bf16 v[100:103], v[222:225], v[198:201], v[100:103]
	v_mfma_f32_16x16x32_bf16 v[88:91], v[214:217], v[206:209], v[88:91]
	v_mfma_f32_16x16x32_bf16 v[84:87], v[222:225], v[206:209], v[84:87]
	v_mfma_f32_16x16x32_bf16 v[136:139], v[218:221], v[162:165], v[136:139]
	v_mfma_f32_16x16x32_bf16 v[132:135], v[226:229], v[162:165], v[132:135]
	v_mfma_f32_16x16x32_bf16 v[120:123], v[218:221], v[194:197], v[120:123]
	v_mfma_f32_16x16x32_bf16 v[116:119], v[226:229], v[194:197], v[116:119]
	v_mfma_f32_16x16x32_bf16 v[104:107], v[218:221], v[202:205], v[104:107]
	v_mfma_f32_16x16x32_bf16 v[100:103], v[226:229], v[202:205], v[100:103]
	v_mfma_f32_16x16x32_bf16 v[88:91], v[218:221], v[210:213], v[88:91]
	v_mfma_f32_16x16x32_bf16 v[84:87], v[226:229], v[210:213], v[84:87]
	s_mov_b32 m0, s68
	v_lshl_add_u64 v[166:167], v[232:233], 0, s[90:91]
	s_barrier
	ds_read_b128 v[158:161], v189 offset:49152
	ds_read_b128 v[162:165], v189 offset:50176
	ds_read_b128 v[190:193], v189 offset:51200
	ds_read_b128 v[194:197], v189 offset:52224
	ds_read_b128 v[198:201], v189 offset:53248
	ds_read_b128 v[202:205], v189 offset:54272
	ds_read_b128 v[206:209], v189 offset:55296
	ds_read_b128 v[210:213], v189 offset:56320
	global_load_lds_dwordx4 v[166:167], off
	v_lshl_add_u64 v[166:167], v[234:235], 0, s[90:91]
	s_mov_b32 m0, s69
	s_nop 0
	global_load_lds_dwordx4 v[166:167], off
	s_barrier
	s_waitcnt lgkmcnt(0)
	s_waitcnt lgkmcnt(0)
	v_mfma_f32_16x16x32_bf16 v[80:83], v[60:63], v[158:161], v[80:83]
	v_mfma_f32_16x16x32_bf16 v[76:79], v[68:71], v[158:161], v[76:79]
	v_mfma_f32_16x16x32_bf16 v[48:51], v[60:63], v[190:193], v[48:51]
	v_mfma_f32_16x16x32_bf16 v[44:47], v[68:71], v[190:193], v[44:47]
	v_mfma_f32_16x16x32_bf16 v[32:35], v[60:63], v[198:201], v[32:35]
	v_mfma_f32_16x16x32_bf16 v[28:31], v[68:71], v[198:201], v[28:31]
	v_mfma_f32_16x16x32_bf16 v[16:19], v[60:63], v[206:209], v[16:19]
	v_mfma_f32_16x16x32_bf16 v[12:15], v[68:71], v[206:209], v[12:15]
	v_mfma_f32_16x16x32_bf16 v[80:83], v[64:67], v[162:165], v[80:83]
	v_mfma_f32_16x16x32_bf16 v[76:79], v[72:75], v[162:165], v[76:79]
	v_mfma_f32_16x16x32_bf16 v[48:51], v[64:67], v[194:197], v[48:51]
	v_mfma_f32_16x16x32_bf16 v[44:47], v[72:75], v[194:197], v[44:47]
	v_mfma_f32_16x16x32_bf16 v[32:35], v[64:67], v[202:205], v[32:35]
	v_mfma_f32_16x16x32_bf16 v[28:31], v[72:75], v[202:205], v[28:31]
	v_mfma_f32_16x16x32_bf16 v[16:19], v[64:67], v[210:213], v[16:19]
	v_mfma_f32_16x16x32_bf16 v[12:15], v[72:75], v[210:213], v[12:15]
	s_barrier
	s_add_u32 s34, s34, 0x80080
	s_addc_u32 s35, s35, 0
	s_add_i32 s25, s36, s47
	v_lshl_add_u64 v[60:61], s[34:35], 0, v[0:1]
	s_mov_b32 m0, s25
	s_nop 0
	global_load_lds_dwordx4 v[60:61], off
	v_lshl_add_u64 v[60:61], s[34:35], 0, v[148:149]
	s_add_i32 m0, s25, 0x2000
	s_nop 0
	global_load_lds_dwordx4 v[60:61], off
	s_waitcnt vmcnt(6)
	s_barrier
	v_mfma_f32_16x16x32_bf16 v[56:59], v[214:217], v[158:161], v[56:59]
	v_mfma_f32_16x16x32_bf16 v[52:55], v[222:225], v[158:161], v[52:55]
	v_mfma_f32_16x16x32_bf16 v[40:43], v[214:217], v[190:193], v[40:43]
	v_mfma_f32_16x16x32_bf16 v[36:39], v[222:225], v[190:193], v[36:39]
	v_mfma_f32_16x16x32_bf16 v[24:27], v[214:217], v[198:201], v[24:27]
	v_mfma_f32_16x16x32_bf16 v[20:23], v[222:225], v[198:201], v[20:23]
	v_mfma_f32_16x16x32_bf16 v[8:11], v[214:217], v[206:209], v[8:11]
	v_mfma_f32_16x16x32_bf16 v[4:7], v[222:225], v[206:209], v[4:7]
	v_mfma_f32_16x16x32_bf16 v[60:63], v[218:221], v[162:165], v[56:59]
	v_mfma_f32_16x16x32_bf16 v[52:55], v[226:229], v[162:165], v[52:55]
	v_mfma_f32_16x16x32_bf16 v[40:43], v[218:221], v[194:197], v[40:43]
	v_mfma_f32_16x16x32_bf16 v[36:39], v[226:229], v[194:197], v[36:39]
	v_mfma_f32_16x16x32_bf16 v[24:27], v[218:221], v[202:205], v[24:27]
	v_mfma_f32_16x16x32_bf16 v[20:23], v[226:229], v[202:205], v[20:23]
	v_mfma_f32_16x16x32_bf16 v[8:11], v[218:221], v[210:213], v[8:11]
	v_mfma_f32_16x16x32_bf16 v[4:7], v[226:229], v[210:213], v[4:7]
	s_add_i32 s19, s19, 2
	s_add_u32 s30, s30, 0x100
	s_addc_u32 s31, s31, 0
	s_add_u32 s11, s11, 0x100
	s_addc_u32 s17, s17, 0
	s_cmp_gt_u32 s19, 29
	s_barrier
	s_cbranch_scc0 .LBB0_949
	s_setprio 0
	v_lshl_or_b32 v158, s10, 8, v169
	s_mul_hi_i32 s11, s24, 0x78787879
	s_lshr_b32 s17, s11, 31
	s_ashr_i32 s11, s11, 3
	s_add_i32 s11, s11, s17
	s_lshl_b32 s17, s24, 8
	s_mul_i32 s10, s11, 0xffffef00
	s_add_i32 s10, s10, s17
	s_cmpk_gt_i32 s10, 0xff
	s_cbranch_scc1 .Lg3e_lat
	s_load_dwordx2 s[28:29], s[0:1], 0x118
	s_load_dwordx2 s[26:27], s[0:1], 0x10
	s_lshl_b32 s17, s11, 21
	s_mov_b32 s11, 4
	s_waitcnt lgkmcnt(0)
	s_add_u32 s28, s28, 0x7f8000
	s_addc_u32 s29, s29, 0
	s_cmp_eq_u32 s76, 0
	s_cbranch_scc1 .Lg3e_ptr
	s_mov_b64 s[26:27], s[28:29]
	s_branch .Lg3e_ptr

; #define G8_STAGE(bufoff, gbase, voff) do { _Pragma("unroll") for (int _i = 0; _i < 2; ++_i) \
;     __builtin_amdgcn_global_load_lds((const unsigned*)((const char*)(gbase) + (voff)[_i]), (LAS unsigned*)(lds + (bufoff) + ldsw + _i * 8192), 16, 0, 0); } while (0)
; #define G8_LDA(dst, b, h) do { _Pragma("unroll") for (int m = 0; m < 4; ++m) _Pragma("unroll") for (int k = 0; k < 2; ++k) dst[m][k] = *(const LAS bf16x8*)(lds + G8_SA(b, h) + aoff + m * 2048 + k * 1024); } while (0)
; #define G8_LDB(dst, b, h) do { _Pragma("unroll") for (int n = 0; n < 2; ++n) _Pragma("unroll") for (int k = 0; k < 2; ++k) dst[n][k] = *(const LAS bf16x8*)(lds + G8_SB(b, h) + boff + n * 2048 + k * 1024); } while (0)
; #define G8_MMA(ai, bj, At, Bt) do { __builtin_amdgcn_s_setprio(1); _Pragma("unroll") for (int m = 0; m < 4; ++m) _Pragma("unroll") for (int n = 0; n < 2; ++n) _Pragma("unroll") for (int k = 0; k < 2; ++k) \
;     acc[ai][bj][m][n] = __builtin_amdgcn_mfma_f32_16x16x32_bf16(Bt[n][k], At[m][k], acc[ai][bj][m][n], 0, 0, 0); __builtin_amdgcn_s_setprio(0); } while (0)
; #define G8_WAIT_L(n) asm volatile("s_waitcnt lgkmcnt(" #n ")" ::: "memory")
; #define G8_BAR __builtin_amdgcn_s_barrier()
; #define G8_SCHED __builtin_amdgcn_sched_barrier(0)
; template <class Epi, class Sched>
; __device__ __forceinline__ void gemm_phase(const int wv_, LAS unsigned char* lds, const int lda, const int ldb, const int K, const Sched& S, const Epi& E) {
;     ...
;     for (int t = 0; t < nt; t += 2) {
;       const bool last = (t == nt - 2);
;       const char* a1 = cA + (size_t)(t + 1) * kstep;
;       const char* a2 = last ? nA : cA + (size_t)(t + 2) * kstep; const char* b2 = last ? nB : cB + (size_t)(t + 2) * kstep;
;       const char* a3 = a2 + kstep; const char* b3 = b2 + kstep;
;       G8_LDB(B0, 0, 0); G8_SCHED; G8_LDA(At, 0, 0); G8_STAGE(G8_SA(1, 1), a1 + hstepA, voffA);
;       G8_WAIT_L(8); G8_BAR; G8_WAIT_L(0); G8_MMA(0, 0, At, B0); G8_BAR; G8_SCHED;
;     ...
; #pragma unroll
;       for (int a = 0; a < 2; ++a)
; #pragma unroll
;         for (int b = 0; b < 2; ++b)
; #pragma unroll
;           for (int m = 0; m < 4; ++m)
; #pragma unroll
;             for (int n = 0; n < 2; ++n) acc[a][b][m][n] = (f32x4){0.f, 0.f, 0.f, 0.f};
.LBB0_1172:
	s_add_u32 s26, s26, 0x80080
	s_addc_u32 s27, s27, 0
	s_add_u32 s13, s28, 0x100
	v_mov_b32_e32 v4, 0
	s_addc_u32 s17, s29, 0
	s_mov_b32 s50, -2
	v_mov_b32_e32 v5, v4
	v_mov_b32_e32 v6, v4
	v_mov_b32_e32 v7, v4
	v_mov_b32_e32 v8, v4
	v_mov_b32_e32 v9, v4
	v_mov_b32_e32 v10, v4
	v_mov_b32_e32 v11, v4
	v_mov_b32_e32 v20, v4
	v_mov_b32_e32 v21, v4
	v_mov_b32_e32 v22, v4
	v_mov_b32_e32 v23, v4
	v_mov_b32_e32 v24, v4
	v_mov_b32_e32 v25, v4
	v_mov_b32_e32 v26, v4
	v_mov_b32_e32 v27, v4
	v_mov_b32_e32 v36, v4
	v_mov_b32_e32 v37, v4
	v_mov_b32_e32 v38, v4
	v_mov_b32_e32 v39, v4
	v_mov_b32_e32 v40, v4
	v_mov_b32_e32 v41, v4
	v_mov_b32_e32 v42, v4
	v_mov_b32_e32 v43, v4
	v_mov_b32_e32 v52, v4
	v_mov_b32_e32 v53, v4
	v_mov_b32_e32 v54, v4
	v_mov_b32_e32 v55, v4
	v_mov_b32_e32 v56, v4
	v_mov_b32_e32 v57, v4
	v_mov_b32_e32 v58, v4
	v_mov_b32_e32 v59, v4
	v_mov_b32_e32 v12, v4
	v_mov_b32_e32 v13, v4
	v_mov_b32_e32 v14, v4
	v_mov_b32_e32 v15, v4
	v_mov_b32_e32 v16, v4
	v_mov_b32_e32 v17, v4
	v_mov_b32_e32 v18, v4
	v_mov_b32_e32 v19, v4
	v_mov_b32_e32 v28, v4
	v_mov_b32_e32 v29, v4
	v_mov_b32_e32 v30, v4
	v_mov_b32_e32 v31, v4
	v_mov_b32_e32 v32, v4
	v_mov_b32_e32 v33, v4
	v_mov_b32_e32 v34, v4
	v_mov_b32_e32 v35, v4
	v_mov_b32_e32 v44, v4
	v_mov_b32_e32 v45, v4
	v_mov_b32_e32 v46, v4
	v_mov_b32_e32 v47, v4
	v_mov_b32_e32 v48, v4
	v_mov_b32_e32 v49, v4
	v_mov_b32_e32 v50, v4
	v_mov_b32_e32 v51, v4
	v_mov_b32_e32 v60, v4
	v_mov_b32_e32 v61, v4
	v_mov_b32_e32 v62, v4
	v_mov_b32_e32 v63, v4
	v_mov_b32_e32 v64, v4
	v_mov_b32_e32 v65, v4
	v_mov_b32_e32 v66, v4
	v_mov_b32_e32 v67, v4
	v_mov_b32_e32 v68, v4
	v_mov_b32_e32 v69, v4
	v_mov_b32_e32 v70, v4
	v_mov_b32_e32 v71, v4
	v_mov_b32_e32 v72, v4
	v_mov_b32_e32 v73, v4
	v_mov_b32_e32 v74, v4
	v_mov_b32_e32 v75, v4
	v_mov_b32_e32 v84, v4
	v_mov_b32_e32 v85, v4
	v_mov_b32_e32 v86, v4
	v_mov_b32_e32 v87, v4
	v_mov_b32_e32 v88, v4
	v_mov_b32_e32 v89, v4
	v_mov_b32_e32 v90, v4
	v_mov_b32_e32 v91, v4
	v_mov_b32_e32 v100, v4
	v_mov_b32_e32 v101, v4
	v_mov_b32_e32 v102, v4
	v_mov_b32_e32 v103, v4
	v_mov_b32_e32 v104, v4
	v_mov_b32_e32 v105, v4
	v_mov_b32_e32 v106, v4
	v_mov_b32_e32 v107, v4
	v_mov_b32_e32 v116, v4
	v_mov_b32_e32 v117, v4
	v_mov_b32_e32 v118, v4
	v_mov_b32_e32 v119, v4
	v_mov_b32_e32 v120, v4
	v_mov_b32_e32 v121, v4
	v_mov_b32_e32 v122, v4
	v_mov_b32_e32 v123, v4
	v_mov_b32_e32 v76, v4
	v_mov_b32_e32 v77, v4
	v_mov_b32_e32 v78, v4
	v_mov_b32_e32 v79, v4
	v_mov_b32_e32 v80, v4
	v_mov_b32_e32 v81, v4
	v_mov_b32_e32 v82, v4
	v_mov_b32_e32 v83, v4
	v_mov_b32_e32 v92, v4
	v_mov_b32_e32 v93, v4
	v_mov_b32_e32 v94, v4
	v_mov_b32_e32 v95, v4
	v_mov_b32_e32 v96, v4
	v_mov_b32_e32 v97, v4
	v_mov_b32_e32 v98, v4
	v_mov_b32_e32 v99, v4
	v_mov_b32_e32 v108, v4
	v_mov_b32_e32 v109, v4
	v_mov_b32_e32 v110, v4
	v_mov_b32_e32 v111, v4
	v_mov_b32_e32 v112, v4
	v_mov_b32_e32 v113, v4
	v_mov_b32_e32 v114, v4
	v_mov_b32_e32 v115, v4
	v_mov_b32_e32 v124, v4
	v_mov_b32_e32 v125, v4
	v_mov_b32_e32 v126, v4
	v_mov_b32_e32 v127, v4
	v_mov_b32_e32 v128, v4
	v_mov_b32_e32 v129, v4
	v_mov_b32_e32 v130, v4
	v_mov_b32_e32 v131, v4
	s_cmp_ge_u32 s72, 0x100
	s_cbranch_scc0 .Lg4_noprio
	s_setprio 1
.Lg4_noprio:
.LBB0_1173:
	s_add_u32 s28, s26, 0xfff80080
	s_addc_u32 s29, s27, -1
	s_add_i32 s51, 0, 0x10000
	v_add_u32_e32 v149, s51, v146
	ds_read_b128 v[142:145], v149
	ds_read_b128 v[156:159], v149 offset:1024
	ds_read_b128 v[160:163], v149 offset:2048
	ds_read_b128 v[164:167], v149 offset:3072
	s_cmp_eq_u32 s50, 28
	s_cselect_b32 s31, s19, s29
	s_cselect_b32 s30, s18, s28
	s_cselect_b32 s29, s21, s17
	s_cselect_b32 s28, s20, s13
	v_lshl_add_u64 v[150:151], s[26:27], 0, v[138:139]
	s_add_i32 m0, s23, 0xc000
	ds_read_b128 v[190:193], v148
	ds_read_b128 v[194:197], v148 offset:1024
	ds_read_b128 v[198:201], v148 offset:2048
	ds_read_b128 v[202:205], v148 offset:3072
	ds_read_b128 v[206:209], v148 offset:4096
	ds_read_b128 v[210:213], v148 offset:5120
	ds_read_b128 v[214:217], v148 offset:6144
	ds_read_b128 v[218:221], v148 offset:7168
	global_load_lds_dwordx4 v[150:151], off
	v_lshl_add_u64 v[150:151], s[26:27], 0, v[140:141]
	s_add_i32 m0, s23, 0xe000
	s_nop 0
	global_load_lds_dwordx4 v[150:151], off
	s_waitcnt lgkmcnt(8)
	s_barrier
	s_waitcnt lgkmcnt(0)
	s_waitcnt lgkmcnt(0)
	v_mfma_f32_16x16x32_bf16 v[128:131], v[142:145], v[190:193], v[128:131]
	v_mfma_f32_16x16x32_bf16 v[124:127], v[160:163], v[190:193], v[124:127]
	v_mfma_f32_16x16x32_bf16 v[112:115], v[142:145], v[198:201], v[112:115]
	v_mfma_f32_16x16x32_bf16 v[108:111], v[160:163], v[198:201], v[108:111]
	v_mfma_f32_16x16x32_bf16 v[96:99], v[142:145], v[206:209], v[96:99]
	v_mfma_f32_16x16x32_bf16 v[92:95], v[160:163], v[206:209], v[92:95]
	v_mfma_f32_16x16x32_bf16 v[80:83], v[142:145], v[214:217], v[80:83]
	v_mfma_f32_16x16x32_bf16 v[76:79], v[160:163], v[214:217], v[76:79]
	v_mfma_f32_16x16x32_bf16 v[128:131], v[156:159], v[194:197], v[128:131]
	v_mfma_f32_16x16x32_bf16 v[124:127], v[164:167], v[194:197], v[124:127]
	v_mfma_f32_16x16x32_bf16 v[112:115], v[156:159], v[202:205], v[112:115]
	v_mfma_f32_16x16x32_bf16 v[108:111], v[164:167], v[202:205], v[108:111]
	v_mfma_f32_16x16x32_bf16 v[96:99], v[156:159], v[210:213], v[96:99]
	v_mfma_f32_16x16x32_bf16 v[92:95], v[164:167], v[210:213], v[92:95]
	v_mfma_f32_16x16x32_bf16 v[80:83], v[156:159], v[218:221], v[80:83]
	v_mfma_f32_16x16x32_bf16 v[76:79], v[164:167], v[218:221], v[76:79]
	s_barrier
; #define G8_STAGE(bufoff, gbase, voff) do { _Pragma("unroll") for (int _i = 0; _i < 2; ++_i) \
;     __builtin_amdgcn_global_load_lds((const unsigned*)((const char*)(gbase) + (voff)[_i]), (LAS unsigned*)(lds + (bufoff) + ldsw + _i * 8192), 16, 0, 0); } while (0)
; #define G8_LDA(dst, b, h) do { _Pragma("unroll") for (int m = 0; m < 4; ++m) _Pragma("unroll") for (int k = 0; k < 2; ++k) dst[m][k] = *(const LAS bf16x8*)(lds + G8_SA(b, h) + aoff + m * 2048 + k * 1024); } while (0)
; #define G8_LDB(dst, b, h) do { _Pragma("unroll") for (int n = 0; n < 2; ++n) _Pragma("unroll") for (int k = 0; k < 2; ++k) dst[n][k] = *(const LAS bf16x8*)(lds + G8_SB(b, h) + boff + n * 2048 + k * 1024); } while (0)
; #define G8_MMA(ai, bj, At, Bt) do { __builtin_amdgcn_s_setprio(1); _Pragma("unroll") for (int m = 0; m < 4; ++m) _Pragma("unroll") for (int n = 0; n < 2; ++n) _Pragma("unroll") for (int k = 0; k < 2; ++k) \
;     acc[ai][bj][m][n] = __builtin_amdgcn_mfma_f32_16x16x32_bf16(Bt[n][k], At[m][k], acc[ai][bj][m][n], 0, 0, 0); __builtin_amdgcn_s_setprio(0); } while (0)
; #define G8_WAIT_V(n) asm volatile("s_waitcnt vmcnt(" #n ")" ::: "memory")
; #define G8_WAIT_L(n) asm volatile("s_waitcnt lgkmcnt(" #n ")" ::: "memory")
; #define G8_BAR __builtin_amdgcn_s_barrier()
; #define G8_SCHED __builtin_amdgcn_sched_barrier(0)
; template <class Epi, class Sched>
; __device__ __forceinline__ void gemm_phase(const int wv_, LAS unsigned char* lds, const int lda, const int ldb, const int K, const Sched& S, const Epi& E) {
;     ...
;       G8_LDB(B1, 0, 1); G8_STAGE(G8_SB(0, 0), b2, voffB);
;       G8_BAR; G8_WAIT_L(0); G8_MMA(0, 1, At, B1); G8_BAR;
;       G8_LDA(At, 0, 1); G8_STAGE(G8_SA(0, 0), a2, voffA);
;       G8_BAR; G8_WAIT_L(0); G8_MMA(1, 0, At, B0); G8_BAR; G8_SCHED;
;       G8_STAGE(G8_SB(0, 1), b2 + hstepB, voffB);
;       G8_WAIT_V(6); G8_BAR; G8_MMA(1, 1, At, B1); G8_BAR;
;       G8_LDB(B0, 1, 0); G8_SCHED; G8_LDA(At, 1, 0); G8_STAGE(G8_SA(0, 1), a2 + hstepA, voffA);
;       G8_WAIT_L(8); G8_BAR; G8_WAIT_L(0); G8_MMA(0, 0, At, B0); G8_BAR; G8_SCHED;
;       G8_LDB(B1, 1, 1); G8_STAGE(G8_SB(1, 0), b3, voffB);
	s_add_i32 s68, 0, 0x14000
	s_add_i32 s51, s51, s40
	v_add_u32_e32 v149, s68, v146
	v_lshl_add_u64 v[150:151], s[28:29], 0, v[132:133]
	s_mov_b32 m0, s51
	ds_read_b128 v[222:225], v149
	ds_read_b128 v[226:229], v149 offset:1024
	ds_read_b128 v[230:233], v149 offset:2048
	ds_read_b128 v[234:237], v149 offset:3072
	global_load_lds_dwordx4 v[150:151], off
	v_lshl_add_u64 v[168:169], s[28:29], 0, v[136:137]
	s_add_i32 m0, s51, 0x2000
	s_nop 0
	global_load_lds_dwordx4 v[168:169], off
	s_barrier
	s_waitcnt lgkmcnt(0)
	s_waitcnt lgkmcnt(0)
	v_mfma_f32_16x16x32_bf16 v[120:123], v[222:225], v[190:193], v[120:123]
	v_mfma_f32_16x16x32_bf16 v[116:119], v[230:233], v[190:193], v[116:119]
	v_mfma_f32_16x16x32_bf16 v[104:107], v[222:225], v[198:201], v[104:107]
	v_mfma_f32_16x16x32_bf16 v[100:103], v[230:233], v[198:201], v[100:103]
	v_mfma_f32_16x16x32_bf16 v[88:91], v[222:225], v[206:209], v[88:91]
	v_mfma_f32_16x16x32_bf16 v[84:87], v[230:233], v[206:209], v[84:87]
	v_mfma_f32_16x16x32_bf16 v[72:75], v[222:225], v[214:217], v[72:75]
	v_mfma_f32_16x16x32_bf16 v[68:71], v[230:233], v[214:217], v[68:71]
	v_mfma_f32_16x16x32_bf16 v[120:123], v[226:229], v[194:197], v[120:123]
	v_mfma_f32_16x16x32_bf16 v[116:119], v[234:237], v[194:197], v[116:119]
	v_mfma_f32_16x16x32_bf16 v[104:107], v[226:229], v[202:205], v[104:107]
	v_mfma_f32_16x16x32_bf16 v[100:103], v[234:237], v[202:205], v[100:103]
	v_mfma_f32_16x16x32_bf16 v[88:91], v[226:229], v[210:213], v[88:91]
	v_mfma_f32_16x16x32_bf16 v[84:87], v[234:237], v[210:213], v[84:87]
	v_mfma_f32_16x16x32_bf16 v[72:75], v[226:229], v[218:221], v[72:75]
	v_mfma_f32_16x16x32_bf16 v[68:71], v[234:237], v[218:221], v[68:71]
	s_mov_b32 m0, s23
	v_lshl_add_u64 v[238:239], s[30:31], 0, v[0:1]
	s_barrier
	ds_read_b128 v[190:193], v148 offset:16384
	ds_read_b128 v[194:197], v148 offset:17408
	ds_read_b128 v[198:201], v148 offset:18432
	ds_read_b128 v[202:205], v148 offset:19456
	ds_read_b128 v[206:209], v148 offset:20480
	ds_read_b128 v[210:213], v148 offset:21504
	ds_read_b128 v[214:217], v148 offset:22528
	ds_read_b128 v[218:221], v148 offset:23552
	global_load_lds_dwordx4 v[238:239], off
	v_lshl_add_u64 v[240:241], s[30:31], 0, v[134:135]
	s_mov_b32 m0, s25
	s_nop 0
	global_load_lds_dwordx4 v[240:241], off
	s_barrier
	s_waitcnt lgkmcnt(0)
	s_waitcnt lgkmcnt(0)
	v_mfma_f32_16x16x32_bf16 v[64:67], v[142:145], v[190:193], v[64:67]
	v_mfma_f32_16x16x32_bf16 v[60:63], v[160:163], v[190:193], v[60:63]
	v_mfma_f32_16x16x32_bf16 v[48:51], v[142:145], v[198:201], v[48:51]
	v_mfma_f32_16x16x32_bf16 v[44:47], v[160:163], v[198:201], v[44:47]
	v_mfma_f32_16x16x32_bf16 v[32:35], v[142:145], v[206:209], v[32:35]
	v_mfma_f32_16x16x32_bf16 v[28:31], v[160:163], v[206:209], v[28:31]
	v_mfma_f32_16x16x32_bf16 v[16:19], v[142:145], v[214:217], v[16:19]
	v_mfma_f32_16x16x32_bf16 v[12:15], v[160:163], v[214:217], v[12:15]
	v_mfma_f32_16x16x32_bf16 v[64:67], v[156:159], v[194:197], v[64:67]
	v_mfma_f32_16x16x32_bf16 v[60:63], v[164:167], v[194:197], v[60:63]
	v_mfma_f32_16x16x32_bf16 v[48:51], v[156:159], v[202:205], v[48:51]
	v_mfma_f32_16x16x32_bf16 v[44:47], v[164:167], v[202:205], v[44:47]
	v_mfma_f32_16x16x32_bf16 v[32:35], v[156:159], v[210:213], v[32:35]
	v_mfma_f32_16x16x32_bf16 v[28:31], v[164:167], v[210:213], v[28:31]
	v_mfma_f32_16x16x32_bf16 v[16:19], v[156:159], v[218:221], v[16:19]
	v_mfma_f32_16x16x32_bf16 v[12:15], v[164:167], v[218:221], v[12:15]
	s_barrier
	s_add_u32 s58, s28, 0x80000
	s_addc_u32 s59, s29, 0
	s_add_i32 s51, s68, s40
	v_lshl_add_u64 v[142:143], s[58:59], 0, v[132:133]
	s_mov_b32 m0, s51
	s_nop 0
	global_load_lds_dwordx4 v[142:143], off
	v_lshl_add_u64 v[142:143], s[58:59], 0, v[136:137]
	s_add_i32 m0, s51, 0x2000
	s_nop 0
	global_load_lds_dwordx4 v[142:143], off
	s_waitcnt vmcnt(6)
	s_barrier
	v_mfma_f32_16x16x32_bf16 v[56:59], v[222:225], v[190:193], v[56:59]
	v_mfma_f32_16x16x32_bf16 v[52:55], v[230:233], v[190:193], v[52:55]
	v_mfma_f32_16x16x32_bf16 v[40:43], v[222:225], v[198:201], v[40:43]
	v_mfma_f32_16x16x32_bf16 v[36:39], v[230:233], v[198:201], v[36:39]
	v_mfma_f32_16x16x32_bf16 v[24:27], v[222:225], v[206:209], v[24:27]
	v_mfma_f32_16x16x32_bf16 v[20:23], v[230:233], v[206:209], v[20:23]
	v_mfma_f32_16x16x32_bf16 v[8:11], v[222:225], v[214:217], v[8:11]
	v_mfma_f32_16x16x32_bf16 v[4:7], v[230:233], v[214:217], v[4:7]
	v_mfma_f32_16x16x32_bf16 v[56:59], v[226:229], v[194:197], v[56:59]
	v_mfma_f32_16x16x32_bf16 v[52:55], v[234:237], v[194:197], v[52:55]
	v_mfma_f32_16x16x32_bf16 v[40:43], v[226:229], v[202:205], v[40:43]
	v_mfma_f32_16x16x32_bf16 v[36:39], v[234:237], v[202:205], v[36:39]
	v_mfma_f32_16x16x32_bf16 v[24:27], v[226:229], v[210:213], v[24:27]
	v_mfma_f32_16x16x32_bf16 v[20:23], v[234:237], v[210:213], v[20:23]
	v_mfma_f32_16x16x32_bf16 v[8:11], v[226:229], v[218:221], v[8:11]
	v_mfma_f32_16x16x32_bf16 v[4:7], v[234:237], v[218:221], v[4:7]
	s_add_i32 s51, 0, 0x18000
	v_add_u32_e32 v149, s51, v146
	s_barrier
	ds_read_b128 v[142:145], v149
	ds_read_b128 v[156:159], v149 offset:1024
	ds_read_b128 v[160:163], v149 offset:2048
	ds_read_b128 v[164:167], v149 offset:3072
	s_add_u32 s30, s30, 0x80000
	s_addc_u32 s31, s31, 0
	s_mov_b32 m0, s41
	v_lshl_add_u64 v[222:223], s[30:31], 0, v[0:1]
	ds_read_b128 v[190:193], v148 offset:32768
	ds_read_b128 v[194:197], v148 offset:33792
	ds_read_b128 v[198:201], v148 offset:34816
	ds_read_b128 v[202:205], v148 offset:35840
	ds_read_b128 v[206:209], v148 offset:36864
	ds_read_b128 v[210:213], v148 offset:37888
	ds_read_b128 v[214:217], v148 offset:38912
	ds_read_b128 v[218:221], v148 offset:39936
	global_load_lds_dwordx4 v[222:223], off
	v_lshl_add_u64 v[222:223], s[30:31], 0, v[134:135]
	s_mov_b32 m0, s42
	s_nop 0
	global_load_lds_dwordx4 v[222:223], off
	s_waitcnt lgkmcnt(8)
	s_barrier
; #define G8_STAGE(bufoff, gbase, voff) do { _Pragma("unroll") for (int _i = 0; _i < 2; ++_i) \
;     __builtin_amdgcn_global_load_lds((const unsigned*)((const char*)(gbase) + (voff)[_i]), (LAS unsigned*)(lds + (bufoff) + ldsw + _i * 8192), 16, 0, 0); } while (0)
; #define G8_LDA(dst, b, h) do { _Pragma("unroll") for (int m = 0; m < 4; ++m) _Pragma("unroll") for (int k = 0; k < 2; ++k) dst[m][k] = *(const LAS bf16x8*)(lds + G8_SA(b, h) + aoff + m * 2048 + k * 1024); } while (0)
; #define G8_MMA(ai, bj, At, Bt) do { __builtin_amdgcn_s_setprio(1); _Pragma("unroll") for (int m = 0; m < 4; ++m) _Pragma("unroll") for (int n = 0; n < 2; ++n) _Pragma("unroll") for (int k = 0; k < 2; ++k) \
;     acc[ai][bj][m][n] = __builtin_amdgcn_mfma_f32_16x16x32_bf16(Bt[n][k], At[m][k], acc[ai][bj][m][n], 0, 0, 0); __builtin_amdgcn_s_setprio(0); } while (0)
; #define G8_WAIT_V(n) asm volatile("s_waitcnt vmcnt(" #n ")" ::: "memory")
; #define G8_WAIT_L(n) asm volatile("s_waitcnt lgkmcnt(" #n ")" ::: "memory")
; #define G8_BAR __builtin_amdgcn_s_barrier()
; #define G8_SCHED __builtin_amdgcn_sched_barrier(0)
; template <class Epi, class Sched>
; __device__ __forceinline__ void gemm_phase(const int wv_, LAS unsigned char* lds, const int lda, const int ldb, const int K, const Sched& S, const Epi& E) {
;     ...
;       G8_BAR; G8_WAIT_L(0); G8_MMA(0, 1, At, B1); G8_BAR;
;       G8_LDA(At, 1, 1); G8_STAGE(G8_SA(1, 0), a3, voffA);
;       G8_BAR; G8_WAIT_L(0); G8_MMA(1, 0, At, B0); G8_BAR; G8_SCHED;
;       G8_STAGE(G8_SB(1, 1), b3 + hstepB, voffB);
;       G8_WAIT_V(6); G8_BAR; G8_MMA(1, 1, At, B1); G8_BAR;
	s_waitcnt lgkmcnt(0)
	s_waitcnt lgkmcnt(0)
	v_mfma_f32_16x16x32_bf16 v[128:131], v[142:145], v[190:193], v[128:131]
	v_mfma_f32_16x16x32_bf16 v[124:127], v[160:163], v[190:193], v[124:127]
	v_mfma_f32_16x16x32_bf16 v[112:115], v[142:145], v[198:201], v[112:115]
	v_mfma_f32_16x16x32_bf16 v[108:111], v[160:163], v[198:201], v[108:111]
	v_mfma_f32_16x16x32_bf16 v[96:99], v[142:145], v[206:209], v[96:99]
	v_mfma_f32_16x16x32_bf16 v[92:95], v[160:163], v[206:209], v[92:95]
	v_mfma_f32_16x16x32_bf16 v[80:83], v[142:145], v[214:217], v[80:83]
	v_mfma_f32_16x16x32_bf16 v[76:79], v[160:163], v[214:217], v[76:79]
	v_mfma_f32_16x16x32_bf16 v[128:131], v[156:159], v[194:197], v[128:131]
	v_mfma_f32_16x16x32_bf16 v[124:127], v[164:167], v[194:197], v[124:127]
	v_mfma_f32_16x16x32_bf16 v[112:115], v[156:159], v[202:205], v[112:115]
	v_mfma_f32_16x16x32_bf16 v[108:111], v[164:167], v[202:205], v[108:111]
	v_mfma_f32_16x16x32_bf16 v[96:99], v[156:159], v[210:213], v[96:99]
	v_mfma_f32_16x16x32_bf16 v[92:95], v[164:167], v[210:213], v[92:95]
	v_mfma_f32_16x16x32_bf16 v[80:83], v[156:159], v[218:221], v[80:83]
	v_mfma_f32_16x16x32_bf16 v[76:79], v[164:167], v[218:221], v[76:79]
	s_barrier
	s_add_i32 s30, 0, 0x1c000
	s_add_i32 s31, s51, s40
	v_add_u32_e32 v149, s30, v146
	v_lshl_add_u64 v[150:151], v[150:151], 0, s[90:91]
	s_mov_b32 m0, s31
	ds_read_b128 v[222:225], v149
	ds_read_b128 v[226:229], v149 offset:1024
	ds_read_b128 v[230:233], v149 offset:2048
	ds_read_b128 v[234:237], v149 offset:3072
	global_load_lds_dwordx4 v[150:151], off
	v_lshl_add_u64 v[150:151], v[168:169], 0, s[90:91]
	s_add_i32 m0, s31, 0x2000
	s_nop 0
	global_load_lds_dwordx4 v[150:151], off
	s_barrier
	s_waitcnt lgkmcnt(0)
	s_waitcnt lgkmcnt(0)
	v_mfma_f32_16x16x32_bf16 v[120:123], v[222:225], v[190:193], v[120:123]
	v_mfma_f32_16x16x32_bf16 v[116:119], v[230:233], v[190:193], v[116:119]
	v_mfma_f32_16x16x32_bf16 v[104:107], v[222:225], v[198:201], v[104:107]
	v_mfma_f32_16x16x32_bf16 v[100:103], v[230:233], v[198:201], v[100:103]
	v_mfma_f32_16x16x32_bf16 v[88:91], v[222:225], v[206:209], v[88:91]
	v_mfma_f32_16x16x32_bf16 v[84:87], v[230:233], v[206:209], v[84:87]
	v_mfma_f32_16x16x32_bf16 v[72:75], v[222:225], v[214:217], v[72:75]
	v_mfma_f32_16x16x32_bf16 v[68:71], v[230:233], v[214:217], v[68:71]
	v_mfma_f32_16x16x32_bf16 v[120:123], v[226:229], v[194:197], v[120:123]
	v_mfma_f32_16x16x32_bf16 v[116:119], v[234:237], v[194:197], v[116:119]
	v_mfma_f32_16x16x32_bf16 v[104:107], v[226:229], v[202:205], v[104:107]
	v_mfma_f32_16x16x32_bf16 v[100:103], v[234:237], v[202:205], v[100:103]
	v_mfma_f32_16x16x32_bf16 v[88:91], v[226:229], v[210:213], v[88:91]
	v_mfma_f32_16x16x32_bf16 v[84:87], v[234:237], v[210:213], v[84:87]
	v_mfma_f32_16x16x32_bf16 v[72:75], v[226:229], v[218:221], v[72:75]
	v_mfma_f32_16x16x32_bf16 v[68:71], v[234:237], v[218:221], v[68:71]
	s_mov_b32 m0, s43
	v_lshl_add_u64 v[150:151], v[238:239], 0, s[90:91]
	s_barrier
	ds_read_b128 v[190:193], v148 offset:49152
	ds_read_b128 v[194:197], v148 offset:50176
	ds_read_b128 v[198:201], v148 offset:51200
	ds_read_b128 v[202:205], v148 offset:52224
	ds_read_b128 v[206:209], v148 offset:53248
	ds_read_b128 v[210:213], v148 offset:54272
	ds_read_b128 v[214:217], v148 offset:55296
	ds_read_b128 v[218:221], v148 offset:56320
	global_load_lds_dwordx4 v[150:151], off
	v_lshl_add_u64 v[150:151], v[240:241], 0, s[90:91]
	s_mov_b32 m0, s46
	s_nop 0
	global_load_lds_dwordx4 v[150:151], off
	s_barrier
	s_waitcnt lgkmcnt(0)
	s_waitcnt lgkmcnt(0)
	v_mfma_f32_16x16x32_bf16 v[64:67], v[142:145], v[190:193], v[64:67]
	v_mfma_f32_16x16x32_bf16 v[60:63], v[160:163], v[190:193], v[60:63]
	v_mfma_f32_16x16x32_bf16 v[48:51], v[142:145], v[198:201], v[48:51]
	v_mfma_f32_16x16x32_bf16 v[44:47], v[160:163], v[198:201], v[44:47]
	v_mfma_f32_16x16x32_bf16 v[32:35], v[142:145], v[206:209], v[32:35]
	v_mfma_f32_16x16x32_bf16 v[28:31], v[160:163], v[206:209], v[28:31]
	v_mfma_f32_16x16x32_bf16 v[16:19], v[142:145], v[214:217], v[16:19]
	v_mfma_f32_16x16x32_bf16 v[12:15], v[160:163], v[214:217], v[12:15]
	v_mfma_f32_16x16x32_bf16 v[64:67], v[156:159], v[194:197], v[64:67]
	v_mfma_f32_16x16x32_bf16 v[60:63], v[164:167], v[194:197], v[60:63]
	v_mfma_f32_16x16x32_bf16 v[48:51], v[156:159], v[202:205], v[48:51]
	v_mfma_f32_16x16x32_bf16 v[44:47], v[164:167], v[202:205], v[44:47]
	v_mfma_f32_16x16x32_bf16 v[32:35], v[156:159], v[210:213], v[32:35]
	v_mfma_f32_16x16x32_bf16 v[28:31], v[164:167], v[210:213], v[28:31]
	v_mfma_f32_16x16x32_bf16 v[16:19], v[156:159], v[218:221], v[16:19]
	v_mfma_f32_16x16x32_bf16 v[12:15], v[164:167], v[218:221], v[12:15]
	s_barrier
	s_add_u32 s28, s28, 0x80080
	s_addc_u32 s29, s29, 0
	s_add_i32 s30, s30, s40
	v_lshl_add_u64 v[142:143], s[28:29], 0, v[132:133]
	s_mov_b32 m0, s30
	s_nop 0
	global_load_lds_dwordx4 v[142:143], off
	v_lshl_add_u64 v[142:143], s[28:29], 0, v[136:137]
	s_add_i32 m0, s30, 0x2000
	s_nop 0
	global_load_lds_dwordx4 v[142:143], off
	s_waitcnt vmcnt(6)
	s_barrier
	v_mfma_f32_16x16x32_bf16 v[56:59], v[222:225], v[190:193], v[56:59]
	v_mfma_f32_16x16x32_bf16 v[52:55], v[230:233], v[190:193], v[52:55]
	v_mfma_f32_16x16x32_bf16 v[40:43], v[222:225], v[198:201], v[40:43]
	v_mfma_f32_16x16x32_bf16 v[36:39], v[230:233], v[198:201], v[36:39]
	v_mfma_f32_16x16x32_bf16 v[24:27], v[222:225], v[206:209], v[24:27]
	v_mfma_f32_16x16x32_bf16 v[20:23], v[230:233], v[206:209], v[20:23]
	v_mfma_f32_16x16x32_bf16 v[8:11], v[222:225], v[214:217], v[8:11]
	v_mfma_f32_16x16x32_bf16 v[4:7], v[230:233], v[214:217], v[4:7]
	v_mfma_f32_16x16x32_bf16 v[56:59], v[226:229], v[194:197], v[56:59]
	v_mfma_f32_16x16x32_bf16 v[52:55], v[234:237], v[194:197], v[52:55]
	v_mfma_f32_16x16x32_bf16 v[40:43], v[226:229], v[202:205], v[40:43]
	v_mfma_f32_16x16x32_bf16 v[36:39], v[234:237], v[202:205], v[36:39]
	v_mfma_f32_16x16x32_bf16 v[24:27], v[226:229], v[210:213], v[24:27]
	v_mfma_f32_16x16x32_bf16 v[20:23], v[234:237], v[210:213], v[20:23]
	v_mfma_f32_16x16x32_bf16 v[8:11], v[226:229], v[218:221], v[8:11]
	v_mfma_f32_16x16x32_bf16 v[4:7], v[234:237], v[218:221], v[4:7]
	s_add_i32 s50, s50, 2
	s_add_u32 s26, s26, 0x100
	s_addc_u32 s27, s27, 0
	s_add_u32 s13, s13, 0x100
	s_addc_u32 s17, s17, 0
	s_cmp_gt_u32 s50, 29
	s_barrier
; __device__ __forceinline__ unsigned pk2(float lo, float hi) { f32x2n v = {lo, hi}; bf16x2n b = __builtin_convertvector(v, bf16x2n); return __builtin_bit_cast(unsigned, b); }
;   __device__ __forceinline__ bool operator()(f32x4 (&acc)[2][2][4][2], const Unit& u, int wr, int wc, int fr, int fq) const {
;     const int row0 = u.pm * BM + wr * 64 + fr, col0 = u.pn * BM + wc * 32 + 8 * fq;
; #pragma unroll
;     for (int ai = 0; ai < 2; ++ai)
; #pragma unroll
;       for (int m = 0; m < 4; ++m) { size_t off = (size_t)(row0 + ai * HALF + m * 16) * HID + col0; asm volatile("" : "+v"(off)); bf16_t* rowp = hid + off;
; #pragma unroll
;         for (int bj = 0; bj < 2; ++bj) { f32x4 v0 = acc[ai][bj][m][0], v1 = acc[ai][bj][m][1];
; #pragma unroll
;           for (int e = 0; e < 4; ++e) { float a = fmaxf(v0[e], 0.f), b = fmaxf(v1[e], 0.f); v0[e] = a * a; v1[e] = b * b; }
;           u32x4 w; w.x = pk2(v0[0], v0[1]); w.y = pk2(v0[2], v0[3]); w.z = pk2(v1[0], v1[1]); w.w = pk2(v1[2], v1[3]);
;           *(u32x4*)(rowp + bj * HALF) = w; } }
	s_cbranch_scc0 .LBB0_1173
	s_setprio 0
	v_lshl_add_u32 v150, s24, 8, v3
	v_max_f32_e32 v124, v124, v124
	v_max_f32_e32 v125, v125, v125
	v_lshl_or_b32 v144, s22, 8, v147
	v_ashrrev_i32_e32 v151, 31, v150
	v_max_f32_e32 v124, 0, v124
	v_max_f32_e32 v125, 0, v125
	v_ashrrev_i32_e32 v145, 31, v144
	v_lshlrev_b64 v[142:143], 13, v[150:151]
	v_pk_mul_f32 v[158:159], v[124:125], v[124:125]
	v_max_f32_e32 v125, v126, v126
	v_lshl_add_u64 v[142:143], v[142:143], 0, v[144:145]
	v_max_f32_e32 v128, v128, v128
	v_max_f32_e32 v129, v129, v129
	v_max_f32_e32 v124, v130, v130
	v_max_f32_e32 v126, 0, v125
	v_max_f32_e32 v125, v131, v131
	v_max_f32_e32 v127, v127, v127
	v_mov_b64_e32 v[156:157], v[142:143]
	v_max_f32_e32 v128, 0, v128
	v_max_f32_e32 v129, 0, v129
	v_max_f32_e32 v124, 0, v124
	v_max_f32_e32 v125, 0, v125
	v_max_f32_e32 v127, 0, v127
	v_pk_mul_f32 v[128:129], v[128:129], v[128:129]
	v_pk_mul_f32 v[130:131], v[124:125], v[124:125]
	v_pk_mul_f32 v[160:161], v[126:127], v[126:127]
	v_max_f32_e32 v116, v116, v116
	v_max_f32_e32 v117, v117, v117
	v_lshl_add_u64 v[156:157], v[156:157], 1, s[10:11]
	v_cvt_pk_bf16_f32 v124, v128, v129
	v_cvt_pk_bf16_f32 v125, v130, v131
	v_cvt_pk_bf16_f32 v126, v158, v159
	v_cvt_pk_bf16_f32 v127, v160, v161
	v_max_f32_e32 v116, 0, v116
	v_max_f32_e32 v117, 0, v117
	global_store_dwordx4 v[156:157], v[124:127], off
	v_max_f32_e32 v120, v120, v120
	v_max_f32_e32 v121, v121, v121
	v_pk_mul_f32 v[124:125], v[116:117], v[116:117]
	v_max_f32_e32 v117, v118, v118
	v_max_f32_e32 v116, v122, v122
	v_max_f32_e32 v118, 0, v117
	v_max_f32_e32 v117, v123, v123
	v_max_f32_e32 v119, v119, v119
	v_max_f32_e32 v120, 0, v120
	v_max_f32_e32 v121, 0, v121
	v_max_f32_e32 v116, 0, v116
	v_max_f32_e32 v117, 0, v117
	v_max_f32_e32 v119, 0, v119
	v_pk_mul_f32 v[120:121], v[120:121], v[120:121]
	v_pk_mul_f32 v[122:123], v[116:117], v[116:117]
	v_pk_mul_f32 v[126:127], v[118:119], v[118:119]
	v_cvt_pk_bf16_f32 v116, v120, v121
	v_cvt_pk_bf16_f32 v117, v122, v123
	v_cvt_pk_bf16_f32 v118, v124, v125
	v_cvt_pk_bf16_f32 v119, v126, v127
	v_max_f32_e32 v108, v108, v108
	v_max_f32_e32 v109, v109, v109
	global_store_dwordx4 v[156:157], v[116:119], off offset:256
	v_max_f32_e32 v108, 0, v108
	v_max_f32_e32 v109, 0, v109
	v_or_b32_e32 v116, 16, v150
	v_ashrrev_i32_e32 v117, 31, v116
	v_pk_mul_f32 v[118:119], v[108:109], v[108:109]
	v_max_f32_e32 v109, v110, v110
	v_lshlrev_b64 v[116:117], 13, v[116:117]
	v_max_f32_e32 v112, v112, v112
	v_max_f32_e32 v113, v113, v113
	v_max_f32_e32 v108, v114, v114
	v_max_f32_e32 v110, 0, v109
	v_max_f32_e32 v109, v115, v115
	v_max_f32_e32 v111, v111, v111
	v_lshl_add_u64 v[116:117], v[116:117], 0, v[144:145]
	v_max_f32_e32 v112, 0, v112
	v_max_f32_e32 v113, 0, v113
	v_max_f32_e32 v108, 0, v108
	v_max_f32_e32 v109, 0, v109
	v_max_f32_e32 v111, 0, v111
	v_pk_mul_f32 v[112:113], v[112:113], v[112:113]
	v_pk_mul_f32 v[114:115], v[108:109], v[108:109]
	v_pk_mul_f32 v[120:121], v[110:111], v[110:111]
	v_max_f32_e32 v100, v100, v100
	v_max_f32_e32 v101, v101, v101
	v_lshl_add_u64 v[116:117], v[116:117], 1, s[10:11]
	v_cvt_pk_bf16_f32 v108, v112, v113
	v_cvt_pk_bf16_f32 v109, v114, v115
	v_cvt_pk_bf16_f32 v110, v118, v119
	v_cvt_pk_bf16_f32 v111, v120, v121
	v_max_f32_e32 v100, 0, v100
	v_max_f32_e32 v101, 0, v101
	global_store_dwordx4 v[116:117], v[108:111], off
	v_max_f32_e32 v104, v104, v104
	v_max_f32_e32 v105, v105, v105
	v_pk_mul_f32 v[108:109], v[100:101], v[100:101]
	v_max_f32_e32 v101, v102, v102
	v_max_f32_e32 v100, v106, v106
	v_max_f32_e32 v102, 0, v101
	v_max_f32_e32 v101, v107, v107
	v_max_f32_e32 v103, v103, v103
	v_max_f32_e32 v104, 0, v104
	v_max_f32_e32 v105, 0, v105
	v_max_f32_e32 v100, 0, v100
	v_max_f32_e32 v101, 0, v101
	v_max_f32_e32 v103, 0, v103
	v_pk_mul_f32 v[104:105], v[104:105], v[104:105]
	v_pk_mul_f32 v[106:107], v[100:101], v[100:101]
	v_pk_mul_f32 v[110:111], v[102:103], v[102:103]
	v_cvt_pk_bf16_f32 v100, v104, v105
	v_cvt_pk_bf16_f32 v101, v106, v107
	v_cvt_pk_bf16_f32 v102, v108, v109
	v_cvt_pk_bf16_f32 v103, v110, v111
	v_max_f32_e32 v92, v92, v92
	v_max_f32_e32 v93, v93, v93
	global_store_dwordx4 v[116:117], v[100:103], off offset:256
	v_max_f32_e32 v92, 0, v92
	v_max_f32_e32 v93, 0, v93
	v_or_b32_e32 v100, 32, v150
	v_ashrrev_i32_e32 v101, 31, v100
	v_pk_mul_f32 v[102:103], v[92:93], v[92:93]
	v_max_f32_e32 v93, v94, v94
	v_lshlrev_b64 v[100:101], 13, v[100:101]
	v_max_f32_e32 v96, v96, v96
	v_max_f32_e32 v97, v97, v97
	v_max_f32_e32 v92, v98, v98
	v_max_f32_e32 v94, 0, v93
	v_max_f32_e32 v93, v99, v99
	v_max_f32_e32 v95, v95, v95
	v_lshl_add_u64 v[100:101], v[100:101], 0, v[144:145]
	v_max_f32_e32 v96, 0, v96
	v_max_f32_e32 v97, 0, v97
	v_max_f32_e32 v92, 0, v92
	v_max_f32_e32 v93, 0, v93
	v_max_f32_e32 v95, 0, v95
	v_pk_mul_f32 v[96:97], v[96:97], v[96:97]
	v_pk_mul_f32 v[98:99], v[92:93], v[92:93]
	v_pk_mul_f32 v[104:105], v[94:95], v[94:95]
	v_max_f32_e32 v84, v84, v84
	v_max_f32_e32 v85, v85, v85
	v_lshl_add_u64 v[100:101], v[100:101], 1, s[10:11]
	v_cvt_pk_bf16_f32 v92, v96, v97
	v_cvt_pk_bf16_f32 v93, v98, v99
	v_cvt_pk_bf16_f32 v94, v102, v103
	v_cvt_pk_bf16_f32 v95, v104, v105
	v_max_f32_e32 v84, 0, v84
	v_max_f32_e32 v85, 0, v85
	global_store_dwordx4 v[100:101], v[92:95], off
	v_max_f32_e32 v88, v88, v88
	v_max_f32_e32 v89, v89, v89
	v_pk_mul_f32 v[92:93], v[84:85], v[84:85]
	v_max_f32_e32 v85, v86, v86
	v_max_f32_e32 v84, v90, v90
	v_max_f32_e32 v86, 0, v85
	v_max_f32_e32 v85, v91, v91
	v_max_f32_e32 v87, v87, v87
	v_max_f32_e32 v88, 0, v88
	v_max_f32_e32 v89, 0, v89
	v_max_f32_e32 v84, 0, v84
	v_max_f32_e32 v85, 0, v85
	v_max_f32_e32 v87, 0, v87
	v_pk_mul_f32 v[88:89], v[88:89], v[88:89]
; __device__ __forceinline__ unsigned pk2(float lo, float hi) { f32x2n v = {lo, hi}; bf16x2n b = __builtin_convertvector(v, bf16x2n); return __builtin_bit_cast(unsigned, b); }
;   __device__ __forceinline__ bool operator()(f32x4 (&acc)[2][2][4][2], const Unit& u, int wr, int wc, int fr, int fq) const {
;     const int row0 = u.pm * BM + wr * 64 + fr, col0 = u.pn * BM + wc * 32 + 8 * fq;
; #pragma unroll
;     for (int ai = 0; ai < 2; ++ai)
; #pragma unroll
;       for (int m = 0; m < 4; ++m) { size_t off = (size_t)(row0 + ai * HALF + m * 16) * HID + col0; asm volatile("" : "+v"(off)); bf16_t* rowp = hid + off;
; #pragma unroll
;         for (int bj = 0; bj < 2; ++bj) { f32x4 v0 = acc[ai][bj][m][0], v1 = acc[ai][bj][m][1];
; #pragma unroll
;           for (int e = 0; e < 4; ++e) { float a = fmaxf(v0[e], 0.f), b = fmaxf(v1[e], 0.f); v0[e] = a * a; v1[e] = b * b; }
;           u32x4 w; w.x = pk2(v0[0], v0[1]); w.y = pk2(v0[2], v0[3]); w.z = pk2(v1[0], v1[1]); w.w = pk2(v1[2], v1[3]);
;           *(u32x4*)(rowp + bj * HALF) = w; } }
	v_pk_mul_f32 v[90:91], v[84:85], v[84:85]
	v_pk_mul_f32 v[94:95], v[86:87], v[86:87]
	v_cvt_pk_bf16_f32 v84, v88, v89
	v_cvt_pk_bf16_f32 v85, v90, v91
	v_cvt_pk_bf16_f32 v86, v92, v93
	v_cvt_pk_bf16_f32 v87, v94, v95
	v_max_f32_e32 v76, v76, v76
	v_max_f32_e32 v77, v77, v77
	global_store_dwordx4 v[100:101], v[84:87], off offset:256
	v_max_f32_e32 v76, 0, v76
	v_max_f32_e32 v77, 0, v77
	v_or_b32_e32 v84, 48, v150
	v_ashrrev_i32_e32 v85, 31, v84
	v_pk_mul_f32 v[86:87], v[76:77], v[76:77]
	v_max_f32_e32 v77, v78, v78
	v_lshlrev_b64 v[84:85], 13, v[84:85]
	v_max_f32_e32 v80, v80, v80
	v_max_f32_e32 v81, v81, v81
	v_max_f32_e32 v76, v82, v82
	v_max_f32_e32 v78, 0, v77
	v_max_f32_e32 v77, v83, v83
	v_max_f32_e32 v79, v79, v79
	v_lshl_add_u64 v[84:85], v[84:85], 0, v[144:145]
	v_max_f32_e32 v80, 0, v80
	v_max_f32_e32 v81, 0, v81
	v_max_f32_e32 v76, 0, v76
	v_max_f32_e32 v77, 0, v77
	v_max_f32_e32 v79, 0, v79
	v_pk_mul_f32 v[80:81], v[80:81], v[80:81]
	v_pk_mul_f32 v[82:83], v[76:77], v[76:77]
	v_pk_mul_f32 v[88:89], v[78:79], v[78:79]
	v_max_f32_e32 v68, v68, v68
	v_max_f32_e32 v69, v69, v69
	v_lshl_add_u64 v[84:85], v[84:85], 1, s[10:11]
	v_cvt_pk_bf16_f32 v76, v80, v81
	v_cvt_pk_bf16_f32 v77, v82, v83
	v_cvt_pk_bf16_f32 v78, v86, v87
	v_cvt_pk_bf16_f32 v79, v88, v89
	v_max_f32_e32 v68, 0, v68
	v_max_f32_e32 v69, 0, v69
	global_store_dwordx4 v[84:85], v[76:79], off
	v_max_f32_e32 v72, v72, v72
	v_max_f32_e32 v73, v73, v73
	v_pk_mul_f32 v[76:77], v[68:69], v[68:69]
	v_max_f32_e32 v69, v70, v70
	v_max_f32_e32 v68, v74, v74
	v_max_f32_e32 v70, 0, v69
	v_max_f32_e32 v69, v75, v75
	v_max_f32_e32 v71, v71, v71
	v_max_f32_e32 v72, 0, v72
	v_max_f32_e32 v73, 0, v73
	v_max_f32_e32 v68, 0, v68
	v_max_f32_e32 v69, 0, v69
	v_max_f32_e32 v71, 0, v71
	v_pk_mul_f32 v[72:73], v[72:73], v[72:73]
	v_pk_mul_f32 v[74:75], v[68:69], v[68:69]
	v_pk_mul_f32 v[78:79], v[70:71], v[70:71]
	v_max_f32_e32 v60, v60, v60
	v_max_f32_e32 v61, v61, v61
	v_cvt_pk_bf16_f32 v68, v72, v73
	v_cvt_pk_bf16_f32 v69, v74, v75
	v_cvt_pk_bf16_f32 v70, v76, v77
	v_cvt_pk_bf16_f32 v71, v78, v79
	v_max_f32_e32 v60, 0, v60
	v_max_f32_e32 v61, 0, v61
	global_store_dwordx4 v[84:85], v[68:71], off offset:256
	s_mov_b64 s[26:27], 0x100000
	v_max_f32_e32 v64, v64, v64
	v_pk_mul_f32 v[70:71], v[60:61], v[60:61]
	v_max_f32_e32 v61, v62, v62
	v_max_f32_e32 v65, v65, v65
	v_max_f32_e32 v60, v66, v66
	v_max_f32_e32 v62, 0, v61
	v_max_f32_e32 v61, v67, v67
	v_max_f32_e32 v63, v63, v63
	v_lshl_add_u64 v[68:69], v[142:143], 0, s[26:27]
	v_max_f32_e32 v64, 0, v64
	v_max_f32_e32 v65, 0, v65
	v_max_f32_e32 v60, 0, v60
	v_max_f32_e32 v61, 0, v61
	v_max_f32_e32 v63, 0, v63
	v_pk_mul_f32 v[64:65], v[64:65], v[64:65]
	v_pk_mul_f32 v[66:67], v[60:61], v[60:61]
	v_pk_mul_f32 v[72:73], v[62:63], v[62:63]
	v_max_f32_e32 v52, v52, v52
	v_max_f32_e32 v53, v53, v53
	v_lshl_add_u64 v[68:69], v[68:69], 1, s[10:11]
	v_cvt_pk_bf16_f32 v60, v64, v65
	v_cvt_pk_bf16_f32 v61, v66, v67
	v_cvt_pk_bf16_f32 v62, v70, v71
	v_cvt_pk_bf16_f32 v63, v72, v73
	v_max_f32_e32 v52, 0, v52
	v_max_f32_e32 v53, 0, v53
	global_store_dwordx4 v[68:69], v[60:63], off
	v_max_f32_e32 v56, v56, v56
	v_max_f32_e32 v57, v57, v57
	v_pk_mul_f32 v[60:61], v[52:53], v[52:53]
	v_max_f32_e32 v53, v54, v54
	v_max_f32_e32 v52, v58, v58
	v_max_f32_e32 v54, 0, v53
	v_max_f32_e32 v53, v59, v59
	v_max_f32_e32 v55, v55, v55
	v_max_f32_e32 v56, 0, v56
	v_max_f32_e32 v57, 0, v57
	v_max_f32_e32 v52, 0, v52
	v_max_f32_e32 v53, 0, v53
	v_max_f32_e32 v55, 0, v55
	v_pk_mul_f32 v[56:57], v[56:57], v[56:57]
	v_pk_mul_f32 v[58:59], v[52:53], v[52:53]
	v_pk_mul_f32 v[62:63], v[54:55], v[54:55]
	v_max_f32_e32 v44, v44, v44
	v_max_f32_e32 v45, v45, v45
	v_cvt_pk_bf16_f32 v52, v56, v57
	v_cvt_pk_bf16_f32 v53, v58, v59
	v_cvt_pk_bf16_f32 v54, v60, v61
	v_cvt_pk_bf16_f32 v55, v62, v63
	v_max_f32_e32 v44, 0, v44
	v_max_f32_e32 v45, 0, v45
	global_store_dwordx4 v[68:69], v[52:55], off offset:256
	s_mov_b64 s[26:27], 0x120000
	v_max_f32_e32 v48, v48, v48
	v_pk_mul_f32 v[54:55], v[44:45], v[44:45]
	v_max_f32_e32 v45, v46, v46
	v_max_f32_e32 v49, v49, v49
	v_max_f32_e32 v44, v50, v50
	v_max_f32_e32 v46, 0, v45
	v_max_f32_e32 v45, v51, v51
	v_max_f32_e32 v47, v47, v47
	v_lshl_add_u64 v[52:53], v[142:143], 0, s[26:27]
	v_max_f32_e32 v48, 0, v48
	v_max_f32_e32 v49, 0, v49
	v_max_f32_e32 v44, 0, v44
	v_max_f32_e32 v45, 0, v45
	v_max_f32_e32 v47, 0, v47
	v_pk_mul_f32 v[48:49], v[48:49], v[48:49]
	v_pk_mul_f32 v[50:51], v[44:45], v[44:45]
	v_pk_mul_f32 v[56:57], v[46:47], v[46:47]
	v_max_f32_e32 v36, v36, v36
	v_max_f32_e32 v37, v37, v37
	v_lshl_add_u64 v[52:53], v[52:53], 1, s[10:11]
; __device__ __forceinline__ unsigned pk2(float lo, float hi) { f32x2n v = {lo, hi}; bf16x2n b = __builtin_convertvector(v, bf16x2n); return __builtin_bit_cast(unsigned, b); }
; #define G8_WAIT_V(n) asm volatile("s_waitcnt vmcnt(" #n ")" ::: "memory")
; template <class Epi, class Sched>
; __device__ __forceinline__ void gemm_phase(const int wv_, LAS unsigned char* lds, const int lda, const int ldb, const int K, const Sched& S, const Epi& E) {
;     ...
;     const bool zero = E(acc, cur, wr, wc, fr, fq);
;     if (!has_next) break;
;     if (zero) {
; #pragma unroll
;       for (int a = 0; a < 2; ++a)
; #pragma unroll
;         for (int b = 0; b < 2; ++b)
; #pragma unroll
;           for (int m = 0; m < 4; ++m)
; #pragma unroll
;             for (int n = 0; n < 2; ++n) acc[a][b][m][n] = (f32x4){0.f, 0.f, 0.f, 0.f};
;     }
;     cur = nxt; cA = nA; cB = nB; ++ui;
;   }
;   G8_WAIT_V(0);
;   __device__ __forceinline__ bool operator()(f32x4 (&acc)[2][2][4][2], const Unit& u, int wr, int wc, int fr, int fq) const {
;     ...
;     for (int ai = 0; ai < 2; ++ai)
; #pragma unroll
;       for (int m = 0; m < 4; ++m) { size_t off = (size_t)(row0 + ai * HALF + m * 16) * HID + col0; asm volatile("" : "+v"(off)); bf16_t* rowp = hid + off;
; #pragma unroll
;         for (int bj = 0; bj < 2; ++bj) { f32x4 v0 = acc[ai][bj][m][0], v1 = acc[ai][bj][m][1];
; #pragma unroll
;           for (int e = 0; e < 4; ++e) { float a = fmaxf(v0[e], 0.f), b = fmaxf(v1[e], 0.f); v0[e] = a * a; v1[e] = b * b; }
;           u32x4 w; w.x = pk2(v0[0], v0[1]); w.y = pk2(v0[2], v0[3]); w.z = pk2(v1[0], v1[1]); w.w = pk2(v1[2], v1[3]);
;           *(u32x4*)(rowp + bj * HALF) = w; } }
	v_cvt_pk_bf16_f32 v44, v48, v49
	v_cvt_pk_bf16_f32 v45, v50, v51
	v_cvt_pk_bf16_f32 v46, v54, v55
	v_cvt_pk_bf16_f32 v47, v56, v57
	v_max_f32_e32 v36, 0, v36
	v_max_f32_e32 v37, 0, v37
	global_store_dwordx4 v[52:53], v[44:47], off
	v_max_f32_e32 v40, v40, v40
	v_max_f32_e32 v41, v41, v41
	v_pk_mul_f32 v[44:45], v[36:37], v[36:37]
	v_max_f32_e32 v37, v38, v38
	v_max_f32_e32 v36, v42, v42
	v_max_f32_e32 v38, 0, v37
	v_max_f32_e32 v37, v43, v43
	v_max_f32_e32 v39, v39, v39
	v_max_f32_e32 v40, 0, v40
	v_max_f32_e32 v41, 0, v41
	v_max_f32_e32 v36, 0, v36
	v_max_f32_e32 v37, 0, v37
	v_max_f32_e32 v39, 0, v39
	v_pk_mul_f32 v[40:41], v[40:41], v[40:41]
	v_pk_mul_f32 v[42:43], v[36:37], v[36:37]
	v_pk_mul_f32 v[46:47], v[38:39], v[38:39]
	v_max_f32_e32 v28, v28, v28
	v_max_f32_e32 v29, v29, v29
	v_cvt_pk_bf16_f32 v36, v40, v41
	v_cvt_pk_bf16_f32 v37, v42, v43
	v_cvt_pk_bf16_f32 v38, v44, v45
	v_cvt_pk_bf16_f32 v39, v46, v47
	v_max_f32_e32 v28, 0, v28
	v_max_f32_e32 v29, 0, v29
	global_store_dwordx4 v[52:53], v[36:39], off offset:256
	s_mov_b64 s[26:27], 0x140000
	v_max_f32_e32 v32, v32, v32
	v_pk_mul_f32 v[38:39], v[28:29], v[28:29]
	v_max_f32_e32 v29, v30, v30
	v_max_f32_e32 v33, v33, v33
	v_max_f32_e32 v28, v34, v34
	v_max_f32_e32 v30, 0, v29
	v_max_f32_e32 v29, v35, v35
	v_max_f32_e32 v31, v31, v31
	v_lshl_add_u64 v[36:37], v[142:143], 0, s[26:27]
	v_max_f32_e32 v32, 0, v32
	v_max_f32_e32 v33, 0, v33
	v_max_f32_e32 v28, 0, v28
	v_max_f32_e32 v29, 0, v29
	v_max_f32_e32 v31, 0, v31
	v_pk_mul_f32 v[32:33], v[32:33], v[32:33]
	v_pk_mul_f32 v[34:35], v[28:29], v[28:29]
	v_pk_mul_f32 v[40:41], v[30:31], v[30:31]
	v_max_f32_e32 v20, v20, v20
	v_max_f32_e32 v21, v21, v21
	v_lshl_add_u64 v[36:37], v[36:37], 1, s[10:11]
	v_cvt_pk_bf16_f32 v28, v32, v33
	v_cvt_pk_bf16_f32 v29, v34, v35
	v_cvt_pk_bf16_f32 v30, v38, v39
	v_cvt_pk_bf16_f32 v31, v40, v41
	v_max_f32_e32 v20, 0, v20
	v_max_f32_e32 v21, 0, v21
	global_store_dwordx4 v[36:37], v[28:31], off
	v_max_f32_e32 v24, v24, v24
	v_max_f32_e32 v25, v25, v25
	v_pk_mul_f32 v[28:29], v[20:21], v[20:21]
	v_max_f32_e32 v21, v22, v22
	v_max_f32_e32 v20, v26, v26
	v_max_f32_e32 v22, 0, v21
	v_max_f32_e32 v21, v27, v27
	v_max_f32_e32 v23, v23, v23
	v_max_f32_e32 v24, 0, v24
	v_max_f32_e32 v25, 0, v25
	v_max_f32_e32 v20, 0, v20
	v_max_f32_e32 v21, 0, v21
	v_max_f32_e32 v23, 0, v23
	v_pk_mul_f32 v[24:25], v[24:25], v[24:25]
	v_pk_mul_f32 v[26:27], v[20:21], v[20:21]
	v_pk_mul_f32 v[30:31], v[22:23], v[22:23]
	v_max_f32_e32 v12, v12, v12
	v_max_f32_e32 v13, v13, v13
	v_cvt_pk_bf16_f32 v20, v24, v25
	v_cvt_pk_bf16_f32 v21, v26, v27
	v_cvt_pk_bf16_f32 v22, v28, v29
	v_cvt_pk_bf16_f32 v23, v30, v31
	v_max_f32_e32 v12, 0, v12
	v_max_f32_e32 v13, 0, v13
	global_store_dwordx4 v[36:37], v[20:23], off offset:256
	s_mov_b64 s[26:27], 0x160000
	v_max_f32_e32 v16, v16, v16
	v_pk_mul_f32 v[22:23], v[12:13], v[12:13]
	v_max_f32_e32 v13, v14, v14
	v_max_f32_e32 v17, v17, v17
	v_max_f32_e32 v12, v18, v18
	v_max_f32_e32 v14, 0, v13
	v_max_f32_e32 v13, v19, v19
	v_max_f32_e32 v15, v15, v15
	v_lshl_add_u64 v[20:21], v[142:143], 0, s[26:27]
	v_max_f32_e32 v16, 0, v16
	v_max_f32_e32 v17, 0, v17
	v_max_f32_e32 v12, 0, v12
	v_max_f32_e32 v13, 0, v13
	v_max_f32_e32 v15, 0, v15
	v_pk_mul_f32 v[16:17], v[16:17], v[16:17]
	v_pk_mul_f32 v[18:19], v[12:13], v[12:13]
	v_pk_mul_f32 v[24:25], v[14:15], v[14:15]
	v_max_f32_e32 v4, v4, v4
	v_max_f32_e32 v5, v5, v5
	v_lshl_add_u64 v[20:21], v[20:21], 1, s[10:11]
	v_cvt_pk_bf16_f32 v12, v16, v17
	v_cvt_pk_bf16_f32 v13, v18, v19
	v_cvt_pk_bf16_f32 v14, v22, v23
	v_cvt_pk_bf16_f32 v15, v24, v25
	v_max_f32_e32 v4, 0, v4
	v_max_f32_e32 v5, 0, v5
	global_store_dwordx4 v[20:21], v[12:15], off
	v_max_f32_e32 v8, v8, v8
	v_max_f32_e32 v9, v9, v9
	v_pk_mul_f32 v[12:13], v[4:5], v[4:5]
	v_max_f32_e32 v5, v6, v6
	v_max_f32_e32 v4, v10, v10
	v_max_f32_e32 v6, 0, v5
	v_max_f32_e32 v5, v11, v11
	v_max_f32_e32 v7, v7, v7
	v_max_f32_e32 v8, 0, v8
	v_max_f32_e32 v9, 0, v9
	v_max_f32_e32 v4, 0, v4
	v_max_f32_e32 v5, 0, v5
	v_max_f32_e32 v7, 0, v7
	v_pk_mul_f32 v[8:9], v[8:9], v[8:9]
	v_pk_mul_f32 v[10:11], v[4:5], v[4:5]
	v_pk_mul_f32 v[14:15], v[6:7], v[6:7]
	v_cvt_pk_bf16_f32 v4, v8, v9
	v_cvt_pk_bf16_f32 v5, v10, v11
	v_cvt_pk_bf16_f32 v6, v12, v13
	v_cvt_pk_bf16_f32 v7, v14, v15
	s_and_b64 vcc, exec, s[8:9]
	s_mov_b32 s22, s12
	s_mov_b32 s24, s16
	s_mov_b64 s[28:29], s[20:21]
	s_mov_b64 s[26:27], s[18:19]
	global_store_dwordx4 v[20:21], v[4:7], off offset:256
	s_cbranch_vccz .LBB0_1168
	s_waitcnt vmcnt(0)
	s_cmpk_gt_u32 s15, 0xff
	s_cbranch_scc1 .LBB0_1177
	s_barrier

; #define G8_STAGE(bufoff, gbase, voff) do { _Pragma("unroll") for (int _i = 0; _i < 2; ++_i) \
;     __builtin_amdgcn_global_load_lds((const unsigned*)((const char*)(gbase) + (voff)[_i]), (LAS unsigned*)(lds + (bufoff) + ldsw + _i * 8192), 16, 0, 0); } while (0)
; #define G8_LDA(dst, b, h) do { _Pragma("unroll") for (int m = 0; m < 4; ++m) _Pragma("unroll") for (int k = 0; k < 2; ++k) dst[m][k] = *(const LAS bf16x8*)(lds + G8_SA(b, h) + aoff + m * 2048 + k * 1024); } while (0)
; #define G8_LDB(dst, b, h) do { _Pragma("unroll") for (int n = 0; n < 2; ++n) _Pragma("unroll") for (int k = 0; k < 2; ++k) dst[n][k] = *(const LAS bf16x8*)(lds + G8_SB(b, h) + boff + n * 2048 + k * 1024); } while (0)
; #define G8_MMA(ai, bj, At, Bt) do { __builtin_amdgcn_s_setprio(1); _Pragma("unroll") for (int m = 0; m < 4; ++m) _Pragma("unroll") for (int n = 0; n < 2; ++n) _Pragma("unroll") for (int k = 0; k < 2; ++k) \
;     acc[ai][bj][m][n] = __builtin_amdgcn_mfma_f32_16x16x32_bf16(Bt[n][k], At[m][k], acc[ai][bj][m][n], 0, 0, 0); __builtin_amdgcn_s_setprio(0); } while (0)
; #define G8_WAIT_L(n) asm volatile("s_waitcnt lgkmcnt(" #n ")" ::: "memory")
; #define G8_BAR __builtin_amdgcn_s_barrier()
; #define G8_SCHED __builtin_amdgcn_sched_barrier(0)
; template <class Epi, class Sched>
; __device__ __forceinline__ void gemm_phase(const int wv_, LAS unsigned char* lds, const int lda, const int ldb, const int K, const Sched& S, const Epi& E) {
;     ...
;     const bool has_next = S.next(ui + 1, nxt);
;     const char* nA = has_next ? nxt.a : cA; const char* nB = has_next ? nxt.b : cB;
;     const int nt = cur.nt;
;     for (int t = 0; t < nt; t += 2) {
;       const bool last = (t == nt - 2);
;       const char* a1 = cA + (size_t)(t + 1) * kstep;
;       const char* a2 = last ? nA : cA + (size_t)(t + 2) * kstep; const char* b2 = last ? nB : cB + (size_t)(t + 2) * kstep;
;       const char* a3 = a2 + kstep; const char* b3 = b2 + kstep;
;       G8_LDB(B0, 0, 0); G8_SCHED; G8_LDA(At, 0, 0); G8_STAGE(G8_SA(1, 1), a1 + hstepA, voffA);
;       G8_WAIT_L(8); G8_BAR; G8_WAIT_L(0); G8_MMA(0, 0, At, B0); G8_BAR; G8_SCHED;
.LBB0_1245:
	s_add_u32 s26, s26, 0x200080
	s_addc_u32 s27, s27, 0
	s_add_u32 s9, s28, 0x100
	v_mov_b32_e32 v4, 0
	s_addc_u32 s11, s29, 0
	v_readlane_b32 s19, v242, 62
	s_cmp_eq_u32 s50, 3
	s_cselect_b32 s19, s19, 0
	s_cmp_lg_u32 s19, 0
	s_cselect_b32 s19, 0x6e, -2
	v_mov_b32_e32 v5, v4
	v_mov_b32_e32 v6, v4
	v_mov_b32_e32 v7, v4
	v_mov_b32_e32 v8, v4
	v_mov_b32_e32 v9, v4
	v_mov_b32_e32 v10, v4
	v_mov_b32_e32 v11, v4
	v_mov_b32_e32 v20, v4
	v_mov_b32_e32 v21, v4
	v_mov_b32_e32 v22, v4
	v_mov_b32_e32 v23, v4
	v_mov_b32_e32 v24, v4
	v_mov_b32_e32 v25, v4
	v_mov_b32_e32 v26, v4
	v_mov_b32_e32 v27, v4
	v_mov_b32_e32 v36, v4
	v_mov_b32_e32 v37, v4
	v_mov_b32_e32 v38, v4
	v_mov_b32_e32 v39, v4
	v_mov_b32_e32 v40, v4
	v_mov_b32_e32 v41, v4
	v_mov_b32_e32 v42, v4
	v_mov_b32_e32 v43, v4
	v_mov_b32_e32 v52, v4
	v_mov_b32_e32 v53, v4
	v_mov_b32_e32 v54, v4
	v_mov_b32_e32 v55, v4
	v_mov_b32_e32 v56, v4
	v_mov_b32_e32 v57, v4
	v_mov_b32_e32 v58, v4
	v_mov_b32_e32 v59, v4
	v_mov_b32_e32 v12, v4
	v_mov_b32_e32 v13, v4
	v_mov_b32_e32 v14, v4
	v_mov_b32_e32 v15, v4
	v_mov_b32_e32 v16, v4
	v_mov_b32_e32 v17, v4
	v_mov_b32_e32 v18, v4
	v_mov_b32_e32 v19, v4
	v_mov_b32_e32 v28, v4
	v_mov_b32_e32 v29, v4
	v_mov_b32_e32 v30, v4
	v_mov_b32_e32 v31, v4
	v_mov_b32_e32 v32, v4
	v_mov_b32_e32 v33, v4
	v_mov_b32_e32 v34, v4
	v_mov_b32_e32 v35, v4
	v_mov_b32_e32 v44, v4
	v_mov_b32_e32 v45, v4
	v_mov_b32_e32 v46, v4
	v_mov_b32_e32 v47, v4
	v_mov_b32_e32 v48, v4
	v_mov_b32_e32 v49, v4
	v_mov_b32_e32 v50, v4
	v_mov_b32_e32 v51, v4
	v_mov_b32_e32 v60, v4
	v_mov_b32_e32 v61, v4
	v_mov_b32_e32 v62, v4
	v_mov_b32_e32 v63, v4
	v_mov_b32_e32 v64, v4
	v_mov_b32_e32 v65, v4
	v_mov_b32_e32 v66, v4
	v_mov_b32_e32 v67, v4
	v_mov_b32_e32 v84, v4
	v_mov_b32_e32 v85, v4
	v_mov_b32_e32 v86, v4
	v_mov_b32_e32 v87, v4
	v_mov_b32_e32 v88, v4
	v_mov_b32_e32 v89, v4
	v_mov_b32_e32 v90, v4
	v_mov_b32_e32 v91, v4
	v_mov_b32_e32 v100, v4
	v_mov_b32_e32 v101, v4
	v_mov_b32_e32 v102, v4
	v_mov_b32_e32 v103, v4
	v_mov_b32_e32 v104, v4
	v_mov_b32_e32 v105, v4
	v_mov_b32_e32 v106, v4
	v_mov_b32_e32 v107, v4
	v_mov_b32_e32 v116, v4
	v_mov_b32_e32 v117, v4
	v_mov_b32_e32 v118, v4
	v_mov_b32_e32 v119, v4
	v_mov_b32_e32 v120, v4
	v_mov_b32_e32 v121, v4
	v_mov_b32_e32 v122, v4
	v_mov_b32_e32 v123, v4
	v_mov_b32_e32 v132, v4
	v_mov_b32_e32 v133, v4
	v_mov_b32_e32 v134, v4
	v_mov_b32_e32 v135, v4
	v_mov_b32_e32 v136, v4
	v_mov_b32_e32 v137, v4
	v_mov_b32_e32 v138, v4
	v_mov_b32_e32 v139, v4
	v_mov_b32_e32 v92, v4
	v_mov_b32_e32 v93, v4
	v_mov_b32_e32 v94, v4
	v_mov_b32_e32 v95, v4
	v_mov_b32_e32 v96, v4
	v_mov_b32_e32 v97, v4
	v_mov_b32_e32 v98, v4
	v_mov_b32_e32 v99, v4
	v_mov_b32_e32 v108, v4
	v_mov_b32_e32 v109, v4
	v_mov_b32_e32 v110, v4
	v_mov_b32_e32 v111, v4
	v_mov_b32_e32 v112, v4
	v_mov_b32_e32 v113, v4
	v_mov_b32_e32 v114, v4
	v_mov_b32_e32 v115, v4
	v_mov_b32_e32 v124, v4
	v_mov_b32_e32 v125, v4
	v_mov_b32_e32 v126, v4
	v_mov_b32_e32 v127, v4
	v_mov_b32_e32 v128, v4
	v_mov_b32_e32 v129, v4
	v_mov_b32_e32 v130, v4
	v_mov_b32_e32 v131, v4
	v_mov_b32_e32 v140, v4
	v_mov_b32_e32 v141, v4
	v_mov_b32_e32 v142, v4
	v_mov_b32_e32 v143, v4
	v_mov_b32_e32 v144, v4
	v_mov_b32_e32 v145, v4
	v_mov_b32_e32 v146, v4
	v_mov_b32_e32 v147, v4
	s_cmp_ge_u32 s72, 0x100
	s_cbranch_scc0 .Lg5_noprio
	s_setprio 1
.Lg5_noprio:
.LBB0_1246:
	s_add_u32 s21, s26, 0xffe00080
	s_addc_u32 s28, s27, -1
	s_add_i32 s51, 0, 0x10000
	v_add_u32_e32 v80, s51, v168
	ds_read_b128 v[68:71], v80
	ds_read_b128 v[72:75], v80 offset:1024
	ds_read_b128 v[76:79], v80 offset:2048
	ds_read_b128 v[80:83], v80 offset:3072
	s_cmpk_eq_i32 s19, 0x7c
	s_cselect_b32 s31, s23, s28
	s_cselect_b32 s30, s22, s21
	s_cselect_b32 s29, s25, s11
	s_cselect_b32 s28, s24, s9
	v_lshl_add_u64 v[166:167], s[26:27], 0, v[150:151]
	s_add_i32 m0, s40, 0xc000
	ds_read_b128 v[158:161], v189
	ds_read_b128 v[162:165], v189 offset:1024
	ds_read_b128 v[190:193], v189 offset:2048
	ds_read_b128 v[194:197], v189 offset:3072
	ds_read_b128 v[198:201], v189 offset:4096
	ds_read_b128 v[202:205], v189 offset:5120
	ds_read_b128 v[206:209], v189 offset:6144
	ds_read_b128 v[210:213], v189 offset:7168
	global_load_lds_dwordx4 v[166:167], off
	v_lshl_add_u64 v[166:167], s[26:27], 0, v[156:157]
	s_add_i32 m0, s40, 0xe000
	s_nop 0
	global_load_lds_dwordx4 v[166:167], off
	s_waitcnt lgkmcnt(8)
	s_barrier
	s_waitcnt lgkmcnt(0)
	s_waitcnt lgkmcnt(0)
	v_mfma_f32_16x16x32_bf16 v[144:147], v[68:71], v[158:161], v[144:147]
	v_mfma_f32_16x16x32_bf16 v[140:143], v[76:79], v[158:161], v[140:143]
	v_mfma_f32_16x16x32_bf16 v[128:131], v[68:71], v[190:193], v[128:131]
	v_mfma_f32_16x16x32_bf16 v[124:127], v[76:79], v[190:193], v[124:127]
	v_mfma_f32_16x16x32_bf16 v[112:115], v[68:71], v[198:201], v[112:115]
	v_mfma_f32_16x16x32_bf16 v[108:111], v[76:79], v[198:201], v[108:111]
	v_mfma_f32_16x16x32_bf16 v[96:99], v[68:71], v[206:209], v[96:99]
	v_mfma_f32_16x16x32_bf16 v[92:95], v[76:79], v[206:209], v[92:95]
	v_mfma_f32_16x16x32_bf16 v[144:147], v[72:75], v[162:165], v[144:147]
	v_mfma_f32_16x16x32_bf16 v[140:143], v[80:83], v[162:165], v[140:143]
	v_mfma_f32_16x16x32_bf16 v[128:131], v[72:75], v[194:197], v[128:131]
	v_mfma_f32_16x16x32_bf16 v[124:127], v[80:83], v[194:197], v[124:127]
	v_mfma_f32_16x16x32_bf16 v[112:115], v[72:75], v[202:205], v[112:115]
	v_mfma_f32_16x16x32_bf16 v[108:111], v[80:83], v[202:205], v[108:111]
	v_mfma_f32_16x16x32_bf16 v[96:99], v[72:75], v[210:213], v[96:99]
	v_mfma_f32_16x16x32_bf16 v[92:95], v[80:83], v[210:213], v[92:95]
	s_barrier
; #define G8_STAGE(bufoff, gbase, voff) do { _Pragma("unroll") for (int _i = 0; _i < 2; ++_i) \
;     __builtin_amdgcn_global_load_lds((const unsigned*)((const char*)(gbase) + (voff)[_i]), (LAS unsigned*)(lds + (bufoff) + ldsw + _i * 8192), 16, 0, 0); } while (0)
; #define G8_LDA(dst, b, h) do { _Pragma("unroll") for (int m = 0; m < 4; ++m) _Pragma("unroll") for (int k = 0; k < 2; ++k) dst[m][k] = *(const LAS bf16x8*)(lds + G8_SA(b, h) + aoff + m * 2048 + k * 1024); } while (0)
; #define G8_LDB(dst, b, h) do { _Pragma("unroll") for (int n = 0; n < 2; ++n) _Pragma("unroll") for (int k = 0; k < 2; ++k) dst[n][k] = *(const LAS bf16x8*)(lds + G8_SB(b, h) + boff + n * 2048 + k * 1024); } while (0)
; #define G8_MMA(ai, bj, At, Bt) do { __builtin_amdgcn_s_setprio(1); _Pragma("unroll") for (int m = 0; m < 4; ++m) _Pragma("unroll") for (int n = 0; n < 2; ++n) _Pragma("unroll") for (int k = 0; k < 2; ++k) \
;     acc[ai][bj][m][n] = __builtin_amdgcn_mfma_f32_16x16x32_bf16(Bt[n][k], At[m][k], acc[ai][bj][m][n], 0, 0, 0); __builtin_amdgcn_s_setprio(0); } while (0)
; #define G8_WAIT_V(n) asm volatile("s_waitcnt vmcnt(" #n ")" ::: "memory")
; #define G8_WAIT_L(n) asm volatile("s_waitcnt lgkmcnt(" #n ")" ::: "memory")
; #define G8_BAR __builtin_amdgcn_s_barrier()
; #define G8_SCHED __builtin_amdgcn_sched_barrier(0)
; template <class Epi, class Sched>
; __device__ __forceinline__ void gemm_phase(const int wv_, LAS unsigned char* lds, const int lda, const int ldb, const int K, const Sched& S, const Epi& E) {
;     ...
;       G8_LDB(B1, 0, 1); G8_STAGE(G8_SB(0, 0), b2, voffB);
;       G8_BAR; G8_WAIT_L(0); G8_MMA(0, 1, At, B1); G8_BAR;
;       G8_LDA(At, 0, 1); G8_STAGE(G8_SA(0, 0), a2, voffA);
;       G8_BAR; G8_WAIT_L(0); G8_MMA(1, 0, At, B0); G8_BAR; G8_SCHED;
;       G8_STAGE(G8_SB(0, 1), b2 + hstepB, voffB);
;       G8_WAIT_V(6); G8_BAR; G8_MMA(1, 1, At, B1); G8_BAR;
;       G8_LDB(B0, 1, 0); G8_SCHED; G8_LDA(At, 1, 0); G8_STAGE(G8_SA(0, 1), a2 + hstepA, voffA);
;       G8_WAIT_L(8); G8_BAR; G8_WAIT_L(0); G8_MMA(0, 0, At, B0); G8_BAR; G8_SCHED;
;       G8_LDB(B1, 1, 1); G8_STAGE(G8_SB(1, 0), b3, voffB);
	s_add_i32 s21, 0, 0x14000
	v_add_u32_e32 v166, s21, v168
	s_add_i32 s51, s51, s39
	ds_read_b128 v[214:217], v166
	ds_read_b128 v[218:221], v166 offset:1024
	ds_read_b128 v[222:225], v166 offset:2048
	ds_read_b128 v[226:229], v166 offset:3072
	v_lshl_add_u64 v[166:167], s[28:29], 0, v[0:1]
	s_mov_b32 m0, s51
	v_lshl_add_u64 v[230:231], s[28:29], 0, v[148:149]
	global_load_lds_dwordx4 v[166:167], off
	s_add_i32 m0, s51, 0x2000
	s_nop 0
	global_load_lds_dwordx4 v[230:231], off
	s_barrier
	s_waitcnt lgkmcnt(0)
	s_waitcnt lgkmcnt(0)
	v_mfma_f32_16x16x32_bf16 v[136:139], v[214:217], v[158:161], v[136:139]
	v_mfma_f32_16x16x32_bf16 v[132:135], v[222:225], v[158:161], v[132:135]
	v_mfma_f32_16x16x32_bf16 v[120:123], v[214:217], v[190:193], v[120:123]
	v_mfma_f32_16x16x32_bf16 v[116:119], v[222:225], v[190:193], v[116:119]
	v_mfma_f32_16x16x32_bf16 v[104:107], v[214:217], v[198:201], v[104:107]
	v_mfma_f32_16x16x32_bf16 v[100:103], v[222:225], v[198:201], v[100:103]
	v_mfma_f32_16x16x32_bf16 v[88:91], v[214:217], v[206:209], v[88:91]
	v_mfma_f32_16x16x32_bf16 v[84:87], v[222:225], v[206:209], v[84:87]
	v_mfma_f32_16x16x32_bf16 v[136:139], v[218:221], v[162:165], v[136:139]
	v_mfma_f32_16x16x32_bf16 v[132:135], v[226:229], v[162:165], v[132:135]
	v_mfma_f32_16x16x32_bf16 v[120:123], v[218:221], v[194:197], v[120:123]
	v_mfma_f32_16x16x32_bf16 v[116:119], v[226:229], v[194:197], v[116:119]
	v_mfma_f32_16x16x32_bf16 v[104:107], v[218:221], v[202:205], v[104:107]
	v_mfma_f32_16x16x32_bf16 v[100:103], v[226:229], v[202:205], v[100:103]
	v_mfma_f32_16x16x32_bf16 v[88:91], v[218:221], v[210:213], v[88:91]
	v_mfma_f32_16x16x32_bf16 v[84:87], v[226:229], v[210:213], v[84:87]
	s_mov_b32 m0, s40
	v_lshl_add_u64 v[232:233], s[30:31], 0, v[0:1]
	s_barrier
	ds_read_b128 v[158:161], v189 offset:16384
	ds_read_b128 v[162:165], v189 offset:17408
	ds_read_b128 v[190:193], v189 offset:18432
	ds_read_b128 v[194:197], v189 offset:19456
	ds_read_b128 v[198:201], v189 offset:20480
	ds_read_b128 v[202:205], v189 offset:21504
	ds_read_b128 v[206:209], v189 offset:22528
	ds_read_b128 v[210:213], v189 offset:23552
	global_load_lds_dwordx4 v[232:233], off
	v_lshl_add_u64 v[234:235], s[30:31], 0, v[148:149]
	s_mov_b32 m0, s41
	s_nop 0
	global_load_lds_dwordx4 v[234:235], off
	s_barrier
	s_waitcnt lgkmcnt(0)
	s_waitcnt lgkmcnt(0)
	v_mfma_f32_16x16x32_bf16 v[64:67], v[68:71], v[158:161], v[64:67]
	v_mfma_f32_16x16x32_bf16 v[60:63], v[76:79], v[158:161], v[60:63]
	v_mfma_f32_16x16x32_bf16 v[48:51], v[68:71], v[190:193], v[48:51]
	v_mfma_f32_16x16x32_bf16 v[44:47], v[76:79], v[190:193], v[44:47]
	v_mfma_f32_16x16x32_bf16 v[32:35], v[68:71], v[198:201], v[32:35]
	v_mfma_f32_16x16x32_bf16 v[28:31], v[76:79], v[198:201], v[28:31]
	v_mfma_f32_16x16x32_bf16 v[16:19], v[68:71], v[206:209], v[16:19]
	v_mfma_f32_16x16x32_bf16 v[12:15], v[76:79], v[206:209], v[12:15]
	v_mfma_f32_16x16x32_bf16 v[64:67], v[72:75], v[162:165], v[64:67]
	v_mfma_f32_16x16x32_bf16 v[60:63], v[80:83], v[162:165], v[60:63]
	v_mfma_f32_16x16x32_bf16 v[48:51], v[72:75], v[194:197], v[48:51]
	v_mfma_f32_16x16x32_bf16 v[44:47], v[80:83], v[194:197], v[44:47]
	v_mfma_f32_16x16x32_bf16 v[32:35], v[72:75], v[202:205], v[32:35]
	v_mfma_f32_16x16x32_bf16 v[28:31], v[80:83], v[202:205], v[28:31]
	v_mfma_f32_16x16x32_bf16 v[16:19], v[72:75], v[210:213], v[16:19]
	v_mfma_f32_16x16x32_bf16 v[12:15], v[80:83], v[210:213], v[12:15]
	s_barrier
	s_add_u32 s58, s28, 0x200000
	s_addc_u32 s59, s29, 0
	s_add_i32 s21, s21, s39
	v_lshl_add_u64 v[68:69], s[58:59], 0, v[0:1]
	s_mov_b32 m0, s21
	s_nop 0
	global_load_lds_dwordx4 v[68:69], off
	v_lshl_add_u64 v[68:69], s[58:59], 0, v[148:149]
	s_add_i32 m0, s21, 0x2000
	s_nop 0
	global_load_lds_dwordx4 v[68:69], off
	s_waitcnt vmcnt(6)
	s_barrier
	v_mfma_f32_16x16x32_bf16 v[56:59], v[214:217], v[158:161], v[56:59]
	v_mfma_f32_16x16x32_bf16 v[52:55], v[222:225], v[158:161], v[52:55]
	v_mfma_f32_16x16x32_bf16 v[40:43], v[214:217], v[190:193], v[40:43]
	v_mfma_f32_16x16x32_bf16 v[36:39], v[222:225], v[190:193], v[36:39]
	v_mfma_f32_16x16x32_bf16 v[24:27], v[214:217], v[198:201], v[24:27]
	v_mfma_f32_16x16x32_bf16 v[20:23], v[222:225], v[198:201], v[20:23]
	v_mfma_f32_16x16x32_bf16 v[8:11], v[214:217], v[206:209], v[8:11]
	v_mfma_f32_16x16x32_bf16 v[4:7], v[222:225], v[206:209], v[4:7]
	v_mfma_f32_16x16x32_bf16 v[56:59], v[218:221], v[162:165], v[56:59]
	v_mfma_f32_16x16x32_bf16 v[52:55], v[226:229], v[162:165], v[52:55]
	v_mfma_f32_16x16x32_bf16 v[40:43], v[218:221], v[194:197], v[40:43]
	v_mfma_f32_16x16x32_bf16 v[36:39], v[226:229], v[194:197], v[36:39]
	v_mfma_f32_16x16x32_bf16 v[24:27], v[218:221], v[202:205], v[24:27]
	v_mfma_f32_16x16x32_bf16 v[20:23], v[226:229], v[202:205], v[20:23]
	v_mfma_f32_16x16x32_bf16 v[8:11], v[218:221], v[210:213], v[8:11]
	v_mfma_f32_16x16x32_bf16 v[4:7], v[226:229], v[210:213], v[4:7]
	s_add_i32 s21, 0, 0x18000
	v_add_u32_e32 v80, s21, v168
	s_barrier
	ds_read_b128 v[68:71], v80
	ds_read_b128 v[72:75], v80 offset:1024
	ds_read_b128 v[76:79], v80 offset:2048
	ds_read_b128 v[80:83], v80 offset:3072
	s_add_u32 s30, s30, 0x200000
	s_addc_u32 s31, s31, 0
	s_mov_b32 m0, s42
	v_lshl_add_u64 v[214:215], s[30:31], 0, v[0:1]
	ds_read_b128 v[158:161], v189 offset:32768
	ds_read_b128 v[162:165], v189 offset:33792
	ds_read_b128 v[190:193], v189 offset:34816
	ds_read_b128 v[194:197], v189 offset:35840
	ds_read_b128 v[198:201], v189 offset:36864
	ds_read_b128 v[202:205], v189 offset:37888
	ds_read_b128 v[206:209], v189 offset:38912
	ds_read_b128 v[210:213], v189 offset:39936
	global_load_lds_dwordx4 v[214:215], off
	v_lshl_add_u64 v[214:215], s[30:31], 0, v[148:149]
	s_mov_b32 m0, s43
	s_nop 0
	global_load_lds_dwordx4 v[214:215], off
	s_waitcnt lgkmcnt(8)
	s_barrier
; #define G8_STAGE(bufoff, gbase, voff) do { _Pragma("unroll") for (int _i = 0; _i < 2; ++_i) \
;     __builtin_amdgcn_global_load_lds((const unsigned*)((const char*)(gbase) + (voff)[_i]), (LAS unsigned*)(lds + (bufoff) + ldsw + _i * 8192), 16, 0, 0); } while (0)
; #define G8_LDA(dst, b, h) do { _Pragma("unroll") for (int m = 0; m < 4; ++m) _Pragma("unroll") for (int k = 0; k < 2; ++k) dst[m][k] = *(const LAS bf16x8*)(lds + G8_SA(b, h) + aoff + m * 2048 + k * 1024); } while (0)
; #define G8_LDB(dst, b, h) do { _Pragma("unroll") for (int n = 0; n < 2; ++n) _Pragma("unroll") for (int k = 0; k < 2; ++k) dst[n][k] = *(const LAS bf16x8*)(lds + G8_SB(b, h) + boff + n * 2048 + k * 1024); } while (0)
; #define G8_WAIT_V(n) asm volatile("s_waitcnt vmcnt(" #n ")" ::: "memory")
; template <class Epi, class Sched>
; __device__ __forceinline__ void gemm_phase(const int wv_, LAS unsigned char* lds, const int lda, const int ldb, const int K, const Sched& S, const Epi& E) {
;     ...
;       G8_LDB(B0, 0, 0); G8_SCHED; G8_LDA(At, 0, 0); G8_STAGE(G8_SA(1, 1), a1 + hstepA, voffA);
;       G8_WAIT_L(8); G8_BAR; G8_WAIT_L(0); G8_MMA(0, 0, At, B0); G8_BAR; G8_SCHED;
;       G8_LDB(B1, 0, 1); G8_STAGE(G8_SB(0, 0), b2, voffB);
;       G8_BAR; G8_WAIT_L(0); G8_MMA(0, 1, At, B1); G8_BAR;
;       G8_LDA(At, 0, 1); G8_STAGE(G8_SA(0, 0), a2, voffA);
;       G8_BAR; G8_WAIT_L(0); G8_MMA(1, 0, At, B0); G8_BAR; G8_SCHED;
;       G8_STAGE(G8_SB(0, 1), b2 + hstepB, voffB);
;       G8_WAIT_V(6); G8_BAR; G8_MMA(1, 1, At, B1); G8_BAR;
;       G8_LDB(B0, 1, 0); G8_SCHED; G8_LDA(At, 1, 0); G8_STAGE(G8_SA(0, 1), a2 + hstepA, voffA);
;       G8_WAIT_L(8); G8_BAR; G8_WAIT_L(0); G8_MMA(0, 0, At, B0); G8_BAR; G8_SCHED;
;       G8_LDB(B1, 1, 1); G8_STAGE(G8_SB(1, 0), b3, voffB);
;       G8_BAR; G8_WAIT_L(0); G8_MMA(0, 1, At, B1); G8_BAR;
;       G8_LDA(At, 1, 1); G8_STAGE(G8_SA(1, 0), a3, voffA);
;       G8_BAR; G8_WAIT_L(0); G8_MMA(1, 0, At, B0); G8_BAR; G8_SCHED;
;       G8_STAGE(G8_SB(1, 1), b3 + hstepB, voffB);
;       G8_WAIT_V(6); G8_BAR; G8_MMA(1, 1, At, B1); G8_BAR;
;   __device__ __forceinline__ bool operator()(f32x4 (&acc)[2][2][4][2], const Unit& u, int wr, int wc, int fr, int fq) const {
;     const int row0 = u.pm * BM + wr * 64 + fr, col0 = u.pn * BM + wc * 32 + 4 * fq;
;     const int who = row_who(u.pm * BM);
;     const float* gp = modl + (size_t)who * 12288 + part * 2048 + col0;
	s_waitcnt lgkmcnt(0)
	s_waitcnt lgkmcnt(0)
	v_mfma_f32_16x16x32_bf16 v[144:147], v[68:71], v[158:161], v[144:147]
	v_mfma_f32_16x16x32_bf16 v[140:143], v[76:79], v[158:161], v[140:143]
	v_mfma_f32_16x16x32_bf16 v[128:131], v[68:71], v[190:193], v[128:131]
	v_mfma_f32_16x16x32_bf16 v[124:127], v[76:79], v[190:193], v[124:127]
	v_mfma_f32_16x16x32_bf16 v[112:115], v[68:71], v[198:201], v[112:115]
	v_mfma_f32_16x16x32_bf16 v[108:111], v[76:79], v[198:201], v[108:111]
	v_mfma_f32_16x16x32_bf16 v[96:99], v[68:71], v[206:209], v[96:99]
	v_mfma_f32_16x16x32_bf16 v[92:95], v[76:79], v[206:209], v[92:95]
	v_mfma_f32_16x16x32_bf16 v[144:147], v[72:75], v[162:165], v[144:147]
	v_mfma_f32_16x16x32_bf16 v[140:143], v[80:83], v[162:165], v[140:143]
	v_mfma_f32_16x16x32_bf16 v[128:131], v[72:75], v[194:197], v[128:131]
	v_mfma_f32_16x16x32_bf16 v[124:127], v[80:83], v[194:197], v[124:127]
	v_mfma_f32_16x16x32_bf16 v[112:115], v[72:75], v[202:205], v[112:115]
	v_mfma_f32_16x16x32_bf16 v[108:111], v[80:83], v[202:205], v[108:111]
	v_mfma_f32_16x16x32_bf16 v[96:99], v[72:75], v[210:213], v[96:99]
	v_mfma_f32_16x16x32_bf16 v[92:95], v[80:83], v[210:213], v[92:95]
	s_barrier
	s_add_i32 s30, 0, 0x1c000
	s_add_i32 s21, s21, s39
	v_add_u32_e32 v226, s30, v168
	v_lshl_add_u64 v[166:167], v[166:167], 0, s[90:91]
	s_mov_b32 m0, s21
	ds_read_b128 v[214:217], v226
	ds_read_b128 v[218:221], v226 offset:1024
	ds_read_b128 v[222:225], v226 offset:2048
	ds_read_b128 v[226:229], v226 offset:3072
	global_load_lds_dwordx4 v[166:167], off
	v_lshl_add_u64 v[166:167], v[230:231], 0, s[90:91]
	s_add_i32 m0, s21, 0x2000
	s_nop 0
	global_load_lds_dwordx4 v[166:167], off
	s_barrier
	s_waitcnt lgkmcnt(0)
	s_waitcnt lgkmcnt(0)
	v_mfma_f32_16x16x32_bf16 v[136:139], v[214:217], v[158:161], v[136:139]
	v_mfma_f32_16x16x32_bf16 v[132:135], v[222:225], v[158:161], v[132:135]
	v_mfma_f32_16x16x32_bf16 v[120:123], v[214:217], v[190:193], v[120:123]
	v_mfma_f32_16x16x32_bf16 v[116:119], v[222:225], v[190:193], v[116:119]
	v_mfma_f32_16x16x32_bf16 v[104:107], v[214:217], v[198:201], v[104:107]
	v_mfma_f32_16x16x32_bf16 v[100:103], v[222:225], v[198:201], v[100:103]
	v_mfma_f32_16x16x32_bf16 v[88:91], v[214:217], v[206:209], v[88:91]
	v_mfma_f32_16x16x32_bf16 v[84:87], v[222:225], v[206:209], v[84:87]
	v_mfma_f32_16x16x32_bf16 v[136:139], v[218:221], v[162:165], v[136:139]
	v_mfma_f32_16x16x32_bf16 v[132:135], v[226:229], v[162:165], v[132:135]
	v_mfma_f32_16x16x32_bf16 v[120:123], v[218:221], v[194:197], v[120:123]
	v_mfma_f32_16x16x32_bf16 v[116:119], v[226:229], v[194:197], v[116:119]
	v_mfma_f32_16x16x32_bf16 v[104:107], v[218:221], v[202:205], v[104:107]
	v_mfma_f32_16x16x32_bf16 v[100:103], v[226:229], v[202:205], v[100:103]
	v_mfma_f32_16x16x32_bf16 v[88:91], v[218:221], v[210:213], v[88:91]
	v_mfma_f32_16x16x32_bf16 v[84:87], v[226:229], v[210:213], v[84:87]
	s_mov_b32 m0, s46
	v_lshl_add_u64 v[166:167], v[232:233], 0, s[90:91]
	s_barrier
	ds_read_b128 v[158:161], v189 offset:49152
	ds_read_b128 v[162:165], v189 offset:50176
	ds_read_b128 v[190:193], v189 offset:51200
	ds_read_b128 v[194:197], v189 offset:52224
	ds_read_b128 v[198:201], v189 offset:53248
	ds_read_b128 v[202:205], v189 offset:54272
	ds_read_b128 v[206:209], v189 offset:55296
	ds_read_b128 v[210:213], v189 offset:56320
	global_load_lds_dwordx4 v[166:167], off
	v_lshl_add_u64 v[166:167], v[234:235], 0, s[90:91]
	s_mov_b32 m0, s47
	s_nop 0
	global_load_lds_dwordx4 v[166:167], off
	s_barrier
	s_waitcnt lgkmcnt(0)
	s_waitcnt lgkmcnt(0)
	v_mfma_f32_16x16x32_bf16 v[64:67], v[68:71], v[158:161], v[64:67]
	v_mfma_f32_16x16x32_bf16 v[60:63], v[76:79], v[158:161], v[60:63]
	v_mfma_f32_16x16x32_bf16 v[48:51], v[68:71], v[190:193], v[48:51]
	v_mfma_f32_16x16x32_bf16 v[44:47], v[76:79], v[190:193], v[44:47]
	v_mfma_f32_16x16x32_bf16 v[32:35], v[68:71], v[198:201], v[32:35]
	v_mfma_f32_16x16x32_bf16 v[28:31], v[76:79], v[198:201], v[28:31]
	v_mfma_f32_16x16x32_bf16 v[16:19], v[68:71], v[206:209], v[16:19]
	v_mfma_f32_16x16x32_bf16 v[12:15], v[76:79], v[206:209], v[12:15]
	v_mfma_f32_16x16x32_bf16 v[64:67], v[72:75], v[162:165], v[64:67]
	v_mfma_f32_16x16x32_bf16 v[60:63], v[80:83], v[162:165], v[60:63]
	v_mfma_f32_16x16x32_bf16 v[48:51], v[72:75], v[194:197], v[48:51]
	v_mfma_f32_16x16x32_bf16 v[44:47], v[80:83], v[194:197], v[44:47]
	v_mfma_f32_16x16x32_bf16 v[32:35], v[72:75], v[202:205], v[32:35]
	v_mfma_f32_16x16x32_bf16 v[28:31], v[80:83], v[202:205], v[28:31]
	v_mfma_f32_16x16x32_bf16 v[16:19], v[72:75], v[210:213], v[16:19]
	v_mfma_f32_16x16x32_bf16 v[12:15], v[80:83], v[210:213], v[12:15]
	s_barrier
	s_add_u32 s28, s28, 0x200080
	s_addc_u32 s29, s29, 0
	s_add_i32 s21, s30, s39
	v_lshl_add_u64 v[68:69], s[28:29], 0, v[0:1]
	s_mov_b32 m0, s21
	s_nop 0
	global_load_lds_dwordx4 v[68:69], off
	v_lshl_add_u64 v[68:69], s[28:29], 0, v[148:149]
	s_add_i32 m0, s21, 0x2000
	s_nop 0
	global_load_lds_dwordx4 v[68:69], off
	s_waitcnt vmcnt(6)
	s_barrier
	v_mfma_f32_16x16x32_bf16 v[56:59], v[214:217], v[158:161], v[56:59]
	v_mfma_f32_16x16x32_bf16 v[52:55], v[222:225], v[158:161], v[52:55]
	v_mfma_f32_16x16x32_bf16 v[40:43], v[214:217], v[190:193], v[40:43]
	v_mfma_f32_16x16x32_bf16 v[36:39], v[222:225], v[190:193], v[36:39]
	v_mfma_f32_16x16x32_bf16 v[24:27], v[214:217], v[198:201], v[24:27]
	v_mfma_f32_16x16x32_bf16 v[20:23], v[222:225], v[198:201], v[20:23]
	v_mfma_f32_16x16x32_bf16 v[8:11], v[214:217], v[206:209], v[8:11]
	v_mfma_f32_16x16x32_bf16 v[4:7], v[222:225], v[206:209], v[4:7]
	v_mfma_f32_16x16x32_bf16 v[56:59], v[218:221], v[162:165], v[56:59]
	v_mfma_f32_16x16x32_bf16 v[52:55], v[226:229], v[162:165], v[52:55]
	v_mfma_f32_16x16x32_bf16 v[40:43], v[218:221], v[194:197], v[40:43]
	v_mfma_f32_16x16x32_bf16 v[36:39], v[226:229], v[194:197], v[36:39]
	v_mfma_f32_16x16x32_bf16 v[24:27], v[218:221], v[202:205], v[24:27]
	v_mfma_f32_16x16x32_bf16 v[20:23], v[226:229], v[202:205], v[20:23]
	v_mfma_f32_16x16x32_bf16 v[8:11], v[218:221], v[210:213], v[8:11]
	v_mfma_f32_16x16x32_bf16 v[4:7], v[226:229], v[210:213], v[4:7]
	s_add_i32 s19, s19, 2
	s_add_u32 s26, s26, 0x100
	s_addc_u32 s27, s27, 0
	s_add_u32 s9, s9, 0x100
	s_addc_u32 s11, s11, 0
	s_cmpk_gt_u32 s19, 0x7d
	s_barrier
	s_cbranch_scc0 .LBB0_1246
	s_setprio 0
	v_readlane_b32 s9, v242, 62
	s_cmp_eq_u32 s50, 3
	s_cselect_b32 s9, s9, 0
	s_cmp_lg_u32 s9, 0
	s_cbranch_scc1 .Lg5s_epi
	v_lshl_or_b32 v158, s18, 8, v169
	s_mul_hi_i32 s11, s20, 0x78787879
	s_lshr_b32 s9, s11, 31
	s_ashr_i32 s11, s11, 3
	s_add_i32 s11, s11, s9
	s_lshl_b32 s9, s20, 8
	s_mul_i32 s18, s11, 0xffffef00
	s_add_i32 s18, s18, s9
	s_cmpk_gt_i32 s18, 0xff
	s_cbranch_scc1 .Lg5e_lat
	s_load_dwordx2 s[20:21], s[0:1], 0x118
	s_lshl_b32 s9, s11, 21
	s_mov_b32 s11, 4
	s_waitcnt lgkmcnt(0)
	s_add_u32 s20, s20, 0x7f8000
	s_addc_u32 s21, s21, 0
	s_branch .Lg5e_ptr
